# pool+P6+P4 epilogues: hoisted loads / counted waits instead of per-group vmcnt(0); grid barrier: L1 invalidate issued before the spin
# speedup vs baseline: 1.0172x; 1.0172x over previous
; __device__ __forceinline__ unsigned xb_ld(unsigned* p)              { return __hip_atomic_load(p, __ATOMIC_RELAXED, __HIP_MEMORY_SCOPE_AGENT); }
; __device__ __forceinline__ unsigned xb_add(unsigned* p, unsigned v) { return __hip_atomic_fetch_add(p, v, __ATOMIC_RELAXED, __HIP_MEMORY_SCOPE_AGENT); }
; #define XB_SPIN(cond, bar) do { unsigned _sp = 0; while (cond) { __builtin_amdgcn_s_sleep(1); \
;     if ((++_sp & 255u) == 0u) { if (xb_ld(&(bar)[XB_TMO])) break; if (_sp > XB_SPIN_CAP) { atomicAdd(&(bar)[XB_TMO], 1u); break; } } } } while (0)
; __device__ __forceinline__ void xcd_barrier(const XcdBarrier& b) {
;     ...
;         unsigned nloc = b.st[0], nx = b.st[1];
;         if (nloc == 0u) { xcd_barrier_complete(bar, b.x, nloc, nx); b.st[0] = nloc; b.st[1] = nx; }
;         const unsigned old = xb_add(&bar[XB_XSUB(b.x)], 1u);
;         const unsigned gen = old / nloc;
;         if (old + 1u == (gen + 1u) * nloc) {
;             __builtin_amdgcn_fence(__ATOMIC_RELEASE, "agent");
;             asm volatile("s_waitcnt vmcnt(0)" ::: "memory");
;             const unsigned og = xb_add(&bar[XB_TOP], 1u);
;             const unsigned tg = og / nx;
;             if (og + 1u == (tg + 1u) * nx) xb_add(&bar[XB_TOPGEN], 1u);
;             else XB_SPIN(xb_ld(&bar[XB_TOPGEN]) == tg, bar);
;             __builtin_amdgcn_fence(__ATOMIC_ACQUIRE, "agent");
;             xb_add(&bar[XB_XGEN(b.x)], 1u);
;             asm volatile("s_waitcnt vmcnt(0)" ::: "memory");
;         } else {
;             XB_SPIN(xb_ld(&bar[XB_XGEN(b.x)]) == gen, bar);
.LBB9_100:
	s_or_b64 exec, exec, s[10:11]
	v_cvt_f32_u32_e32 v4, v2
	s_waitcnt vmcnt(0)
	v_readfirstlane_b32 s2, v3
	v_sub_u32_e32 v3, 0, v2
	v_rcp_iflag_f32_e32 v4, v4
	v_add_u32_e32 v5, s2, v1
	v_mul_f32_e32 v4, 0x4f7ffffe, v4
	v_cvt_u32_f32_e32 v4, v4
	v_mul_lo_u32 v1, v3, v4
	v_mul_hi_u32 v1, v4, v1
	v_add_u32_e32 v1, v4, v1
	v_mul_hi_u32 v1, v5, v1
	v_mul_lo_u32 v3, v1, v2
	v_sub_u32_e32 v3, v5, v3
	v_add_u32_e32 v4, 1, v1
	v_cmp_ge_u32_e32 vcc, v3, v2
	s_nop 1
	v_cndmask_b32_e32 v1, v1, v4, vcc
	v_sub_u32_e32 v4, v3, v2
	v_cndmask_b32_e32 v3, v3, v4, vcc
	v_add_u32_e32 v4, 1, v1
	v_cmp_ge_u32_e32 vcc, v3, v2
	v_add_u32_e32 v3, 1, v5
	s_nop 0
	v_cndmask_b32_e32 v1, v1, v4, vcc
	v_mul_lo_u32 v4, v2, v1
	v_add_u32_e32 v2, v4, v2
	v_cmp_ne_u32_e32 vcc, v3, v2
	s_and_saveexec_b64 s[2:3], vcc
	s_xor_b64 s[10:11], exec, s[2:3]
	s_cbranch_execz .LBB9_114
	s_waitcnt lgkmcnt(0)
	buffer_inv sc1
	v_mov_b32_e32 v0, 0x2000
	global_load_dword v0, v0, s[8:9] offset:1024 sc1
	s_add_u32 s16, s8, 0x2400
	s_addc_u32 s17, s9, 0
	s_waitcnt vmcnt(0)
	v_cmp_eq_u32_e32 vcc, v0, v1
	s_and_saveexec_b64 s[12:13], vcc
	s_cbranch_execz .LBB9_113
	s_mov_b32 s28, 1
	s_mov_b64 s[18:19], 0
	v_mov_b32_e32 v0, 0
	s_branch .LBB9_104

; __device__ __forceinline__ unsigned xb_ld(unsigned* p)              { return __hip_atomic_load(p, __ATOMIC_RELAXED, __HIP_MEMORY_SCOPE_AGENT); }
; __device__ __forceinline__ unsigned xb_add(unsigned* p, unsigned v) { return __hip_atomic_fetch_add(p, v, __ATOMIC_RELAXED, __HIP_MEMORY_SCOPE_AGENT); }
; #define XB_SPIN(cond, bar) do { unsigned _sp = 0; while (cond) { __builtin_amdgcn_s_sleep(1); \
;     if ((++_sp & 255u) == 0u) { if (xb_ld(&(bar)[XB_TMO])) break; if (_sp > XB_SPIN_CAP) { atomicAdd(&(bar)[XB_TMO], 1u); break; } } } } while (0)
; __device__ __forceinline__ void xcd_barrier(const XcdBarrier& b) {
;     ...
;         const unsigned old = xb_add(&bar[XB_XSUB(b.x)], 1u);
;         const unsigned gen = old / nloc;
;         if (old + 1u == (gen + 1u) * nloc) {
;             __builtin_amdgcn_fence(__ATOMIC_RELEASE, "agent");
;             asm volatile("s_waitcnt vmcnt(0)" ::: "memory");
;             const unsigned og = xb_add(&bar[XB_TOP], 1u);
;     ...
;         } else {
;             XB_SPIN(xb_ld(&bar[XB_XGEN(b.x)]) == gen, bar);
;             __builtin_amdgcn_fence(__ATOMIC_ACQUIRE, "agent");
;             asm volatile("s_waitcnt vmcnt(0)" ::: "memory");
;         }
.LBB9_113:
	s_or_b64 exec, exec, s[12:13]
	s_waitcnt vmcnt(0)
	s_waitcnt vmcnt(0)
.LBB9_114:
	s_andn2_saveexec_b64 s[2:3], s[10:11]
	s_cbranch_execz .LBB9_134
	s_mov_b64 s[2:3], exec
	buffer_wbl2 sc1
	buffer_inv sc1
	s_waitcnt lgkmcnt(0)
	s_waitcnt vmcnt(0)
	v_mbcnt_lo_u32_b32 v1, s2, 0
	v_mbcnt_hi_u32_b32 v1, s3, v1
	v_cmp_eq_u32_e32 vcc, 0, v1
	s_and_saveexec_b64 s[10:11], vcc
	s_cbranch_execz .LBB9_117
	s_bcnt1_i32_b64 s2, s[2:3]
	v_mov_b32_e32 v2, 0x3000
	v_mov_b32_e32 v3, s2
	global_atomic_add v2, v2, v3, s[90:91] offset:1024 sc0

; __device__ __forceinline__ unsigned xb_ld(unsigned* p)              { return __hip_atomic_load(p, __ATOMIC_RELAXED, __HIP_MEMORY_SCOPE_AGENT); }
; __device__ __forceinline__ unsigned xb_add(unsigned* p, unsigned v) { return __hip_atomic_fetch_add(p, v, __ATOMIC_RELAXED, __HIP_MEMORY_SCOPE_AGENT); }
; #define XB_SPIN(cond, bar) do { unsigned _sp = 0; while (cond) { __builtin_amdgcn_s_sleep(1); \
;     if ((++_sp & 255u) == 0u) { if (xb_ld(&(bar)[XB_TMO])) break; if (_sp > XB_SPIN_CAP) { atomicAdd(&(bar)[XB_TMO], 1u); break; } } } } while (0)
; __device__ __forceinline__ void xcd_barrier(const XcdBarrier& b) {
;     ...
;             else XB_SPIN(xb_ld(&bar[XB_TOPGEN]) == tg, bar);
;             __builtin_amdgcn_fence(__ATOMIC_ACQUIRE, "agent");
;             xb_add(&bar[XB_XGEN(b.x)], 1u);
;             asm volatile("s_waitcnt vmcnt(0)" ::: "memory");
.LBB9_131:
	s_or_b64 exec, exec, s[10:11]
	s_mov_b64 s[2:3], exec
	v_mbcnt_lo_u32_b32 v0, s2, 0
	v_mbcnt_hi_u32_b32 v0, s3, v0
	v_cmp_eq_u32_e32 vcc, 0, v0
	s_waitcnt vmcnt(0)
	s_and_saveexec_b64 s[10:11], vcc
	s_cbranch_execz .LBB9_133
	s_bcnt1_i32_b64 s2, s[2:3]
	v_mov_b32_e32 v0, 0x2000
	v_mov_b32_e32 v1, s2
	global_atomic_add v0, v1, s[8:9] offset:1024

; __device__ __forceinline__ unsigned xb_ld(unsigned* p)              { return __hip_atomic_load(p, __ATOMIC_RELAXED, __HIP_MEMORY_SCOPE_AGENT); }
; __device__ __forceinline__ unsigned xb_add(unsigned* p, unsigned v) { return __hip_atomic_fetch_add(p, v, __ATOMIC_RELAXED, __HIP_MEMORY_SCOPE_AGENT); }
; #define XB_SPIN(cond, bar) do { unsigned _sp = 0; while (cond) { __builtin_amdgcn_s_sleep(1); \
;     if ((++_sp & 255u) == 0u) { if (xb_ld(&(bar)[XB_TMO])) break; if (_sp > XB_SPIN_CAP) { atomicAdd(&(bar)[XB_TMO], 1u); break; } } } } while (0)
; __device__ __forceinline__ void xcd_barrier(const XcdBarrier& b) {
;     ...
;         unsigned nloc = b.st[0], nx = b.st[1];
;         if (nloc == 0u) { xcd_barrier_complete(bar, b.x, nloc, nx); b.st[0] = nloc; b.st[1] = nx; }
;         const unsigned old = xb_add(&bar[XB_XSUB(b.x)], 1u);
;         const unsigned gen = old / nloc;
;         if (old + 1u == (gen + 1u) * nloc) {
;             __builtin_amdgcn_fence(__ATOMIC_RELEASE, "agent");
;             asm volatile("s_waitcnt vmcnt(0)" ::: "memory");
;             const unsigned og = xb_add(&bar[XB_TOP], 1u);
;             const unsigned tg = og / nx;
;             if (og + 1u == (tg + 1u) * nx) xb_add(&bar[XB_TOPGEN], 1u);
;             else XB_SPIN(xb_ld(&bar[XB_TOPGEN]) == tg, bar);
;             __builtin_amdgcn_fence(__ATOMIC_ACQUIRE, "agent");
;             xb_add(&bar[XB_XGEN(b.x)], 1u);
;             asm volatile("s_waitcnt vmcnt(0)" ::: "memory");
;         } else {
;             XB_SPIN(xb_ld(&bar[XB_XGEN(b.x)]) == gen, bar);
.LBB9_169:
	s_or_b64 exec, exec, s[8:9]
	v_cvt_f32_u32_e32 v4, v2
	s_waitcnt vmcnt(0)
	v_readfirstlane_b32 s2, v3
	v_sub_u32_e32 v3, 0, v2
	v_rcp_iflag_f32_e32 v4, v4
	v_add_u32_e32 v5, s2, v1
	v_mul_f32_e32 v4, 0x4f7ffffe, v4
	v_cvt_u32_f32_e32 v4, v4
	v_mul_lo_u32 v1, v3, v4
	v_mul_hi_u32 v1, v4, v1
	v_add_u32_e32 v1, v4, v1
	v_mul_hi_u32 v1, v5, v1
	v_mul_lo_u32 v3, v1, v2
	v_sub_u32_e32 v3, v5, v3
	v_add_u32_e32 v4, 1, v1
	v_cmp_ge_u32_e32 vcc, v3, v2
	s_nop 1
	v_cndmask_b32_e32 v1, v1, v4, vcc
	v_sub_u32_e32 v4, v3, v2
	v_cndmask_b32_e32 v3, v3, v4, vcc
	v_add_u32_e32 v4, 1, v1
	v_cmp_ge_u32_e32 vcc, v3, v2
	v_add_u32_e32 v3, 1, v5
	s_nop 0
	v_cndmask_b32_e32 v1, v1, v4, vcc
	v_mul_lo_u32 v4, v2, v1
	v_add_u32_e32 v2, v4, v2
	v_cmp_ne_u32_e32 vcc, v3, v2
	s_and_saveexec_b64 s[2:3], vcc
	s_xor_b64 s[8:9], exec, s[2:3]
	s_cbranch_execz .LBB9_183
	s_waitcnt lgkmcnt(0)
	buffer_inv sc1
	v_mov_b32_e32 v0, 0x2000
	global_load_dword v0, v0, s[4:5] offset:1024 sc1
	s_add_u32 s12, s4, 0x2400
	s_addc_u32 s13, s5, 0
	s_waitcnt vmcnt(0)
	v_cmp_eq_u32_e32 vcc, v0, v1
	s_and_saveexec_b64 s[10:11], vcc
	s_cbranch_execz .LBB9_182
	s_mov_b32 s24, 1
	s_mov_b64 s[16:17], 0
	v_mov_b32_e32 v0, 0
	s_branch .LBB9_173

; __device__ __forceinline__ unsigned xb_ld(unsigned* p)              { return __hip_atomic_load(p, __ATOMIC_RELAXED, __HIP_MEMORY_SCOPE_AGENT); }
; __device__ __forceinline__ unsigned xb_add(unsigned* p, unsigned v) { return __hip_atomic_fetch_add(p, v, __ATOMIC_RELAXED, __HIP_MEMORY_SCOPE_AGENT); }
; #define XB_SPIN(cond, bar) do { unsigned _sp = 0; while (cond) { __builtin_amdgcn_s_sleep(1); \
;     if ((++_sp & 255u) == 0u) { if (xb_ld(&(bar)[XB_TMO])) break; if (_sp > XB_SPIN_CAP) { atomicAdd(&(bar)[XB_TMO], 1u); break; } } } } while (0)
; __device__ __forceinline__ void xcd_barrier(const XcdBarrier& b) {
;     ...
;         const unsigned old = xb_add(&bar[XB_XSUB(b.x)], 1u);
;         const unsigned gen = old / nloc;
;         if (old + 1u == (gen + 1u) * nloc) {
;             __builtin_amdgcn_fence(__ATOMIC_RELEASE, "agent");
;             asm volatile("s_waitcnt vmcnt(0)" ::: "memory");
;             const unsigned og = xb_add(&bar[XB_TOP], 1u);
;     ...
;         } else {
;             XB_SPIN(xb_ld(&bar[XB_XGEN(b.x)]) == gen, bar);
;             __builtin_amdgcn_fence(__ATOMIC_ACQUIRE, "agent");
;             asm volatile("s_waitcnt vmcnt(0)" ::: "memory");
;         }
.LBB9_182:
	s_or_b64 exec, exec, s[10:11]
	s_waitcnt vmcnt(0)
	s_waitcnt vmcnt(0)
.LBB9_183:
	s_andn2_saveexec_b64 s[2:3], s[8:9]
	s_cbranch_execz .LBB9_203
	s_mov_b64 s[2:3], exec
	buffer_wbl2 sc1
	buffer_inv sc1
	s_waitcnt lgkmcnt(0)
	s_waitcnt vmcnt(0)
	v_mbcnt_lo_u32_b32 v1, s2, 0
	v_mbcnt_hi_u32_b32 v1, s3, v1
	v_cmp_eq_u32_e32 vcc, 0, v1
	s_and_saveexec_b64 s[8:9], vcc
	s_cbranch_execz .LBB9_186
	s_bcnt1_i32_b64 s2, s[2:3]
	v_mov_b32_e32 v2, 0x3000
	v_mov_b32_e32 v3, s2
	global_atomic_add v2, v2, v3, s[90:91] offset:1024 sc0

; __device__ __forceinline__ unsigned xb_ld(unsigned* p)              { return __hip_atomic_load(p, __ATOMIC_RELAXED, __HIP_MEMORY_SCOPE_AGENT); }
; __device__ __forceinline__ unsigned xb_add(unsigned* p, unsigned v) { return __hip_atomic_fetch_add(p, v, __ATOMIC_RELAXED, __HIP_MEMORY_SCOPE_AGENT); }
; #define XB_SPIN(cond, bar) do { unsigned _sp = 0; while (cond) { __builtin_amdgcn_s_sleep(1); \
;     if ((++_sp & 255u) == 0u) { if (xb_ld(&(bar)[XB_TMO])) break; if (_sp > XB_SPIN_CAP) { atomicAdd(&(bar)[XB_TMO], 1u); break; } } } } while (0)
; __device__ __forceinline__ void xcd_barrier(const XcdBarrier& b) {
;     ...
;             else XB_SPIN(xb_ld(&bar[XB_TOPGEN]) == tg, bar);
;             __builtin_amdgcn_fence(__ATOMIC_ACQUIRE, "agent");
;             xb_add(&bar[XB_XGEN(b.x)], 1u);
;             asm volatile("s_waitcnt vmcnt(0)" ::: "memory");
.LBB9_200:
	s_or_b64 exec, exec, s[8:9]
	s_mov_b64 s[2:3], exec
	v_mbcnt_lo_u32_b32 v0, s2, 0
	v_mbcnt_hi_u32_b32 v0, s3, v0
	v_cmp_eq_u32_e32 vcc, 0, v0
	s_waitcnt vmcnt(0)
	s_and_saveexec_b64 s[8:9], vcc
	s_cbranch_execz .LBB9_202
	s_bcnt1_i32_b64 s2, s[2:3]
	v_mov_b32_e32 v0, 0x2000
	v_mov_b32_e32 v1, s2
	global_atomic_add v0, v1, s[4:5] offset:1024

; __device__ __forceinline__ unsigned xb_ld(unsigned* p)              { return __hip_atomic_load(p, __ATOMIC_RELAXED, __HIP_MEMORY_SCOPE_AGENT); }
; __device__ __forceinline__ unsigned xb_add(unsigned* p, unsigned v) { return __hip_atomic_fetch_add(p, v, __ATOMIC_RELAXED, __HIP_MEMORY_SCOPE_AGENT); }
; #define XB_SPIN(cond, bar) do { unsigned _sp = 0; while (cond) { __builtin_amdgcn_s_sleep(1); \
;     if ((++_sp & 255u) == 0u) { if (xb_ld(&(bar)[XB_TMO])) break; if (_sp > XB_SPIN_CAP) { atomicAdd(&(bar)[XB_TMO], 1u); break; } } } } while (0)
; __device__ __forceinline__ void xcd_barrier(const XcdBarrier& b) {
;     ...
;         unsigned nloc = b.st[0], nx = b.st[1];
;         if (nloc == 0u) { xcd_barrier_complete(bar, b.x, nloc, nx); b.st[0] = nloc; b.st[1] = nx; }
;         const unsigned old = xb_add(&bar[XB_XSUB(b.x)], 1u);
;         const unsigned gen = old / nloc;
;         if (old + 1u == (gen + 1u) * nloc) {
;             __builtin_amdgcn_fence(__ATOMIC_RELEASE, "agent");
;             asm volatile("s_waitcnt vmcnt(0)" ::: "memory");
;             const unsigned og = xb_add(&bar[XB_TOP], 1u);
;             const unsigned tg = og / nx;
;             if (og + 1u == (tg + 1u) * nx) xb_add(&bar[XB_TOPGEN], 1u);
;             else XB_SPIN(xb_ld(&bar[XB_TOPGEN]) == tg, bar);
;             __builtin_amdgcn_fence(__ATOMIC_ACQUIRE, "agent");
;             xb_add(&bar[XB_XGEN(b.x)], 1u);
;             asm volatile("s_waitcnt vmcnt(0)" ::: "memory");
;         } else {
;             XB_SPIN(xb_ld(&bar[XB_XGEN(b.x)]) == gen, bar);
.LBB9_270:
	s_or_b64 exec, exec, s[8:9]
	v_cvt_f32_u32_e32 v4, v2
	s_waitcnt vmcnt(0)
	v_readfirstlane_b32 s2, v3
	v_sub_u32_e32 v3, 0, v2
	v_rcp_iflag_f32_e32 v4, v4
	v_add_u32_e32 v5, s2, v1
	v_mul_f32_e32 v4, 0x4f7ffffe, v4
	v_cvt_u32_f32_e32 v4, v4
	v_mul_lo_u32 v1, v3, v4
	v_mul_hi_u32 v1, v4, v1
	v_add_u32_e32 v1, v4, v1
	v_mul_hi_u32 v1, v5, v1
	v_mul_lo_u32 v3, v1, v2
	v_sub_u32_e32 v3, v5, v3
	v_add_u32_e32 v4, 1, v1
	v_cmp_ge_u32_e32 vcc, v3, v2
	s_nop 1
	v_cndmask_b32_e32 v1, v1, v4, vcc
	v_sub_u32_e32 v4, v3, v2
	v_cndmask_b32_e32 v3, v3, v4, vcc
	v_add_u32_e32 v4, 1, v1
	v_cmp_ge_u32_e32 vcc, v3, v2
	v_add_u32_e32 v3, 1, v5
	s_nop 0
	v_cndmask_b32_e32 v1, v1, v4, vcc
	v_mul_lo_u32 v4, v2, v1
	v_add_u32_e32 v2, v4, v2
	v_cmp_ne_u32_e32 vcc, v3, v2
	s_and_saveexec_b64 s[2:3], vcc
	s_xor_b64 s[8:9], exec, s[2:3]
	s_cbranch_execz .LBB9_284
	s_waitcnt lgkmcnt(0)
	buffer_inv sc1
	v_mov_b32_e32 v0, 0x2000
	global_load_dword v0, v0, s[6:7] offset:1024 sc1
	s_add_u32 s12, s6, 0x2400
	s_addc_u32 s13, s7, 0
	s_waitcnt vmcnt(0)
	v_cmp_eq_u32_e32 vcc, v0, v1
	s_and_saveexec_b64 s[10:11], vcc
	s_cbranch_execz .LBB9_283
	s_mov_b32 s22, 1
	s_mov_b64 s[14:15], 0
	v_mov_b32_e32 v0, 0
	s_branch .LBB9_274

; __device__ __forceinline__ unsigned xb_ld(unsigned* p)              { return __hip_atomic_load(p, __ATOMIC_RELAXED, __HIP_MEMORY_SCOPE_AGENT); }
; __device__ __forceinline__ unsigned xb_add(unsigned* p, unsigned v) { return __hip_atomic_fetch_add(p, v, __ATOMIC_RELAXED, __HIP_MEMORY_SCOPE_AGENT); }
; #define XB_SPIN(cond, bar) do { unsigned _sp = 0; while (cond) { __builtin_amdgcn_s_sleep(1); \
;     if ((++_sp & 255u) == 0u) { if (xb_ld(&(bar)[XB_TMO])) break; if (_sp > XB_SPIN_CAP) { atomicAdd(&(bar)[XB_TMO], 1u); break; } } } } while (0)
; __device__ __forceinline__ void xcd_barrier(const XcdBarrier& b) {
;     ...
;             else XB_SPIN(xb_ld(&bar[XB_TOPGEN]) == tg, bar);
;             __builtin_amdgcn_fence(__ATOMIC_ACQUIRE, "agent");
;             xb_add(&bar[XB_XGEN(b.x)], 1u);
;             asm volatile("s_waitcnt vmcnt(0)" ::: "memory");
.LBB9_301:
	s_or_b64 exec, exec, s[8:9]
	s_mov_b64 s[2:3], exec
	v_mbcnt_lo_u32_b32 v0, s2, 0
	v_mbcnt_hi_u32_b32 v0, s3, v0
	v_cmp_eq_u32_e32 vcc, 0, v0
	s_waitcnt vmcnt(0)
	s_and_saveexec_b64 s[8:9], vcc
	s_cbranch_execz .LBB9_303
	s_bcnt1_i32_b64 s2, s[2:3]
	v_mov_b32_e32 v0, 0x2000
	v_mov_b32_e32 v1, s2
	global_atomic_add v0, v1, s[6:7] offset:1024

; __device__ __forceinline__ float bf2f(bf16_t v) { return __uint_as_float((unsigned)v << 16); }
; __device__ __forceinline__ unsigned cvtpk(float lo, float hi) { f32x2_t v = {lo, hi}; bf16x2_t b = __builtin_convertvector(v, bf16x2_t); return __builtin_bit_cast(unsigned, b); }
; #define LAS __attribute__((address_space(3)))
; #define LDS_WAIT() asm volatile("s_waitcnt lgkmcnt(0)" ::: "memory")
; __device__ __forceinline__ void pool_units(const Ptrs& P, LAS unsigned char* lds, int bx, int G, int tid, int wave, int lane) {
;     ...
;     const int r = lane & 31, hh = lane >> 5, rb = wave >> 1;
;     ...
;     PL_LOAD(u);
;     for (;;) {
;         const int g = u & 3, tt = u >> 2, ts0 = (tt & 31) * 128;
; #pragma unroll
;         for (int i = 0; i < 5; ++i) { const int p = tid + NTHR * i; if (p < 144 * 16) *(LAS u32x4*)(lds + PL_U + (p >> 4) * 256 + (p & 15) * 16) = tv[i]; }
;         if (g != gcur) { const bf16_t* PWg = (const bf16_t*)(ws + WS_PW) + g * 16384; gcur = g;
; #pragma unroll
;             for (int j = 0; j < 2; ++j)
; #pragma unroll
;                 for (int ks = 0; ks < 8; ++ks) wa[j][ks] = *(const bf16x8_t*)(PWg + (size_t)(32 * (2 * (wave & 1) + j) + r) * 128 + 16 * ks + 8 * hh); }
;         LDS_WAIT(); __builtin_amdgcn_s_barrier(); asm volatile("" ::: "memory");
;         const int un = u + G; const bool hasn = un < NU;
;         if (hasn) PL_LOAD(un);
;         {
;             const int c = tid & 127, tl0 = (tid >> 7) * 32, w2 = 1 << g; const LAS bf16_t* U = (const LAS bf16_t*)(lds + PL_U) + c; float sum = 0.f;
;             for (int j = tl0 - w2; j < tl0 + w2; ++j) sum += bf2f(U[(j + 8) * 128]);
;             for (int tl = tl0; tl < tl0 + 32; ++tl) {
;                 const int ts = ts0 + tl, lo = ts - w2 < 0 ? 0 : ts - w2, hi = ts + w2 > SEQ ? SEQ : ts + w2;
;                 const float d = sum * __builtin_amdgcn_rcpf((float)(hi - lo)) - bf2f(U[(tl + 8) * 128]);
;                 *(LAS bf16_t*)(lds + PL_A + tl * PL_AP + c * 2) = (bf16_t)(cvtpk(d, 0.f) & 0xffffu);
;                 sum += bf2f(U[(tl + w2 + 8) * 128]) - bf2f(U[(tl - w2 + 8) * 128]);
;             }
.LBB9_420:
	s_or_b64 exec, exec, s[2:3]
	s_lshl_b32 s2, s50, 1
	v_lshlrev_b32_e32 v1, 4, v1
	s_and_b32 s6, s2, 2
	s_lshl_b32 s2, s50, 4
	v_and_b32_e32 v15, 0x7f00, v1
	v_lshlrev_b32_e32 v1, 4, v6
	v_lshlrev_b32_e32 v10, 4, v208
	s_and_b32 s2, s2, 0x3fffffe0
	v_and_b32_e32 v6, 0x7f00, v1
	v_lshlrev_b32_e32 v1, 4, v7
	v_and_b32_e32 v4, 0xf0, v10
	v_or_b32_e32 v139, s2, v171
	s_movk_i32 s2, 0x110
	v_and_b32_e32 v7, 0xff00, v1
	v_lshlrev_b32_e32 v1, 4, v3
	v_mov_b32_e32 v3, v119
	v_add_u32_e32 v11, 0, v4
	v_lshlrev_b32_e32 v4, 4, v184
	v_mov_b32_e32 v5, v119
	v_mul_lo_u32 v13, v139, s2
	s_movk_i32 s2, 0xe000
	v_lshlrev_b64 v[126:127], 10, v[2:3]
	v_lshlrev_b32_e32 v2, 8, v171
	v_lshl_add_u64 v[8:9], s[90:91], 0, v[4:5]
	v_lshlrev_b32_e32 v14, 2, v184
	v_and_b32_e32 v16, 0xbf00, v1
	v_mov_b32_e32 v1, v119
	s_mov_b32 s3, -1
	v_lshl_or_b32 v2, s6, 13, v2
	v_lshl_add_u64 v[124:125], v[0:1], 0, s[2:3]
	v_lshl_or_b32 v0, s6, 5, v14
	v_lshl_add_u64 v[2:3], v[8:9], 0, v[2:3]
	s_mov_b64 s[2:3], 0x1f00000
	v_readlane_b32 s36, v251, 16
	v_and_b32_e32 v5, 0x7f, v208
	v_lshrrev_b32_e32 v12, 2, v208
	v_lshl_add_u64 v[128:129], v[2:3], 0, s[2:3]
	v_lshlrev_b32_e32 v2, 2, v0
	v_mov_b32_e32 v3, v119
	v_readlane_b32 s48, v251, 28
	v_readlane_b32 s49, v251, 29
	v_and_b32_e32 v137, 0xe0, v12
	v_lshlrev_b32_e32 v5, 1, v5
	v_lshl_add_u64 v[130:131], s[48:49], 0, v[2:3]
	v_lshlrev_b32_e32 v2, 6, v208
	s_mov_b32 s2, 0xe000
	v_or_b32_e32 v140, 1, v137
	v_or_b32_e32 v141, 2, v137
	v_or_b32_e32 v142, 3, v137
	v_or_b32_e32 v143, 4, v137
	v_or_b32_e32 v144, 5, v137
	v_or_b32_e32 v145, 6, v137
	v_or_b32_e32 v146, 7, v137
	v_or_b32_e32 v147, 8, v137
	v_or_b32_e32 v148, 9, v137
	v_or_b32_e32 v149, 10, v137
	v_or_b32_e32 v150, 11, v137
	v_or_b32_e32 v151, 12, v137
	v_or_b32_e32 v152, 13, v137
	v_or_b32_e32 v153, 14, v137
	v_or_b32_e32 v154, 15, v137
	v_or_b32_e32 v155, 16, v137
	v_or_b32_e32 v156, 17, v137
	v_or_b32_e32 v157, 18, v137
	v_or_b32_e32 v158, 19, v137
	v_or_b32_e32 v159, 20, v137
	v_or_b32_e32 v160, 21, v137
	v_or_b32_e32 v161, 22, v137
	v_or_b32_e32 v162, 23, v137
	v_or_b32_e32 v163, 24, v137
	v_or_b32_e32 v164, 25, v137
	v_or_b32_e32 v165, 26, v137
	v_or_b32_e32 v166, 27, v137
	v_or_b32_e32 v167, 28, v137
	v_or_b32_e32 v168, 29, v137
	v_or_b32_e32 v169, 30, v137
	v_or_b32_e32 v170, 31, v12
	v_and_or_b32 v2, v2, s2, v5
	v_add_u32_e32 v138, 0, v5
	v_add_u32_e32 v13, 0, v13
	s_add_u32 s8, s90, 0xc300000
	v_and_b32_e32 v10, 0x3f00, v10
	v_lshlrev_b32_e32 v1, 8, v137
	v_mul_u32_u24_e32 v17, 0x110, v137
	v_lshlrev_b32_e32 v18, 8, v140
	v_lshlrev_b32_e32 v19, 8, v141
	v_lshlrev_b32_e32 v20, 8, v142
	v_lshlrev_b32_e32 v21, 8, v143
	v_lshlrev_b32_e32 v22, 8, v144
	v_lshlrev_b32_e32 v23, 8, v145
	v_lshlrev_b32_e32 v24, 8, v146
	v_lshlrev_b32_e32 v25, 8, v147
	v_lshlrev_b32_e32 v26, 8, v148
	v_lshlrev_b32_e32 v27, 8, v149
	v_lshlrev_b32_e32 v28, 8, v150
	v_lshlrev_b32_e32 v29, 8, v151
	v_lshlrev_b32_e32 v30, 8, v152
	v_lshlrev_b32_e32 v31, 8, v153
	v_lshlrev_b32_e32 v52, 8, v154
	v_lshlrev_b32_e32 v53, 8, v155
	v_lshlrev_b32_e32 v54, 8, v156
	v_lshlrev_b32_e32 v55, 8, v157
	v_lshlrev_b32_e32 v56, 8, v158
	v_lshlrev_b32_e32 v57, 8, v159
	v_lshlrev_b32_e32 v58, 8, v160
	v_lshlrev_b32_e32 v59, 8, v161
	v_lshlrev_b32_e32 v60, 8, v162
	v_lshlrev_b32_e32 v61, 8, v163
	v_lshlrev_b32_e32 v62, 8, v164
	v_lshlrev_b32_e32 v63, 8, v165
	v_lshlrev_b32_e32 v64, 8, v166
	v_lshlrev_b32_e32 v65, 8, v167
	v_lshlrev_b32_e32 v66, 8, v168
	v_lshlrev_b32_e32 v67, 8, v169
	v_lshlrev_b32_e32 v12, 8, v170
	v_mul_u32_u24_e32 v68, 0x110, v170
	v_add_u32_e32 v2, 0, v2
	s_mov_b32 s7, 0
	s_addc_u32 s9, s91, 0
	v_add_u32_e32 v171, 0x800, v2
	v_add_u32_e32 v172, 0x800, v138
	s_mov_b32 s17, -1
	v_add_u32_e32 v173, v11, v10
	v_add_u32_e32 v174, v11, v15
	v_add_u32_e32 v175, v11, v6
	v_add_u32_e32 v176, v11, v7
	v_add_u32_e32 v177, v11, v16
	v_add_u32_e32 v178, v138, v1
	v_add_u32_e32 v179, v138, v17
	v_add_u32_e32 v180, v138, v18
	v_add_u32_e32 v181, v138, v19
	v_add_u32_e32 v182, v138, v20
	v_add_u32_e32 v183, v138, v21
	v_add_u32_e32 v184, v138, v22
	v_add_u32_e32 v185, v138, v23
	v_add_u32_e32 v186, v138, v24
	v_add_u32_e32 v187, v138, v25
	v_add_u32_e32 v188, v138, v26
	v_add_u32_e32 v189, v138, v27
	v_add_u32_e32 v190, v138, v28
	v_add_u32_e32 v191, v138, v29
	v_add_u32_e32 v192, v138, v30
	v_add_u32_e32 v193, v138, v31
	v_add_u32_e32 v194, v138, v52
	v_add_u32_e32 v195, v138, v53
	v_add_u32_e32 v196, v138, v54
	v_add_u32_e32 v197, v138, v55
	v_add_u32_e32 v198, v138, v56
	v_add_u32_e32 v199, v138, v57
	v_add_u32_e32 v200, v138, v58
	v_add_u32_e32 v201, v138, v59
	v_add_u32_e32 v202, v138, v60
	v_add_u32_e32 v203, v138, v61
	v_add_u32_e32 v204, v138, v62
	v_add_u32_e32 v205, v138, v63
	v_add_u32_e32 v206, v138, v64
	v_add_u32_e32 v207, v138, v65
	v_add_u32_e32 v209, v138, v66
	v_add_u32_e32 v210, v138, v67
	v_add_u32_e32 v211, v138, v12
	v_add_u32_e32 v212, v138, v68
	v_add_u32_e32 v213, v13, v4
	v_lshlrev_b32_e32 v132, 1, v0
	s_mov_b32 s20, s97
	v_readlane_b32 s37, v251, 17
	v_readlane_b32 s38, v251, 18
	v_readlane_b32 s39, v251, 19
	v_readlane_b32 s40, v251, 20
	v_readlane_b32 s41, v251, 21
	v_readlane_b32 s42, v251, 22
	v_readlane_b32 s43, v251, 23
	v_readlane_b32 s44, v251, 24
	v_readlane_b32 s45, v251, 25
	v_readlane_b32 s46, v251, 26
	v_readlane_b32 s47, v251, 27
	v_readlane_b32 s50, v251, 30
	v_readlane_b32 s51, v251, 31
	s_waitcnt vmcnt(0)
	s_branch .LBB9_422
; __device__ __forceinline__ float bf2f(bf16_t v) { return __uint_as_float((unsigned)v << 16); }
; __device__ __forceinline__ unsigned cvtpk(float lo, float hi) { f32x2_t v = {lo, hi}; bf16x2_t b = __builtin_convertvector(v, bf16x2_t); return __builtin_bit_cast(unsigned, b); }
; #define LAS __attribute__((address_space(3)))
; __device__ __forceinline__ void pool_units(const Ptrs& P, LAS unsigned char* lds, int bx, int G, int tid, int wave, int lane) {
;     ...
;             const int c = tid & 127, tl0 = (tid >> 7) * 32, w2 = 1 << g; const LAS bf16_t* U = (const LAS bf16_t*)(lds + PL_U) + c; float sum = 0.f;
;             for (int j = tl0 - w2; j < tl0 + w2; ++j) sum += bf2f(U[(j + 8) * 128]);
;             for (int tl = tl0; tl < tl0 + 32; ++tl) {
;                 const int ts = ts0 + tl, lo = ts - w2 < 0 ? 0 : ts - w2, hi = ts + w2 > SEQ ? SEQ : ts + w2;
;                 const float d = sum * __builtin_amdgcn_rcpf((float)(hi - lo)) - bf2f(U[(tl + 8) * 128]);
;                 *(LAS bf16_t*)(lds + PL_A + tl * PL_AP + c * 2) = (bf16_t)(cvtpk(d, 0.f) & 0xffffu);
;                 sum += bf2f(U[(tl + w2 + 8) * 128]) - bf2f(U[(tl - w2 + 8) * 128]);
;             }
.LBB9_421:
	s_or_b64 exec, exec, s[12:13]
	s_lshl_b32 s2, s20, 5
	s_and_b32 s3, s2, 0xf80
	v_add_u32_e32 v3, s3, v137
	v_subrev_u32_e32 v4, s6, v3
	v_or_b32_e32 v3, s6, v3
	v_max_i32_e32 v4, 0, v4
	v_min_u32_e32 v3, 0x1000, v3
	v_sub_u32_e32 v3, v3, v4
	v_cvt_f32_i32_e32 v3, v3
	ds_read_u16 v4, v178 offset:2048
	v_lshl_add_u32 v2, v2, 8, v138
	v_lshl_add_u32 v1, v1, 8, v138
	v_rcp_iflag_f32_e32 v3, v3
	s_and_b32 s2, s2, 0xffffff80
	s_waitcnt lgkmcnt(0)
	v_lshlrev_b32_e32 v4, 16, v4
	v_add_u32_e32 v230, s2, v139
	v_fma_f32 v3, v3, v0, -v4
	v_cvt_pk_bf16_f32 v3, v3, s0
	ds_write_b16 v179, v3 offset:36864
	v_add_u32_e32 v3, s3, v140
	v_subrev_u32_e32 v4, s6, v3
	v_add_u32_e32 v3, s6, v3
	v_max_i32_e32 v4, 0, v4
	v_min_u32_e32 v3, 0x1000, v3
	v_sub_u32_e32 v3, v3, v4
	ds_read_u16 v2, v2 offset:2048
	ds_read_u16 v1, v1 offset:2048
	v_cvt_f32_i32_e32 v3, v3
	ds_read_u16 v4, v180 offset:2048
	v_ashrrev_i32_e32 v231, 31, v230
	s_waitcnt lgkmcnt(2)
	v_lshlrev_b32_e32 v2, 16, v2
	v_rcp_iflag_f32_e32 v3, v3
	s_waitcnt lgkmcnt(1)
	v_lshlrev_b32_e32 v1, 16, v1
	v_sub_f32_e32 v1, v2, v1
	v_add_f32_e32 v0, v0, v1
	s_waitcnt lgkmcnt(0)
	v_lshlrev_b32_e32 v1, 16, v4
	v_fma_f32 v1, v3, v0, -v1
	v_add_u32_e32 v3, s3, v141
	v_cvt_pk_bf16_f32 v1, v1, s0
	v_subrev_u32_e32 v4, s6, v3
	v_add_u32_e32 v3, s6, v3
	ds_write_b16 v179, v1 offset:37136
	v_add_u32_e32 v1, s6, v140
	v_subrev_u32_e32 v2, s6, v140
	v_max_i32_e32 v4, 0, v4
	v_min_u32_e32 v3, 0x1000, v3
	v_lshl_add_u32 v1, v1, 8, v138
	v_lshl_add_u32 v2, v2, 8, v138
	v_sub_u32_e32 v3, v3, v4
	ds_read_u16 v1, v1 offset:2048
	ds_read_u16 v2, v2 offset:2048
	v_cvt_f32_i32_e32 v3, v3
	ds_read_u16 v4, v181 offset:2048
	v_lshlrev_b64 v[230:231], 11, v[230:231]
	s_waitcnt lgkmcnt(2)
	v_lshlrev_b32_e32 v1, 16, v1
	v_rcp_iflag_f32_e32 v3, v3
	s_waitcnt lgkmcnt(1)
	v_lshlrev_b32_e32 v2, 16, v2
	v_sub_f32_e32 v1, v1, v2
	v_add_f32_e32 v0, v0, v1
	s_waitcnt lgkmcnt(0)
	v_lshlrev_b32_e32 v1, 16, v4
	v_fma_f32 v1, v3, v0, -v1
	v_add_u32_e32 v3, s3, v142
	v_cvt_pk_bf16_f32 v1, v1, s0
	v_subrev_u32_e32 v4, s6, v3
	v_add_u32_e32 v3, s6, v3
	ds_write_b16 v179, v1 offset:37408
	v_add_u32_e32 v1, s6, v141
	v_subrev_u32_e32 v2, s6, v141
	v_max_i32_e32 v4, 0, v4
	v_min_u32_e32 v3, 0x1000, v3
	v_lshl_add_u32 v1, v1, 8, v138
	v_lshl_add_u32 v2, v2, 8, v138
	v_sub_u32_e32 v3, v3, v4
	ds_read_u16 v1, v1 offset:2048
	ds_read_u16 v2, v2 offset:2048
	v_cvt_f32_i32_e32 v3, v3
	ds_read_u16 v4, v182 offset:2048
	v_lshl_add_u64 v[230:231], s[8:9], 0, v[230:231]
	s_waitcnt lgkmcnt(2)
	v_lshlrev_b32_e32 v1, 16, v1
	v_rcp_iflag_f32_e32 v3, v3
	s_waitcnt lgkmcnt(1)
	v_lshlrev_b32_e32 v2, 16, v2
	v_sub_f32_e32 v1, v1, v2
	v_add_f32_e32 v0, v0, v1
	s_waitcnt lgkmcnt(0)
	v_lshlrev_b32_e32 v1, 16, v4
	v_fma_f32 v1, v3, v0, -v1
	v_add_u32_e32 v3, s3, v143
	v_cvt_pk_bf16_f32 v1, v1, s0
	v_subrev_u32_e32 v4, s6, v3
	v_add_u32_e32 v3, s6, v3
	ds_write_b16 v179, v1 offset:37680
	v_add_u32_e32 v1, s6, v142
	v_subrev_u32_e32 v2, s6, v142
	v_max_i32_e32 v4, 0, v4
	v_min_u32_e32 v3, 0x1000, v3
	v_lshl_add_u32 v1, v1, 8, v138
	v_lshl_add_u32 v2, v2, 8, v138
	v_sub_u32_e32 v3, v3, v4
	ds_read_u16 v1, v1 offset:2048
	ds_read_u16 v2, v2 offset:2048
	v_cvt_f32_i32_e32 v3, v3
	ds_read_u16 v4, v183 offset:2048
	v_mov_b32_e32 v133, v119
	s_waitcnt lgkmcnt(2)
	v_lshlrev_b32_e32 v1, 16, v1
	v_rcp_iflag_f32_e32 v3, v3
	s_waitcnt lgkmcnt(1)
	v_lshlrev_b32_e32 v2, 16, v2
	v_sub_f32_e32 v1, v1, v2
	v_add_f32_e32 v0, v0, v1
	s_waitcnt lgkmcnt(0)
	v_lshlrev_b32_e32 v1, 16, v4
	v_fma_f32 v1, v3, v0, -v1
	v_add_u32_e32 v3, s3, v144
	v_cvt_pk_bf16_f32 v1, v1, s0
	v_subrev_u32_e32 v4, s6, v3
	v_add_u32_e32 v3, s6, v3
	ds_write_b16 v179, v1 offset:37952
	v_add_u32_e32 v1, s6, v143
	v_subrev_u32_e32 v2, s6, v143
	v_max_i32_e32 v4, 0, v4
	v_min_u32_e32 v3, 0x1000, v3
	v_lshl_add_u32 v1, v1, 8, v138
	v_lshl_add_u32 v2, v2, 8, v138
	v_sub_u32_e32 v3, v3, v4
	ds_read_u16 v1, v1 offset:2048
	ds_read_u16 v2, v2 offset:2048
	v_cvt_f32_i32_e32 v3, v3
	ds_read_u16 v4, v184 offset:2048
	s_and_b64 vcc, exec, s[10:11]
	s_waitcnt lgkmcnt(2)
	v_lshlrev_b32_e32 v1, 16, v1
	v_rcp_iflag_f32_e32 v3, v3
	s_waitcnt lgkmcnt(1)
	v_lshlrev_b32_e32 v2, 16, v2
	v_sub_f32_e32 v1, v1, v2
	v_add_f32_e32 v0, v0, v1
	s_waitcnt lgkmcnt(0)
	v_lshlrev_b32_e32 v1, 16, v4
	v_fma_f32 v1, v3, v0, -v1
	v_add_u32_e32 v3, s3, v145
	v_cvt_pk_bf16_f32 v1, v1, s0
	v_subrev_u32_e32 v4, s6, v3
	v_add_u32_e32 v3, s6, v3
	ds_write_b16 v179, v1 offset:38224
	v_add_u32_e32 v1, s6, v144
	v_subrev_u32_e32 v2, s6, v144
	v_max_i32_e32 v4, 0, v4
	v_min_u32_e32 v3, 0x1000, v3
	v_lshl_add_u32 v1, v1, 8, v138
	v_lshl_add_u32 v2, v2, 8, v138
	v_sub_u32_e32 v3, v3, v4
	ds_read_u16 v1, v1 offset:2048
	ds_read_u16 v2, v2 offset:2048
	v_cvt_f32_i32_e32 v3, v3
	ds_read_u16 v4, v185 offset:2048
	s_mov_b32 s20, s18
	s_waitcnt lgkmcnt(2)
	v_lshlrev_b32_e32 v1, 16, v1
	v_rcp_iflag_f32_e32 v3, v3
	s_waitcnt lgkmcnt(1)
	v_lshlrev_b32_e32 v2, 16, v2
	v_sub_f32_e32 v1, v1, v2
	v_add_f32_e32 v0, v0, v1
	s_waitcnt lgkmcnt(0)
	v_lshlrev_b32_e32 v1, 16, v4
	v_fma_f32 v1, v3, v0, -v1
	v_add_u32_e32 v3, s3, v146
	v_cvt_pk_bf16_f32 v1, v1, s0
	v_subrev_u32_e32 v4, s6, v3
	v_add_u32_e32 v3, s6, v3
	ds_write_b16 v179, v1 offset:38496
	v_add_u32_e32 v1, s6, v145
	v_subrev_u32_e32 v2, s6, v145
	v_max_i32_e32 v4, 0, v4
	v_min_u32_e32 v3, 0x1000, v3
	v_lshl_add_u32 v1, v1, 8, v138
	v_lshl_add_u32 v2, v2, 8, v138
	v_sub_u32_e32 v3, v3, v4
	ds_read_u16 v1, v1 offset:2048
	ds_read_u16 v2, v2 offset:2048
	v_cvt_f32_i32_e32 v3, v3
	ds_read_u16 v4, v186 offset:2048
	s_waitcnt lgkmcnt(2)
	v_lshlrev_b32_e32 v1, 16, v1
	v_rcp_iflag_f32_e32 v3, v3
	s_waitcnt lgkmcnt(1)
; __device__ __forceinline__ float bf2f(bf16_t v) { return __uint_as_float((unsigned)v << 16); }
; __device__ __forceinline__ unsigned cvtpk(float lo, float hi) { f32x2_t v = {lo, hi}; bf16x2_t b = __builtin_convertvector(v, bf16x2_t); return __builtin_bit_cast(unsigned, b); }
; #define LAS __attribute__((address_space(3)))
; __device__ __forceinline__ void pool_units(const Ptrs& P, LAS unsigned char* lds, int bx, int G, int tid, int wave, int lane) {
;     ...
;             const int c = tid & 127, tl0 = (tid >> 7) * 32, w2 = 1 << g; const LAS bf16_t* U = (const LAS bf16_t*)(lds + PL_U) + c; float sum = 0.f;
;             for (int j = tl0 - w2; j < tl0 + w2; ++j) sum += bf2f(U[(j + 8) * 128]);
;             for (int tl = tl0; tl < tl0 + 32; ++tl) {
;                 const int ts = ts0 + tl, lo = ts - w2 < 0 ? 0 : ts - w2, hi = ts + w2 > SEQ ? SEQ : ts + w2;
;                 const float d = sum * __builtin_amdgcn_rcpf((float)(hi - lo)) - bf2f(U[(tl + 8) * 128]);
;                 *(LAS bf16_t*)(lds + PL_A + tl * PL_AP + c * 2) = (bf16_t)(cvtpk(d, 0.f) & 0xffffu);
;                 sum += bf2f(U[(tl + w2 + 8) * 128]) - bf2f(U[(tl - w2 + 8) * 128]);
;             }
	v_lshlrev_b32_e32 v2, 16, v2
	v_sub_f32_e32 v1, v1, v2
	v_add_f32_e32 v0, v0, v1
	s_waitcnt lgkmcnt(0)
	v_lshlrev_b32_e32 v1, 16, v4
	v_fma_f32 v1, v3, v0, -v1
	v_add_u32_e32 v3, s3, v147
	v_cvt_pk_bf16_f32 v1, v1, s0
	v_sub_u32_e32 v4, s6, v3
	v_add_u32_e32 v3, s6, v3
	ds_write_b16 v179, v1 offset:38768
	v_add_u32_e32 v1, s6, v146
	v_subrev_u32_e32 v2, s6, v146
	v_min_u32_e32 v3, 0x1000, v3
	v_lshl_add_u32 v1, v1, 8, v138
	v_lshl_add_u32 v2, v2, 8, v138
	v_add_u32_e32 v3, v4, v3
	ds_read_u16 v1, v1 offset:2048
	ds_read_u16 v2, v2 offset:2048
	v_cvt_f32_i32_e32 v3, v3
	ds_read_u16 v4, v187 offset:2048
	s_waitcnt lgkmcnt(2)
	v_lshlrev_b32_e32 v1, 16, v1
	v_rcp_iflag_f32_e32 v3, v3
	s_waitcnt lgkmcnt(1)
	v_lshlrev_b32_e32 v2, 16, v2
	v_sub_f32_e32 v1, v1, v2
	v_add_f32_e32 v0, v0, v1
	s_waitcnt lgkmcnt(0)
	v_lshlrev_b32_e32 v1, 16, v4
	v_fma_f32 v1, v3, v0, -v1
	v_add_u32_e32 v3, s3, v148
	v_cvt_pk_bf16_f32 v1, v1, s0
	v_sub_u32_e32 v4, s6, v3
	v_add_u32_e32 v3, s6, v3
	ds_write_b16 v179, v1 offset:39040
	v_add_u32_e32 v1, s6, v147
	v_subrev_u32_e32 v2, s6, v147
	v_min_u32_e32 v3, 0x1000, v3
	v_lshl_add_u32 v1, v1, 8, v138
	v_lshl_add_u32 v2, v2, 8, v138
	v_add_u32_e32 v3, v4, v3
	ds_read_u16 v1, v1 offset:2048
	ds_read_u16 v2, v2 offset:2048
	v_cvt_f32_i32_e32 v3, v3
	ds_read_u16 v4, v188 offset:2048
	s_waitcnt lgkmcnt(2)
	v_lshlrev_b32_e32 v1, 16, v1
	v_rcp_iflag_f32_e32 v3, v3
	s_waitcnt lgkmcnt(1)
	v_lshlrev_b32_e32 v2, 16, v2
	v_sub_f32_e32 v1, v1, v2
	v_add_f32_e32 v0, v0, v1
	s_waitcnt lgkmcnt(0)
	v_lshlrev_b32_e32 v1, 16, v4
	v_fma_f32 v1, v3, v0, -v1
	v_add_u32_e32 v3, s3, v149
	v_cvt_pk_bf16_f32 v1, v1, s0
	v_sub_u32_e32 v4, s6, v3
	v_add_u32_e32 v3, s6, v3
	ds_write_b16 v179, v1 offset:39312
	v_add_u32_e32 v1, s6, v148
	v_subrev_u32_e32 v2, s6, v148
	v_min_u32_e32 v3, 0x1000, v3
	v_lshl_add_u32 v1, v1, 8, v138
	v_lshl_add_u32 v2, v2, 8, v138
	v_add_u32_e32 v3, v4, v3
	ds_read_u16 v1, v1 offset:2048
	ds_read_u16 v2, v2 offset:2048
	v_cvt_f32_i32_e32 v3, v3
	ds_read_u16 v4, v189 offset:2048
	s_waitcnt lgkmcnt(2)
	v_lshlrev_b32_e32 v1, 16, v1
	v_rcp_iflag_f32_e32 v3, v3
	s_waitcnt lgkmcnt(1)
	v_lshlrev_b32_e32 v2, 16, v2
	v_sub_f32_e32 v1, v1, v2
	v_add_f32_e32 v0, v0, v1
	s_waitcnt lgkmcnt(0)
	v_lshlrev_b32_e32 v1, 16, v4
	v_fma_f32 v1, v3, v0, -v1
	v_add_u32_e32 v3, s3, v150
	v_cvt_pk_bf16_f32 v1, v1, s0
	v_sub_u32_e32 v4, s6, v3
	v_add_u32_e32 v3, s6, v3
	ds_write_b16 v179, v1 offset:39584
	v_add_u32_e32 v1, s6, v149
	v_subrev_u32_e32 v2, s6, v149
	v_min_u32_e32 v3, 0x1000, v3
	v_lshl_add_u32 v1, v1, 8, v138
	v_lshl_add_u32 v2, v2, 8, v138
	v_add_u32_e32 v3, v4, v3
	ds_read_u16 v1, v1 offset:2048
	ds_read_u16 v2, v2 offset:2048
	v_cvt_f32_i32_e32 v3, v3
	ds_read_u16 v4, v190 offset:2048
	s_waitcnt lgkmcnt(2)
	v_lshlrev_b32_e32 v1, 16, v1
	v_rcp_iflag_f32_e32 v3, v3
	s_waitcnt lgkmcnt(1)
	v_lshlrev_b32_e32 v2, 16, v2
	v_sub_f32_e32 v1, v1, v2
	v_add_f32_e32 v0, v0, v1
	s_waitcnt lgkmcnt(0)
	v_lshlrev_b32_e32 v1, 16, v4
	v_fma_f32 v1, v3, v0, -v1
	v_add_u32_e32 v3, s3, v151
	v_cvt_pk_bf16_f32 v1, v1, s0
	v_sub_u32_e32 v4, s6, v3
	v_add_u32_e32 v3, s6, v3
	ds_write_b16 v179, v1 offset:39856
	v_add_u32_e32 v1, s6, v150
	v_subrev_u32_e32 v2, s6, v150
	v_min_u32_e32 v3, 0x1000, v3
	v_lshl_add_u32 v1, v1, 8, v138
	v_lshl_add_u32 v2, v2, 8, v138
	v_add_u32_e32 v3, v4, v3
	ds_read_u16 v1, v1 offset:2048
	ds_read_u16 v2, v2 offset:2048
	v_cvt_f32_i32_e32 v3, v3
	ds_read_u16 v4, v191 offset:2048
	s_waitcnt lgkmcnt(2)
	v_lshlrev_b32_e32 v1, 16, v1
	v_rcp_iflag_f32_e32 v3, v3
	s_waitcnt lgkmcnt(1)
	v_lshlrev_b32_e32 v2, 16, v2
	v_sub_f32_e32 v1, v1, v2
	v_add_f32_e32 v0, v0, v1
	s_waitcnt lgkmcnt(0)
	v_lshlrev_b32_e32 v1, 16, v4
	v_fma_f32 v1, v3, v0, -v1
	v_add_u32_e32 v3, s3, v152
	v_cvt_pk_bf16_f32 v1, v1, s0
	v_sub_u32_e32 v4, s6, v3
	v_add_u32_e32 v3, s6, v3
	ds_write_b16 v179, v1 offset:40128
	v_add_u32_e32 v1, s6, v151
	v_subrev_u32_e32 v2, s6, v151
	v_min_u32_e32 v3, 0x1000, v3
	v_lshl_add_u32 v1, v1, 8, v138
	v_lshl_add_u32 v2, v2, 8, v138
	v_add_u32_e32 v3, v4, v3
	ds_read_u16 v1, v1 offset:2048
	ds_read_u16 v2, v2 offset:2048
	v_cvt_f32_i32_e32 v3, v3
	ds_read_u16 v4, v192 offset:2048
	s_waitcnt lgkmcnt(2)
	v_lshlrev_b32_e32 v1, 16, v1
	v_rcp_iflag_f32_e32 v3, v3
	s_waitcnt lgkmcnt(1)
	v_lshlrev_b32_e32 v2, 16, v2
	v_sub_f32_e32 v1, v1, v2
	v_add_f32_e32 v0, v0, v1
	s_waitcnt lgkmcnt(0)
	v_lshlrev_b32_e32 v1, 16, v4
	v_fma_f32 v1, v3, v0, -v1
	v_add_u32_e32 v3, s3, v153
	v_cvt_pk_bf16_f32 v1, v1, s0
	v_sub_u32_e32 v4, s6, v3
	v_add_u32_e32 v3, s6, v3
	ds_write_b16 v179, v1 offset:40400
	v_add_u32_e32 v1, s6, v152
	v_subrev_u32_e32 v2, s6, v152
	v_min_u32_e32 v3, 0x1000, v3
	v_lshl_add_u32 v1, v1, 8, v138
	v_lshl_add_u32 v2, v2, 8, v138
	v_add_u32_e32 v3, v4, v3
	ds_read_u16 v1, v1 offset:2048
	ds_read_u16 v2, v2 offset:2048
	v_cvt_f32_i32_e32 v3, v3
	ds_read_u16 v4, v193 offset:2048
	s_waitcnt lgkmcnt(2)
	v_lshlrev_b32_e32 v1, 16, v1
	v_rcp_iflag_f32_e32 v3, v3
	s_waitcnt lgkmcnt(1)
	v_lshlrev_b32_e32 v2, 16, v2
	v_sub_f32_e32 v1, v1, v2
	v_add_f32_e32 v0, v0, v1
	s_waitcnt lgkmcnt(0)
	v_lshlrev_b32_e32 v1, 16, v4
	v_fma_f32 v1, v3, v0, -v1
	v_add_u32_e32 v3, s3, v154
	v_cvt_pk_bf16_f32 v1, v1, s0
	v_sub_u32_e32 v4, s6, v3
	v_add_u32_e32 v3, s6, v3
	ds_write_b16 v179, v1 offset:40672
	v_add_u32_e32 v1, s6, v153
	v_subrev_u32_e32 v2, s6, v153
	v_min_u32_e32 v3, 0x1000, v3
	v_lshl_add_u32 v1, v1, 8, v138
	v_lshl_add_u32 v2, v2, 8, v138
	v_add_u32_e32 v3, v4, v3
	ds_read_u16 v1, v1 offset:2048
	ds_read_u16 v2, v2 offset:2048
	v_cvt_f32_i32_e32 v3, v3
	ds_read_u16 v4, v194 offset:2048
	s_waitcnt lgkmcnt(2)
; __device__ __forceinline__ float bf2f(bf16_t v) { return __uint_as_float((unsigned)v << 16); }
; __device__ __forceinline__ unsigned cvtpk(float lo, float hi) { f32x2_t v = {lo, hi}; bf16x2_t b = __builtin_convertvector(v, bf16x2_t); return __builtin_bit_cast(unsigned, b); }
; #define LAS __attribute__((address_space(3)))
; __device__ __forceinline__ void pool_units(const Ptrs& P, LAS unsigned char* lds, int bx, int G, int tid, int wave, int lane) {
;     ...
;             const int c = tid & 127, tl0 = (tid >> 7) * 32, w2 = 1 << g; const LAS bf16_t* U = (const LAS bf16_t*)(lds + PL_U) + c; float sum = 0.f;
;             for (int j = tl0 - w2; j < tl0 + w2; ++j) sum += bf2f(U[(j + 8) * 128]);
;             for (int tl = tl0; tl < tl0 + 32; ++tl) {
;                 const int ts = ts0 + tl, lo = ts - w2 < 0 ? 0 : ts - w2, hi = ts + w2 > SEQ ? SEQ : ts + w2;
;                 const float d = sum * __builtin_amdgcn_rcpf((float)(hi - lo)) - bf2f(U[(tl + 8) * 128]);
;                 *(LAS bf16_t*)(lds + PL_A + tl * PL_AP + c * 2) = (bf16_t)(cvtpk(d, 0.f) & 0xffffu);
;                 sum += bf2f(U[(tl + w2 + 8) * 128]) - bf2f(U[(tl - w2 + 8) * 128]);
;             }
	v_lshlrev_b32_e32 v1, 16, v1
	v_rcp_iflag_f32_e32 v3, v3
	s_waitcnt lgkmcnt(1)
	v_lshlrev_b32_e32 v2, 16, v2
	v_sub_f32_e32 v1, v1, v2
	v_add_f32_e32 v0, v0, v1
	s_waitcnt lgkmcnt(0)
	v_lshlrev_b32_e32 v1, 16, v4
	v_fma_f32 v1, v3, v0, -v1
	v_add_u32_e32 v3, s3, v155
	v_cvt_pk_bf16_f32 v1, v1, s0
	v_sub_u32_e32 v4, s6, v3
	v_or_b32_e32 v3, s6, v3
	ds_write_b16 v179, v1 offset:40944
	v_add_u32_e32 v1, s6, v154
	v_subrev_u32_e32 v2, s6, v154
	v_min_u32_e32 v3, 0x1000, v3
	v_lshl_add_u32 v1, v1, 8, v138
	v_lshl_add_u32 v2, v2, 8, v138
	v_add_u32_e32 v3, v4, v3
	ds_read_u16 v1, v1 offset:2048
	ds_read_u16 v2, v2 offset:2048
	v_cvt_f32_i32_e32 v3, v3
	ds_read_u16 v4, v195 offset:2048
	s_waitcnt lgkmcnt(2)
	v_lshlrev_b32_e32 v1, 16, v1
	v_rcp_iflag_f32_e32 v3, v3
	s_waitcnt lgkmcnt(1)
	v_lshlrev_b32_e32 v2, 16, v2
	v_sub_f32_e32 v1, v1, v2
	v_add_f32_e32 v0, v0, v1
	s_waitcnt lgkmcnt(0)
	v_lshlrev_b32_e32 v1, 16, v4
	v_fma_f32 v1, v3, v0, -v1
	v_add_u32_e32 v3, s3, v156
	v_cvt_pk_bf16_f32 v1, v1, s0
	v_sub_u32_e32 v4, s6, v3
	v_add_u32_e32 v3, s6, v3
	ds_write_b16 v179, v1 offset:41216
	v_or_b32_e32 v1, s6, v155
	v_subrev_u32_e32 v2, s6, v155
	v_min_u32_e32 v3, 0x1000, v3
	v_lshl_add_u32 v1, v1, 8, v138
	v_lshl_add_u32 v2, v2, 8, v138
	v_add_u32_e32 v3, v4, v3
	ds_read_u16 v1, v1 offset:2048
	ds_read_u16 v2, v2 offset:2048
	v_cvt_f32_i32_e32 v3, v3
	ds_read_u16 v4, v196 offset:2048
	s_waitcnt lgkmcnt(2)
	v_lshlrev_b32_e32 v1, 16, v1
	v_rcp_iflag_f32_e32 v3, v3
	s_waitcnt lgkmcnt(1)
	v_lshlrev_b32_e32 v2, 16, v2
	v_sub_f32_e32 v1, v1, v2
	v_add_f32_e32 v0, v0, v1
	s_waitcnt lgkmcnt(0)
	v_lshlrev_b32_e32 v1, 16, v4
	v_fma_f32 v1, v3, v0, -v1
	v_add_u32_e32 v3, s3, v157
	v_cvt_pk_bf16_f32 v1, v1, s0
	v_sub_u32_e32 v4, s6, v3
	v_add_u32_e32 v3, s6, v3
	ds_write_b16 v179, v1 offset:41488
	v_add_u32_e32 v1, s6, v156
	v_subrev_u32_e32 v2, s6, v156
	v_min_u32_e32 v3, 0x1000, v3
	v_lshl_add_u32 v1, v1, 8, v138
	v_lshl_add_u32 v2, v2, 8, v138
	v_add_u32_e32 v3, v4, v3
	ds_read_u16 v1, v1 offset:2048
	ds_read_u16 v2, v2 offset:2048
	v_cvt_f32_i32_e32 v3, v3
	ds_read_u16 v4, v197 offset:2048
	s_waitcnt lgkmcnt(2)
	v_lshlrev_b32_e32 v1, 16, v1
	v_rcp_iflag_f32_e32 v3, v3
	s_waitcnt lgkmcnt(1)
	v_lshlrev_b32_e32 v2, 16, v2
	v_sub_f32_e32 v1, v1, v2
	v_add_f32_e32 v0, v0, v1
	s_waitcnt lgkmcnt(0)
	v_lshlrev_b32_e32 v1, 16, v4
	v_fma_f32 v1, v3, v0, -v1
	v_add_u32_e32 v3, s3, v158
	v_cvt_pk_bf16_f32 v1, v1, s0
	v_sub_u32_e32 v4, s6, v3
	v_add_u32_e32 v3, s6, v3
	ds_write_b16 v179, v1 offset:41760
	v_add_u32_e32 v1, s6, v157
	v_subrev_u32_e32 v2, s6, v157
	v_min_u32_e32 v3, 0x1000, v3
	v_lshl_add_u32 v1, v1, 8, v138
	v_lshl_add_u32 v2, v2, 8, v138
	v_add_u32_e32 v3, v4, v3
	ds_read_u16 v1, v1 offset:2048
	ds_read_u16 v2, v2 offset:2048
	v_cvt_f32_i32_e32 v3, v3
	ds_read_u16 v4, v198 offset:2048
	s_waitcnt lgkmcnt(2)
	v_lshlrev_b32_e32 v1, 16, v1
	v_rcp_iflag_f32_e32 v3, v3
	s_waitcnt lgkmcnt(1)
	v_lshlrev_b32_e32 v2, 16, v2
	v_sub_f32_e32 v1, v1, v2
	v_add_f32_e32 v0, v0, v1
	s_waitcnt lgkmcnt(0)
	v_lshlrev_b32_e32 v1, 16, v4
	v_fma_f32 v1, v3, v0, -v1
	v_add_u32_e32 v3, s3, v159
	v_cvt_pk_bf16_f32 v1, v1, s0
	v_sub_u32_e32 v4, s6, v3
	v_add_u32_e32 v3, s6, v3
	ds_write_b16 v179, v1 offset:42032
	v_add_u32_e32 v1, s6, v158
	v_subrev_u32_e32 v2, s6, v158
	v_min_u32_e32 v3, 0x1000, v3
	v_lshl_add_u32 v1, v1, 8, v138
	v_lshl_add_u32 v2, v2, 8, v138
	v_add_u32_e32 v3, v4, v3
	ds_read_u16 v1, v1 offset:2048
	ds_read_u16 v2, v2 offset:2048
	v_cvt_f32_i32_e32 v3, v3
	ds_read_u16 v4, v199 offset:2048
	s_waitcnt lgkmcnt(2)
	v_lshlrev_b32_e32 v1, 16, v1
	v_rcp_iflag_f32_e32 v3, v3
	s_waitcnt lgkmcnt(1)
	v_lshlrev_b32_e32 v2, 16, v2
	v_sub_f32_e32 v1, v1, v2
	v_add_f32_e32 v0, v0, v1
	s_waitcnt lgkmcnt(0)
	v_lshlrev_b32_e32 v1, 16, v4
	v_fma_f32 v1, v3, v0, -v1
	v_add_u32_e32 v3, s3, v160
	v_cvt_pk_bf16_f32 v1, v1, s0
	v_sub_u32_e32 v4, s6, v3
	v_add_u32_e32 v3, s6, v3
	ds_write_b16 v179, v1 offset:42304
	v_add_u32_e32 v1, s6, v159
	v_subrev_u32_e32 v2, s6, v159
	v_min_u32_e32 v3, 0x1000, v3
	v_lshl_add_u32 v1, v1, 8, v138
	v_lshl_add_u32 v2, v2, 8, v138
	v_add_u32_e32 v3, v4, v3
	ds_read_u16 v1, v1 offset:2048
	ds_read_u16 v2, v2 offset:2048
	v_cvt_f32_i32_e32 v3, v3
	ds_read_u16 v4, v200 offset:2048
	s_waitcnt lgkmcnt(2)
	v_lshlrev_b32_e32 v1, 16, v1
	v_rcp_iflag_f32_e32 v3, v3
	s_waitcnt lgkmcnt(1)
	v_lshlrev_b32_e32 v2, 16, v2
	v_sub_f32_e32 v1, v1, v2
	v_add_f32_e32 v0, v0, v1
	s_waitcnt lgkmcnt(0)
	v_lshlrev_b32_e32 v1, 16, v4
	v_fma_f32 v1, v3, v0, -v1
	v_add_u32_e32 v3, s3, v161
	v_cvt_pk_bf16_f32 v1, v1, s0
	v_sub_u32_e32 v4, s6, v3
	v_add_u32_e32 v3, s6, v3
	ds_write_b16 v179, v1 offset:42576
	v_add_u32_e32 v1, s6, v160
	v_subrev_u32_e32 v2, s6, v160
	v_min_u32_e32 v3, 0x1000, v3
	v_lshl_add_u32 v1, v1, 8, v138
	v_lshl_add_u32 v2, v2, 8, v138
	v_add_u32_e32 v3, v4, v3
	ds_read_u16 v1, v1 offset:2048
	ds_read_u16 v2, v2 offset:2048
	v_cvt_f32_i32_e32 v3, v3
	ds_read_u16 v4, v201 offset:2048
	s_waitcnt lgkmcnt(2)
	v_lshlrev_b32_e32 v1, 16, v1
	v_rcp_iflag_f32_e32 v3, v3
	s_waitcnt lgkmcnt(1)
	v_lshlrev_b32_e32 v2, 16, v2
	v_sub_f32_e32 v1, v1, v2
	v_add_f32_e32 v0, v0, v1
	s_waitcnt lgkmcnt(0)
	v_lshlrev_b32_e32 v1, 16, v4
	v_fma_f32 v1, v3, v0, -v1
	v_add_u32_e32 v3, s3, v162
	v_cvt_pk_bf16_f32 v1, v1, s0
	v_sub_u32_e32 v4, s6, v3
	v_add_u32_e32 v3, s6, v3
	ds_write_b16 v179, v1 offset:42848
	v_add_u32_e32 v1, s6, v161
	v_subrev_u32_e32 v2, s6, v161
	v_min_u32_e32 v3, 0x1000, v3
	v_lshl_add_u32 v1, v1, 8, v138
	v_lshl_add_u32 v2, v2, 8, v138
	v_add_u32_e32 v3, v4, v3
	ds_read_u16 v1, v1 offset:2048
	ds_read_u16 v2, v2 offset:2048
	v_cvt_f32_i32_e32 v3, v3
	ds_read_u16 v4, v202 offset:2048
	s_waitcnt lgkmcnt(2)
; __device__ __forceinline__ float bf2f(bf16_t v) { return __uint_as_float((unsigned)v << 16); }
; __device__ __forceinline__ unsigned cvtpk(float lo, float hi) { f32x2_t v = {lo, hi}; bf16x2_t b = __builtin_convertvector(v, bf16x2_t); return __builtin_bit_cast(unsigned, b); }
; #define LAS __attribute__((address_space(3)))
; #define LDS_WAIT() asm volatile("s_waitcnt lgkmcnt(0)" ::: "memory")
; __device__ __forceinline__ void pool_units(const Ptrs& P, LAS unsigned char* lds, int bx, int G, int tid, int wave, int lane) {
;     ...
;             const int c = tid & 127, tl0 = (tid >> 7) * 32, w2 = 1 << g; const LAS bf16_t* U = (const LAS bf16_t*)(lds + PL_U) + c; float sum = 0.f;
;             for (int j = tl0 - w2; j < tl0 + w2; ++j) sum += bf2f(U[(j + 8) * 128]);
;             for (int tl = tl0; tl < tl0 + 32; ++tl) {
;                 const int ts = ts0 + tl, lo = ts - w2 < 0 ? 0 : ts - w2, hi = ts + w2 > SEQ ? SEQ : ts + w2;
;                 const float d = sum * __builtin_amdgcn_rcpf((float)(hi - lo)) - bf2f(U[(tl + 8) * 128]);
;                 *(LAS bf16_t*)(lds + PL_A + tl * PL_AP + c * 2) = (bf16_t)(cvtpk(d, 0.f) & 0xffffu);
;                 sum += bf2f(U[(tl + w2 + 8) * 128]) - bf2f(U[(tl - w2 + 8) * 128]);
;             }
;         }
;         LDS_WAIT(); __builtin_amdgcn_s_barrier(); asm volatile("" ::: "memory");
	v_lshlrev_b32_e32 v1, 16, v1
	v_rcp_iflag_f32_e32 v3, v3
	s_waitcnt lgkmcnt(1)
	v_lshlrev_b32_e32 v2, 16, v2
	v_sub_f32_e32 v1, v1, v2
	v_add_f32_e32 v0, v0, v1
	s_waitcnt lgkmcnt(0)
	v_lshlrev_b32_e32 v1, 16, v4
	v_fma_f32 v1, v3, v0, -v1
	v_add_u32_e32 v3, s3, v163
	v_cvt_pk_bf16_f32 v1, v1, s0
	v_sub_u32_e32 v4, s6, v3
	v_add_u32_e32 v3, s6, v3
	ds_write_b16 v179, v1 offset:43120
	v_add_u32_e32 v1, s6, v162
	v_subrev_u32_e32 v2, s6, v162
	v_min_u32_e32 v3, 0x1000, v3
	v_lshl_add_u32 v1, v1, 8, v138
	v_lshl_add_u32 v2, v2, 8, v138
	v_add_u32_e32 v3, v4, v3
	ds_read_u16 v1, v1 offset:2048
	ds_read_u16 v2, v2 offset:2048
	v_cvt_f32_i32_e32 v3, v3
	ds_read_u16 v4, v203 offset:2048
	s_waitcnt lgkmcnt(2)
	v_lshlrev_b32_e32 v1, 16, v1
	v_rcp_iflag_f32_e32 v3, v3
	s_waitcnt lgkmcnt(1)
	v_lshlrev_b32_e32 v2, 16, v2
	v_sub_f32_e32 v1, v1, v2
	v_add_f32_e32 v0, v0, v1
	s_waitcnt lgkmcnt(0)
	v_lshlrev_b32_e32 v1, 16, v4
	v_fma_f32 v1, v3, v0, -v1
	v_add_u32_e32 v3, s3, v164
	v_cvt_pk_bf16_f32 v1, v1, s0
	v_sub_u32_e32 v4, s6, v3
	v_add_u32_e32 v3, s6, v3
	ds_write_b16 v179, v1 offset:43392
	v_add_u32_e32 v1, s6, v163
	v_subrev_u32_e32 v2, s6, v163
	v_min_u32_e32 v3, 0x1000, v3
	v_lshl_add_u32 v1, v1, 8, v138
	v_lshl_add_u32 v2, v2, 8, v138
	v_add_u32_e32 v3, v4, v3
	ds_read_u16 v1, v1 offset:2048
	ds_read_u16 v2, v2 offset:2048
	v_cvt_f32_i32_e32 v3, v3
	ds_read_u16 v4, v204 offset:2048
	s_waitcnt lgkmcnt(2)
	v_lshlrev_b32_e32 v1, 16, v1
	v_rcp_iflag_f32_e32 v3, v3
	s_waitcnt lgkmcnt(1)
	v_lshlrev_b32_e32 v2, 16, v2
	v_sub_f32_e32 v1, v1, v2
	v_add_f32_e32 v0, v0, v1
	s_waitcnt lgkmcnt(0)
	v_lshlrev_b32_e32 v1, 16, v4
	v_fma_f32 v1, v3, v0, -v1
	v_add_u32_e32 v3, s3, v165
	v_cvt_pk_bf16_f32 v1, v1, s0
	v_sub_u32_e32 v4, s6, v3
	v_add_u32_e32 v3, s6, v3
	ds_write_b16 v179, v1 offset:43664
	v_add_u32_e32 v1, s6, v164
	v_subrev_u32_e32 v2, s6, v164
	v_min_u32_e32 v3, 0x1000, v3
	v_lshl_add_u32 v1, v1, 8, v138
	v_lshl_add_u32 v2, v2, 8, v138
	v_add_u32_e32 v3, v4, v3
	ds_read_u16 v1, v1 offset:2048
	ds_read_u16 v2, v2 offset:2048
	v_cvt_f32_i32_e32 v3, v3
	ds_read_u16 v4, v205 offset:2048
	s_waitcnt lgkmcnt(2)
	v_lshlrev_b32_e32 v1, 16, v1
	v_rcp_iflag_f32_e32 v3, v3
	s_waitcnt lgkmcnt(1)
	v_lshlrev_b32_e32 v2, 16, v2
	v_sub_f32_e32 v1, v1, v2
	v_add_f32_e32 v0, v0, v1
	s_waitcnt lgkmcnt(0)
	v_lshlrev_b32_e32 v1, 16, v4
	v_fma_f32 v1, v3, v0, -v1
	v_add_u32_e32 v3, s3, v166
	v_cvt_pk_bf16_f32 v1, v1, s0
	v_sub_u32_e32 v4, s6, v3
	v_add_u32_e32 v3, s6, v3
	ds_write_b16 v179, v1 offset:43936
	v_add_u32_e32 v1, s6, v165
	v_subrev_u32_e32 v2, s6, v165
	v_min_u32_e32 v3, 0x1000, v3
	v_lshl_add_u32 v1, v1, 8, v138
	v_lshl_add_u32 v2, v2, 8, v138
	v_add_u32_e32 v3, v4, v3
	ds_read_u16 v1, v1 offset:2048
	ds_read_u16 v2, v2 offset:2048
	v_cvt_f32_i32_e32 v3, v3
	ds_read_u16 v4, v206 offset:2048
	s_waitcnt lgkmcnt(2)
	v_lshlrev_b32_e32 v1, 16, v1
	v_rcp_iflag_f32_e32 v3, v3
	s_waitcnt lgkmcnt(1)
	v_lshlrev_b32_e32 v2, 16, v2
	v_sub_f32_e32 v1, v1, v2
	v_add_f32_e32 v0, v0, v1
	s_waitcnt lgkmcnt(0)
	v_lshlrev_b32_e32 v1, 16, v4
	v_fma_f32 v1, v3, v0, -v1
	v_add_u32_e32 v3, s3, v167
	v_cvt_pk_bf16_f32 v1, v1, s0
	v_sub_u32_e32 v4, s6, v3
	v_add_u32_e32 v3, s6, v3
	ds_write_b16 v179, v1 offset:44208
	v_add_u32_e32 v1, s6, v166
	v_subrev_u32_e32 v2, s6, v166
	v_min_u32_e32 v3, 0x1000, v3
	v_lshl_add_u32 v1, v1, 8, v138
	v_lshl_add_u32 v2, v2, 8, v138
	v_add_u32_e32 v3, v4, v3
	ds_read_u16 v1, v1 offset:2048
	ds_read_u16 v2, v2 offset:2048
	v_cvt_f32_i32_e32 v3, v3
	ds_read_u16 v4, v207 offset:2048
	s_waitcnt lgkmcnt(2)
	v_lshlrev_b32_e32 v1, 16, v1
	v_rcp_iflag_f32_e32 v3, v3
	s_waitcnt lgkmcnt(1)
	v_lshlrev_b32_e32 v2, 16, v2
	v_sub_f32_e32 v1, v1, v2
	v_add_f32_e32 v0, v0, v1
	s_waitcnt lgkmcnt(0)
	v_lshlrev_b32_e32 v1, 16, v4
	v_fma_f32 v1, v3, v0, -v1
	v_add_u32_e32 v3, s3, v168
	v_cvt_pk_bf16_f32 v1, v1, s0
	v_sub_u32_e32 v4, s6, v3
	v_add_u32_e32 v3, s6, v3
	ds_write_b16 v179, v1 offset:44480
	v_add_u32_e32 v1, s6, v167
	v_subrev_u32_e32 v2, s6, v167
	v_min_u32_e32 v3, 0x1000, v3
	v_lshl_add_u32 v1, v1, 8, v138
	v_lshl_add_u32 v2, v2, 8, v138
	v_add_u32_e32 v3, v4, v3
	ds_read_u16 v1, v1 offset:2048
	ds_read_u16 v2, v2 offset:2048
	v_cvt_f32_i32_e32 v3, v3
	ds_read_u16 v4, v209 offset:2048
	s_waitcnt lgkmcnt(2)
	v_lshlrev_b32_e32 v1, 16, v1
	v_rcp_iflag_f32_e32 v3, v3
	s_waitcnt lgkmcnt(1)
	v_lshlrev_b32_e32 v2, 16, v2
	v_sub_f32_e32 v1, v1, v2
	v_add_f32_e32 v0, v0, v1
	s_waitcnt lgkmcnt(0)
	v_lshlrev_b32_e32 v1, 16, v4
	v_fma_f32 v1, v3, v0, -v1
	v_add_u32_e32 v3, s3, v169
	v_cvt_pk_bf16_f32 v1, v1, s0
	v_sub_u32_e32 v4, s6, v3
	v_add_u32_e32 v3, s6, v3
	ds_write_b16 v179, v1 offset:44752
	v_add_u32_e32 v1, s6, v168
	v_subrev_u32_e32 v2, s6, v168
	v_min_u32_e32 v3, 0x1000, v3
	v_lshl_add_u32 v1, v1, 8, v138
	v_lshl_add_u32 v2, v2, 8, v138
	v_add_u32_e32 v3, v4, v3
	ds_read_u16 v1, v1 offset:2048
	ds_read_u16 v2, v2 offset:2048
	v_cvt_f32_i32_e32 v3, v3
	ds_read_u16 v4, v210 offset:2048
	s_waitcnt lgkmcnt(2)
	v_lshlrev_b32_e32 v1, 16, v1
	v_rcp_iflag_f32_e32 v3, v3
	s_waitcnt lgkmcnt(1)
	v_lshlrev_b32_e32 v2, 16, v2
	v_sub_f32_e32 v1, v1, v2
	v_add_f32_e32 v0, v0, v1
	s_waitcnt lgkmcnt(0)
	v_lshlrev_b32_e32 v1, 16, v4
	v_fma_f32 v1, v3, v0, -v1
	v_add_u32_e32 v3, s3, v170
	v_cvt_pk_bf16_f32 v1, v1, s0
	v_sub_u32_e32 v4, s6, v3
	v_add_u32_e32 v3, s6, v3
	ds_write_b16 v179, v1 offset:45024
	v_add_u32_e32 v1, s6, v169
	v_subrev_u32_e32 v2, s6, v169
	v_min_u32_e32 v3, 0x1000, v3
	v_lshl_add_u32 v1, v1, 8, v138
	v_lshl_add_u32 v2, v2, 8, v138
	v_add_u32_e32 v3, v4, v3
	ds_read_u16 v1, v1 offset:2048
	ds_read_u16 v2, v2 offset:2048
	v_cvt_f32_i32_e32 v3, v3
	ds_read_u16 v4, v211 offset:2048
	s_lshl_b32 s6, s19, 8
	s_waitcnt lgkmcnt(2)
	v_lshlrev_b32_e32 v1, 16, v1
	v_rcp_iflag_f32_e32 v3, v3
	s_waitcnt lgkmcnt(1)
	v_lshlrev_b32_e32 v2, 16, v2
	v_sub_f32_e32 v1, v1, v2
	v_add_f32_e32 v0, v0, v1
	s_waitcnt lgkmcnt(0)
	v_lshlrev_b32_e32 v1, 16, v4
	v_fma_f32 v0, v3, v0, -v1
	v_cvt_pk_bf16_f32 v0, v0, s0
	ds_write_b16 v212, v0 offset:36864
	s_waitcnt lgkmcnt(0)
	s_barrier
; __device__ __forceinline__ unsigned cvtpk(float lo, float hi) { f32x2_t v = {lo, hi}; bf16x2_t b = __builtin_convertvector(v, bf16x2_t); return __builtin_bit_cast(unsigned, b); }
; #define LAS __attribute__((address_space(3)))
; #define LDS_WAIT() asm volatile("s_waitcnt lgkmcnt(0)" ::: "memory")
; #define MFMA32(a, b, c) __builtin_amdgcn_mfma_f32_32x32x16_bf16((a), (b), (c), 0, 0, 0)
; __device__ __forceinline__ void pool_units(const Ptrs& P, LAS unsigned char* lds, int bx, int G, int tid, int wave, int lane) {
;     ...
; #pragma unroll
;         for (int i = 0; i < 5; ++i) { const int p = tid + NTHR * i; if (p < 144 * 16) *(LAS u32x4*)(lds + PL_U + (p >> 4) * 256 + (p & 15) * 16) = tv[i]; }
;     ...
; #pragma unroll
;             for (int ks = 0; ks < 8; ++ks) {
;                 const bf16x8_t bt = *(const LAS bf16x8_t*)(lds + PL_A + (32 * rb + r) * PL_AP + (16 * ks + 8 * hh) * 2);
; #pragma unroll
;                 for (int j = 0; j < 2; ++j) acc[j] = MFMA32(wa[j][ks], bt, acc[j]);
;             }
;             bf16_t* PMr = (bf16_t*)(ws + WS_PM) + (size_t)(tt * 128 + 32 * rb + r) * PMP + g * 128;
; #pragma unroll
;             for (int j = 0; j < 2; ++j)
; #pragma unroll
;                 for (int g4 = 0; g4 < 4; ++g4) { const int d = 32 * (2 * (wave & 1) + j) + 8 * g4 + 4 * hh; const f32x4 sc = *(const f32x4*)(P.pool_scale + g * 128 + d);
;                     u32x2 w; w.x = cvtpk(acc[j][4 * g4] * sc[0], acc[j][4 * g4 + 1] * sc[1]); w.y = cvtpk(acc[j][4 * g4 + 2] * sc[2], acc[j][4 * g4 + 3] * sc[3]);
;                     *(u32x2*)(PMr + d) = w; }
;         }
;         LDS_WAIT(); __builtin_amdgcn_s_barrier(); asm volatile("" ::: "memory");
	ds_read_b128 v[0:3], v213 offset:36864
	ds_read_b128 v[214:217], v213 offset:36896
	s_waitcnt vmcnt(15) lgkmcnt(1)
	v_mfma_f32_32x32x16_bf16 v[16:31], v[80:83], v[0:3], 0
	v_lshl_add_u64 v[234:235], v[230:231], 0, s[6:7]
	s_lshl_b32 s6, s19, 9
	v_lshl_add_u64 v[236:237], v[130:131], 0, s[6:7]
	s_waitcnt vmcnt(7)
	v_mfma_f32_32x32x16_bf16 v[0:15], v[112:115], v[0:3], 0
	s_waitcnt lgkmcnt(0)
	v_mfma_f32_32x32x16_bf16 v[16:31], v[76:79], v[214:217], v[16:31]
	s_waitcnt vmcnt(6)
	v_mfma_f32_32x32x16_bf16 v[0:15], v[108:111], v[214:217], v[0:15]
	ds_read_b128 v[214:217], v213 offset:36928
	ds_read_b128 v[218:221], v213 offset:36960
	s_waitcnt lgkmcnt(1)
	v_mfma_f32_32x32x16_bf16 v[16:31], v[72:75], v[214:217], v[16:31]
	s_waitcnt vmcnt(5)
	v_mfma_f32_32x32x16_bf16 v[0:15], v[104:107], v[214:217], v[0:15]
	s_waitcnt lgkmcnt(0)
	v_mfma_f32_32x32x16_bf16 v[16:31], v[68:71], v[218:221], v[16:31]
	s_waitcnt vmcnt(4)
	v_mfma_f32_32x32x16_bf16 v[0:15], v[100:103], v[218:221], v[0:15]
	ds_read_b128 v[214:217], v213 offset:36992
	ds_read_b128 v[218:221], v213 offset:37024
	ds_read_b128 v[222:225], v213 offset:37056
	ds_read_b128 v[226:229], v213 offset:37088
	v_lshl_add_u64 v[230:231], v[234:235], 0, v[132:133]
	s_waitcnt lgkmcnt(3)
	v_mfma_f32_32x32x16_bf16 v[16:31], v[64:67], v[214:217], v[16:31]
	s_waitcnt lgkmcnt(2)
	v_mfma_f32_32x32x16_bf16 v[16:31], v[60:63], v[218:221], v[16:31]
	s_waitcnt lgkmcnt(1)
	v_mfma_f32_32x32x16_bf16 v[16:31], v[56:59], v[222:225], v[16:31]
	s_waitcnt lgkmcnt(0)
	v_mfma_f32_32x32x16_bf16 v[16:31], v[52:55], v[226:229], v[16:31]
	s_waitcnt vmcnt(0)
	v_mfma_f32_32x32x16_bf16 v[0:15], v[96:99], v[214:217], v[0:15]
	v_mfma_f32_32x32x16_bf16 v[0:15], v[92:95], v[218:221], v[0:15]
	v_mfma_f32_32x32x16_bf16 v[0:15], v[88:91], v[222:225], v[0:15]
	v_mfma_f32_32x32x16_bf16 v[0:15], v[84:87], v[226:229], v[0:15]
	global_load_dwordx4 v[214:217], v[236:237], off offset:128
	global_load_dwordx4 v[218:221], v[236:237], off offset:160
	global_load_dwordx4 v[222:225], v[236:237], off offset:192
	global_load_dwordx4 v[226:229], v[236:237], off offset:224
	s_nop 7
	v_mul_f32_e64 v16, v16, v238
	v_mul_f32_e64 v17, v17, v239
	v_mul_f32_e64 v18, v18, v240
	v_mul_f32_e64 v19, v19, v241
	v_cvt_pk_bf16_f32 v16, v16, v17
	v_cvt_pk_bf16_f32 v17, v18, v19
	global_store_dwordx2 v[230:231], v[16:17], off
	v_mul_f32_e64 v20, v20, v242
	v_mul_f32_e64 v21, v21, v243
	v_mul_f32_e64 v22, v22, v244
	v_mul_f32_e64 v23, v23, v245
	v_cvt_pk_bf16_f32 v20, v20, v21
	v_cvt_pk_bf16_f32 v21, v22, v23
	global_store_dwordx2 v[230:231], v[20:21], off offset:16
	v_mul_f32_e64 v24, v24, v246
	v_mul_f32_e64 v25, v25, v247
	v_mul_f32_e64 v26, v26, v248
	v_mul_f32_e64 v27, v27, v249
	v_cvt_pk_bf16_f32 v24, v24, v25
	v_cvt_pk_bf16_f32 v25, v26, v27
	global_store_dwordx2 v[230:231], v[24:25], off offset:32
	v_mul_f32_e64 v28, v28, v252
	v_mul_f32_e64 v29, v29, v253
	v_mul_f32_e64 v30, v30, v254
	v_mul_f32_e64 v31, v31, v255
	v_cvt_pk_bf16_f32 v28, v28, v29
	v_cvt_pk_bf16_f32 v29, v30, v31
	global_store_dwordx2 v[230:231], v[28:29], off offset:48
	s_waitcnt vmcnt(4)
	v_pk_mul_f32 v[0:1], v[0:1], v[214:215]
	v_pk_mul_f32 v[2:3], v[2:3], v[216:217]
	v_cvt_pk_bf16_f32 v0, v0, v1
	v_cvt_pk_bf16_f32 v1, v2, v3
	global_store_dwordx2 v[230:231], v[0:1], off offset:64
	v_pk_mul_f32 v[4:5], v[4:5], v[218:219]
	v_pk_mul_f32 v[6:7], v[6:7], v[220:221]
	v_cvt_pk_bf16_f32 v4, v4, v5
	v_cvt_pk_bf16_f32 v5, v6, v7
	global_store_dwordx2 v[230:231], v[4:5], off offset:80
	v_pk_mul_f32 v[8:9], v[8:9], v[222:223]
	v_pk_mul_f32 v[10:11], v[10:11], v[224:225]
	v_cvt_pk_bf16_f32 v8, v8, v9
	v_cvt_pk_bf16_f32 v9, v10, v11
	global_store_dwordx2 v[230:231], v[8:9], off offset:96
	v_pk_mul_f32 v[12:13], v[12:13], v[226:227]
	v_pk_mul_f32 v[14:15], v[14:15], v[228:229]
	v_cvt_pk_bf16_f32 v12, v12, v13
	v_cvt_pk_bf16_f32 v13, v14, v15
	global_store_dwordx2 v[230:231], v[12:13], off offset:112
	s_waitcnt lgkmcnt(0)
	s_barrier
	s_cbranch_vccnz .LBB9_444
.LBB9_422:
	s_waitcnt vmcnt(8)
	ds_write_b128 v173, v[36:39]
	ds_write_b128 v174, v[40:43]
	ds_write_b128 v175, v[44:47]
	s_and_saveexec_b64 s[2:3], s[0:1]
	s_cbranch_execnz .LBB9_442
	s_or_b64 exec, exec, s[2:3]
	s_and_saveexec_b64 s[2:3], s[4:5]
	s_cbranch_execnz .LBB9_443

; __device__ __forceinline__ void pool_units(const Ptrs& P, LAS unsigned char* lds, int bx, int G, int tid, int wave, int lane) {
;     ...
;         if (g != gcur) { const bf16_t* PWg = (const bf16_t*)(ws + WS_PW) + g * 16384; gcur = g;
; #pragma unroll
;             for (int j = 0; j < 2; ++j)
; #pragma unroll
;                 for (int ks = 0; ks < 8; ++ks) wa[j][ks] = *(const bf16x8_t*)(PWg + (size_t)(32 * (2 * (wave & 1) + j) + r) * 128 + 16 * ks + 8 * hh); }
;     ...
;                 for (int g4 = 0; g4 < 4; ++g4) { const int d = 32 * (2 * (wave & 1) + j) + 8 * g4 + 4 * hh; const f32x4 sc = *(const f32x4*)(P.pool_scale + g * 128 + d);
.LBB9_425:
	s_lshl_b32 s6, s19, 15
	v_lshl_add_u64 v[0:1], v[128:129], 0, s[6:7]
	global_load_dwordx4 v[80:83], v[0:1], off
	global_load_dwordx4 v[76:79], v[0:1], off offset:32
	global_load_dwordx4 v[72:75], v[0:1], off offset:64
	global_load_dwordx4 v[68:71], v[0:1], off offset:96
	global_load_dwordx4 v[64:67], v[0:1], off offset:128
	global_load_dwordx4 v[60:63], v[0:1], off offset:160
	global_load_dwordx4 v[56:59], v[0:1], off offset:192
	global_load_dwordx4 v[52:55], v[0:1], off offset:224
	v_add_co_u32_e32 v0, vcc, 0x2000, v0
	s_mov_b32 s17, s19
	s_nop 0
	v_addc_co_u32_e32 v1, vcc, 0, v1, vcc
	global_load_dwordx4 v[112:115], v[0:1], off
	global_load_dwordx4 v[108:111], v[0:1], off offset:32
	global_load_dwordx4 v[104:107], v[0:1], off offset:64
	global_load_dwordx4 v[100:103], v[0:1], off offset:96
	global_load_dwordx4 v[96:99], v[0:1], off offset:128
	global_load_dwordx4 v[92:95], v[0:1], off offset:160
	global_load_dwordx4 v[88:91], v[0:1], off offset:192
	global_load_dwordx4 v[84:87], v[0:1], off offset:224
	s_lshl_b32 s6, s19, 9
	v_lshl_add_u64 v[0:1], v[130:131], 0, s[6:7]
	global_load_dwordx4 v[238:241], v[0:1], off
	global_load_dwordx4 v[242:245], v[0:1], off offset:32
	global_load_dwordx4 v[246:249], v[0:1], off offset:64
	global_load_dwordx4 v[252:255], v[0:1], off offset:96

; __device__ __forceinline__ u32x4 pack8(const float (&v)[8]) { u32x4 w; w.x = cvtpk(v[0], v[1]); w.y = cvtpk(v[2], v[3]); w.z = cvtpk(v[4], v[5]); w.w = cvtpk(v[6], v[7]); return w; }
;     __device__ __forceinline__ void operator()(pg8::f32x4 (&acc)[2][2][4][2], const pg8::Unit& u, int wr, int wc, int fr, int fq) const {
; #pragma unroll
;         for (int ai = 0; ai < 2; ++ai)
; #pragma unroll
;             for (int m = 0; m < 4; ++m)
; #pragma unroll
;                 for (int bj = 0; bj < 2; ++bj) {
;                     const int row = u.pm * 256 + ai * 128 + wr * 64 + m * 16 + fr, c0 = u.pn * 256 + bj * 128 + wc * 32 + 8 * fq;
;                     if (u.seg == 0) { float rr[8]; unpack8(__builtin_nontemporal_load((const u32x4*)(GATES + (size_t)row * 2048 + 1024 + c0)), rr);
; #pragma unroll
;                         for (int i = 0; i < 8; ++i) acc[ai][bj][m][i >> 2][i & 3] *= rr[i];
;                     } else { float ga[8], o[8]; unpack8(__builtin_nontemporal_load((const u32x4*)(GATES + (size_t)row * 2048 + c0)), ga);
; #pragma unroll
;                         for (int i = 0; i < 8; ++i) o[i] = ga[i] * acc[ai][bj][m][i >> 2][i & 3];
;                         *(u32x4*)(U + (size_t)row * DM + c0) = pack8(o); }
;                 }
;     }
.LBB9_521:
	s_lshl_b32 s19, s26, 8
	s_lshl_b32 s2, s4, 9
	v_lshl_add_u32 v240, v159, 1, s2
	s_not_b64 s[4:5], s[28:29]
	s_and_b64 vcc, exec, s[28:29]
	s_cbranch_vccnz .Lp4e_seg1
	v_add_u32_e32 v161, s19, v150
	v_lshl_add_u32 v161, v161, 12, v240
	global_load_dwordx4 v[162:165], v161, s[10:11] offset:2048 nt
	global_load_dwordx4 v[166:169], v161, s[10:11] offset:2304 nt
	v_add_u32_e32 v161, s19, v152
	v_lshl_add_u32 v161, v161, 12, v240
	global_load_dwordx4 v[170:173], v161, s[10:11] offset:2048 nt
	global_load_dwordx4 v[174:177], v161, s[10:11] offset:2304 nt
	v_add_u32_e32 v161, s19, v153
	v_lshl_add_u32 v161, v161, 12, v240
	global_load_dwordx4 v[178:181], v161, s[10:11] offset:2048 nt
	global_load_dwordx4 v[182:185], v161, s[10:11] offset:2304 nt
	v_add_u32_e32 v161, s19, v154
	v_lshl_add_u32 v161, v161, 12, v240
	global_load_dwordx4 v[186:189], v161, s[10:11] offset:2048 nt
	global_load_dwordx4 v[190:193], v161, s[10:11] offset:2304 nt
	v_add_u32_e32 v161, s19, v155
	v_lshl_add_u32 v161, v161, 12, v240
	global_load_dwordx4 v[194:197], v161, s[10:11] offset:2048 nt
	global_load_dwordx4 v[198:201], v161, s[10:11] offset:2304 nt
	v_add_u32_e32 v161, s19, v156
	v_lshl_add_u32 v161, v161, 12, v240
	global_load_dwordx4 v[202:205], v161, s[10:11] offset:2048 nt
	global_load_dwordx4 v[210:213], v161, s[10:11] offset:2304 nt
	v_add_u32_e32 v161, s19, v157
	v_lshl_add_u32 v161, v161, 12, v240
	global_load_dwordx4 v[214:217], v161, s[10:11] offset:2048 nt
	global_load_dwordx4 v[218:221], v161, s[10:11] offset:2304 nt
	v_add_u32_e32 v161, s19, v158
	v_lshl_add_u32 v161, v161, 12, v240
	global_load_dwordx4 v[222:225], v161, s[10:11] offset:2048 nt
	global_load_dwordx4 v[144:147], v161, s[10:11] offset:2304 nt
	s_waitcnt vmcnt(15)
	v_lshlrev_b32_e32 v148, 16, v162
	v_and_b32_e32 v149, 0xffff0000, v162
	v_lshlrev_b32_e32 v238, 16, v163
	v_and_b32_e32 v239, 0xffff0000, v163
	v_lshlrev_b32_e32 v162, 16, v164
	v_and_b32_e32 v163, 0xffff0000, v164
	v_lshlrev_b32_e32 v164, 16, v165
	v_and_b32_e32 v165, 0xffff0000, v165
	v_pk_mul_f32 v[124:125], v[124:125], v[148:149]
	v_pk_mul_f32 v[126:127], v[126:127], v[238:239]
	v_pk_mul_f32 v[120:121], v[120:121], v[162:163]
	v_pk_mul_f32 v[122:123], v[122:123], v[164:165]
	s_waitcnt vmcnt(14)
	v_lshlrev_b32_e32 v148, 16, v166
	v_and_b32_e32 v149, 0xffff0000, v166
	v_lshlrev_b32_e32 v238, 16, v167
	v_and_b32_e32 v239, 0xffff0000, v167
	v_lshlrev_b32_e32 v166, 16, v168
	v_and_b32_e32 v167, 0xffff0000, v168
	v_lshlrev_b32_e32 v168, 16, v169
	v_and_b32_e32 v169, 0xffff0000, v169
	v_pk_mul_f32 v[92:93], v[92:93], v[148:149]
	v_pk_mul_f32 v[94:95], v[94:95], v[238:239]
	v_pk_mul_f32 v[88:89], v[88:89], v[166:167]
	v_pk_mul_f32 v[90:91], v[90:91], v[168:169]
	s_waitcnt vmcnt(13)
	v_lshlrev_b32_e32 v148, 16, v170
	v_and_b32_e32 v149, 0xffff0000, v170
	v_lshlrev_b32_e32 v238, 16, v171
	v_and_b32_e32 v239, 0xffff0000, v171
	v_lshlrev_b32_e32 v170, 16, v172
	v_and_b32_e32 v171, 0xffff0000, v172
	v_lshlrev_b32_e32 v172, 16, v173
	v_and_b32_e32 v173, 0xffff0000, v173
	v_pk_mul_f32 v[116:117], v[116:117], v[148:149]
	v_pk_mul_f32 v[118:119], v[118:119], v[238:239]
	v_pk_mul_f32 v[112:113], v[112:113], v[170:171]
	v_pk_mul_f32 v[114:115], v[114:115], v[172:173]
	s_waitcnt vmcnt(12)
	v_lshlrev_b32_e32 v148, 16, v174
	v_and_b32_e32 v149, 0xffff0000, v174
	v_lshlrev_b32_e32 v238, 16, v175
	v_and_b32_e32 v239, 0xffff0000, v175
	v_lshlrev_b32_e32 v174, 16, v176
	v_and_b32_e32 v175, 0xffff0000, v176
	v_lshlrev_b32_e32 v176, 16, v177
	v_and_b32_e32 v177, 0xffff0000, v177
	v_pk_mul_f32 v[84:85], v[84:85], v[148:149]
	v_pk_mul_f32 v[86:87], v[86:87], v[238:239]
	v_pk_mul_f32 v[80:81], v[80:81], v[174:175]
	v_pk_mul_f32 v[82:83], v[82:83], v[176:177]
	s_waitcnt vmcnt(11)
	v_lshlrev_b32_e32 v148, 16, v178
	v_and_b32_e32 v149, 0xffff0000, v178
	v_lshlrev_b32_e32 v238, 16, v179
	v_and_b32_e32 v239, 0xffff0000, v179
	v_lshlrev_b32_e32 v178, 16, v180
	v_and_b32_e32 v179, 0xffff0000, v180
	v_lshlrev_b32_e32 v180, 16, v181
	v_and_b32_e32 v181, 0xffff0000, v181
	v_pk_mul_f32 v[108:109], v[108:109], v[148:149]
	v_pk_mul_f32 v[110:111], v[110:111], v[238:239]
	v_pk_mul_f32 v[104:105], v[104:105], v[178:179]
	v_pk_mul_f32 v[106:107], v[106:107], v[180:181]
	s_waitcnt vmcnt(10)
	v_lshlrev_b32_e32 v148, 16, v182
	v_and_b32_e32 v149, 0xffff0000, v182
	v_lshlrev_b32_e32 v238, 16, v183
	v_and_b32_e32 v239, 0xffff0000, v183
	v_lshlrev_b32_e32 v182, 16, v184
	v_and_b32_e32 v183, 0xffff0000, v184
	v_lshlrev_b32_e32 v184, 16, v185
	v_and_b32_e32 v185, 0xffff0000, v185
	v_pk_mul_f32 v[76:77], v[76:77], v[148:149]
	v_pk_mul_f32 v[78:79], v[78:79], v[238:239]
	v_pk_mul_f32 v[72:73], v[72:73], v[182:183]
	v_pk_mul_f32 v[74:75], v[74:75], v[184:185]
	s_waitcnt vmcnt(9)
	v_lshlrev_b32_e32 v148, 16, v186
	v_and_b32_e32 v149, 0xffff0000, v186
	v_lshlrev_b32_e32 v238, 16, v187
	v_and_b32_e32 v239, 0xffff0000, v187
	v_lshlrev_b32_e32 v186, 16, v188
	v_and_b32_e32 v187, 0xffff0000, v188
	v_lshlrev_b32_e32 v188, 16, v189
	v_and_b32_e32 v189, 0xffff0000, v189
	v_pk_mul_f32 v[100:101], v[100:101], v[148:149]
	v_pk_mul_f32 v[102:103], v[102:103], v[238:239]
	v_pk_mul_f32 v[96:97], v[96:97], v[186:187]
	v_pk_mul_f32 v[98:99], v[98:99], v[188:189]
	s_waitcnt vmcnt(8)
	v_lshlrev_b32_e32 v148, 16, v190
	v_and_b32_e32 v149, 0xffff0000, v190
	v_lshlrev_b32_e32 v238, 16, v191
	v_and_b32_e32 v239, 0xffff0000, v191
	v_lshlrev_b32_e32 v190, 16, v192
	v_and_b32_e32 v191, 0xffff0000, v192
	v_lshlrev_b32_e32 v192, 16, v193
	v_and_b32_e32 v193, 0xffff0000, v193
	v_pk_mul_f32 v[68:69], v[68:69], v[148:149]
	v_pk_mul_f32 v[70:71], v[70:71], v[238:239]
	v_pk_mul_f32 v[64:65], v[64:65], v[190:191]
	v_pk_mul_f32 v[66:67], v[66:67], v[192:193]
	s_waitcnt vmcnt(7)
; __device__ __forceinline__ u32x4 pack8(const float (&v)[8]) { u32x4 w; w.x = cvtpk(v[0], v[1]); w.y = cvtpk(v[2], v[3]); w.z = cvtpk(v[4], v[5]); w.w = cvtpk(v[6], v[7]); return w; }
;     __device__ __forceinline__ void operator()(pg8::f32x4 (&acc)[2][2][4][2], const pg8::Unit& u, int wr, int wc, int fr, int fq) const {
; #pragma unroll
;         for (int ai = 0; ai < 2; ++ai)
; #pragma unroll
;             for (int m = 0; m < 4; ++m)
; #pragma unroll
;                 for (int bj = 0; bj < 2; ++bj) {
;                     const int row = u.pm * 256 + ai * 128 + wr * 64 + m * 16 + fr, c0 = u.pn * 256 + bj * 128 + wc * 32 + 8 * fq;
;                     if (u.seg == 0) { float rr[8]; unpack8(__builtin_nontemporal_load((const u32x4*)(GATES + (size_t)row * 2048 + 1024 + c0)), rr);
; #pragma unroll
;                         for (int i = 0; i < 8; ++i) acc[ai][bj][m][i >> 2][i & 3] *= rr[i];
;                     } else { float ga[8], o[8]; unpack8(__builtin_nontemporal_load((const u32x4*)(GATES + (size_t)row * 2048 + c0)), ga);
; #pragma unroll
;                         for (int i = 0; i < 8; ++i) o[i] = ga[i] * acc[ai][bj][m][i >> 2][i & 3];
;                         *(u32x4*)(U + (size_t)row * DM + c0) = pack8(o); }
;                 }
;     }
	v_lshlrev_b32_e32 v148, 16, v194
	v_and_b32_e32 v149, 0xffff0000, v194
	v_lshlrev_b32_e32 v238, 16, v195
	v_and_b32_e32 v239, 0xffff0000, v195
	v_lshlrev_b32_e32 v194, 16, v196
	v_and_b32_e32 v195, 0xffff0000, v196
	v_lshlrev_b32_e32 v196, 16, v197
	v_and_b32_e32 v197, 0xffff0000, v197
	v_pk_mul_f32 v[60:61], v[60:61], v[148:149]
	v_pk_mul_f32 v[62:63], v[62:63], v[238:239]
	v_pk_mul_f32 v[56:57], v[56:57], v[194:195]
	v_pk_mul_f32 v[58:59], v[58:59], v[196:197]
	s_waitcnt vmcnt(6)
	v_lshlrev_b32_e32 v148, 16, v198
	v_and_b32_e32 v149, 0xffff0000, v198
	v_lshlrev_b32_e32 v238, 16, v199
	v_and_b32_e32 v239, 0xffff0000, v199
	v_lshlrev_b32_e32 v198, 16, v200
	v_and_b32_e32 v199, 0xffff0000, v200
	v_lshlrev_b32_e32 v200, 16, v201
	v_and_b32_e32 v201, 0xffff0000, v201
	v_pk_mul_f32 v[28:29], v[28:29], v[148:149]
	v_pk_mul_f32 v[30:31], v[30:31], v[238:239]
	v_pk_mul_f32 v[24:25], v[24:25], v[198:199]
	v_pk_mul_f32 v[26:27], v[26:27], v[200:201]
	s_waitcnt vmcnt(5)
	v_lshlrev_b32_e32 v148, 16, v202
	v_and_b32_e32 v149, 0xffff0000, v202
	v_lshlrev_b32_e32 v238, 16, v203
	v_and_b32_e32 v239, 0xffff0000, v203
	v_lshlrev_b32_e32 v202, 16, v204
	v_and_b32_e32 v203, 0xffff0000, v204
	v_lshlrev_b32_e32 v204, 16, v205
	v_and_b32_e32 v205, 0xffff0000, v205
	v_pk_mul_f32 v[52:53], v[52:53], v[148:149]
	v_pk_mul_f32 v[54:55], v[54:55], v[238:239]
	v_pk_mul_f32 v[48:49], v[48:49], v[202:203]
	v_pk_mul_f32 v[50:51], v[50:51], v[204:205]
	s_waitcnt vmcnt(4)
	v_lshlrev_b32_e32 v148, 16, v210
	v_and_b32_e32 v149, 0xffff0000, v210
	v_lshlrev_b32_e32 v238, 16, v211
	v_and_b32_e32 v239, 0xffff0000, v211
	v_lshlrev_b32_e32 v210, 16, v212
	v_and_b32_e32 v211, 0xffff0000, v212
	v_lshlrev_b32_e32 v212, 16, v213
	v_and_b32_e32 v213, 0xffff0000, v213
	v_pk_mul_f32 v[20:21], v[20:21], v[148:149]
	v_pk_mul_f32 v[22:23], v[22:23], v[238:239]
	v_pk_mul_f32 v[16:17], v[16:17], v[210:211]
	v_pk_mul_f32 v[18:19], v[18:19], v[212:213]
	s_waitcnt vmcnt(3)
	v_lshlrev_b32_e32 v148, 16, v214
	v_and_b32_e32 v149, 0xffff0000, v214
	v_lshlrev_b32_e32 v238, 16, v215
	v_and_b32_e32 v239, 0xffff0000, v215
	v_lshlrev_b32_e32 v214, 16, v216
	v_and_b32_e32 v215, 0xffff0000, v216
	v_lshlrev_b32_e32 v216, 16, v217
	v_and_b32_e32 v217, 0xffff0000, v217
	v_pk_mul_f32 v[44:45], v[44:45], v[148:149]
	v_pk_mul_f32 v[46:47], v[46:47], v[238:239]
	v_pk_mul_f32 v[40:41], v[40:41], v[214:215]
	v_pk_mul_f32 v[42:43], v[42:43], v[216:217]
	s_waitcnt vmcnt(2)
	v_lshlrev_b32_e32 v148, 16, v218
	v_and_b32_e32 v149, 0xffff0000, v218
	v_lshlrev_b32_e32 v238, 16, v219
	v_and_b32_e32 v239, 0xffff0000, v219
	v_lshlrev_b32_e32 v218, 16, v220
	v_and_b32_e32 v219, 0xffff0000, v220
	v_lshlrev_b32_e32 v220, 16, v221
	v_and_b32_e32 v221, 0xffff0000, v221
	v_pk_mul_f32 v[12:13], v[12:13], v[148:149]
	v_pk_mul_f32 v[14:15], v[14:15], v[238:239]
	v_pk_mul_f32 v[8:9], v[8:9], v[218:219]
	v_pk_mul_f32 v[10:11], v[10:11], v[220:221]
	s_waitcnt vmcnt(1)
	v_lshlrev_b32_e32 v148, 16, v222
	v_and_b32_e32 v149, 0xffff0000, v222
	v_lshlrev_b32_e32 v238, 16, v223
	v_and_b32_e32 v239, 0xffff0000, v223
	v_lshlrev_b32_e32 v222, 16, v224
	v_and_b32_e32 v223, 0xffff0000, v224
	v_lshlrev_b32_e32 v224, 16, v225
	v_and_b32_e32 v225, 0xffff0000, v225
	v_pk_mul_f32 v[36:37], v[36:37], v[148:149]
	v_pk_mul_f32 v[38:39], v[38:39], v[238:239]
	v_pk_mul_f32 v[32:33], v[32:33], v[222:223]
	v_pk_mul_f32 v[34:35], v[34:35], v[224:225]
	s_waitcnt vmcnt(0)
	v_lshlrev_b32_e32 v148, 16, v144
	v_and_b32_e32 v149, 0xffff0000, v144
	v_lshlrev_b32_e32 v238, 16, v145
	v_and_b32_e32 v239, 0xffff0000, v145
	v_lshlrev_b32_e32 v144, 16, v146
	v_and_b32_e32 v145, 0xffff0000, v146
	v_lshlrev_b32_e32 v146, 16, v147
	v_and_b32_e32 v147, 0xffff0000, v147
	v_pk_mul_f32 v[4:5], v[4:5], v[148:149]
	v_pk_mul_f32 v[6:7], v[6:7], v[238:239]
	v_pk_mul_f32 v[0:1], v[0:1], v[144:145]
	v_pk_mul_f32 v[2:3], v[2:3], v[146:147]
	s_branch .Lp4e_done
.Lp4e_seg1:
	v_add_u32_e32 v161, s19, v150
	v_lshl_add_u32 v161, v161, 12, v240
	global_load_dwordx4 v[162:165], v161, s[10:11] offset:0 nt
	global_load_dwordx4 v[166:169], v161, s[10:11] offset:256 nt
	v_add_u32_e32 v161, s19, v152
	v_lshl_add_u32 v161, v161, 12, v240
	global_load_dwordx4 v[170:173], v161, s[10:11] offset:0 nt
	global_load_dwordx4 v[174:177], v161, s[10:11] offset:256 nt
	v_add_u32_e32 v161, s19, v153
	v_lshl_add_u32 v161, v161, 12, v240
	global_load_dwordx4 v[178:181], v161, s[10:11] offset:0 nt
	global_load_dwordx4 v[182:185], v161, s[10:11] offset:256 nt
	v_add_u32_e32 v161, s19, v154
	v_lshl_add_u32 v161, v161, 12, v240
	global_load_dwordx4 v[186:189], v161, s[10:11] offset:0 nt
	global_load_dwordx4 v[190:193], v161, s[10:11] offset:256 nt
	v_add_u32_e32 v161, s19, v155
	v_lshl_add_u32 v161, v161, 12, v240
	global_load_dwordx4 v[194:197], v161, s[10:11] offset:0 nt
	global_load_dwordx4 v[198:201], v161, s[10:11] offset:256 nt
	v_add_u32_e32 v161, s19, v156
	v_lshl_add_u32 v161, v161, 12, v240
	global_load_dwordx4 v[202:205], v161, s[10:11] offset:0 nt
	global_load_dwordx4 v[210:213], v161, s[10:11] offset:256 nt
	v_add_u32_e32 v161, s19, v157
	v_lshl_add_u32 v161, v161, 12, v240
	global_load_dwordx4 v[214:217], v161, s[10:11] offset:0 nt
	global_load_dwordx4 v[218:221], v161, s[10:11] offset:256 nt
	v_add_u32_e32 v161, s19, v158
	v_lshl_add_u32 v161, v161, 12, v240
	global_load_dwordx4 v[222:225], v161, s[10:11] offset:0 nt
	global_load_dwordx4 v[144:147], v161, s[10:11] offset:256 nt
	s_waitcnt vmcnt(15)
; __device__ __forceinline__ u32x4 pack8(const float (&v)[8]) { u32x4 w; w.x = cvtpk(v[0], v[1]); w.y = cvtpk(v[2], v[3]); w.z = cvtpk(v[4], v[5]); w.w = cvtpk(v[6], v[7]); return w; }
;     __device__ __forceinline__ void operator()(pg8::f32x4 (&acc)[2][2][4][2], const pg8::Unit& u, int wr, int wc, int fr, int fq) const {
;     ...
;                     } else { float ga[8], o[8]; unpack8(__builtin_nontemporal_load((const u32x4*)(GATES + (size_t)row * 2048 + c0)), ga);
; #pragma unroll
;                         for (int i = 0; i < 8; ++i) o[i] = ga[i] * acc[ai][bj][m][i >> 2][i & 3];
;                         *(u32x4*)(U + (size_t)row * DM + c0) = pack8(o); }
	v_lshlrev_b32_e32 v148, 16, v162
	v_and_b32_e32 v149, 0xffff0000, v162
	v_lshlrev_b32_e32 v238, 16, v163
	v_and_b32_e32 v239, 0xffff0000, v163
	v_lshlrev_b32_e32 v162, 16, v164
	v_and_b32_e32 v163, 0xffff0000, v164
	v_lshlrev_b32_e32 v164, 16, v165
	v_and_b32_e32 v165, 0xffff0000, v165
	v_pk_mul_f32 v[148:149], v[124:125], v[148:149]
	v_pk_mul_f32 v[238:239], v[126:127], v[238:239]
	v_pk_mul_f32 v[162:163], v[120:121], v[162:163]
	v_pk_mul_f32 v[164:165], v[122:123], v[164:165]
	v_add_u32_e32 v241, s19, v150
	v_lshl_add_u32 v241, v241, 11, v240
	v_cvt_pk_bf16_f32 v165, v164, v165
	v_cvt_pk_bf16_f32 v164, v162, v163
	v_cvt_pk_bf16_f32 v162, v148, v149
	v_cvt_pk_bf16_f32 v163, v238, v239
	global_store_dwordx4 v241, v[162:165], s[12:13] offset:0
	s_waitcnt vmcnt(15)
	v_lshlrev_b32_e32 v148, 16, v166
	v_and_b32_e32 v149, 0xffff0000, v166
	v_lshlrev_b32_e32 v238, 16, v167
	v_and_b32_e32 v239, 0xffff0000, v167
	v_lshlrev_b32_e32 v166, 16, v168
	v_and_b32_e32 v167, 0xffff0000, v168
	v_lshlrev_b32_e32 v168, 16, v169
	v_and_b32_e32 v169, 0xffff0000, v169
	v_pk_mul_f32 v[148:149], v[92:93], v[148:149]
	v_pk_mul_f32 v[238:239], v[94:95], v[238:239]
	v_pk_mul_f32 v[166:167], v[88:89], v[166:167]
	v_pk_mul_f32 v[168:169], v[90:91], v[168:169]
	v_cvt_pk_bf16_f32 v169, v168, v169
	v_cvt_pk_bf16_f32 v168, v166, v167
	v_cvt_pk_bf16_f32 v166, v148, v149
	v_cvt_pk_bf16_f32 v167, v238, v239
	global_store_dwordx4 v241, v[166:169], s[12:13] offset:256
	s_waitcnt vmcnt(15)
	v_lshlrev_b32_e32 v148, 16, v170
	v_and_b32_e32 v149, 0xffff0000, v170
	v_lshlrev_b32_e32 v238, 16, v171
	v_and_b32_e32 v239, 0xffff0000, v171
	v_lshlrev_b32_e32 v170, 16, v172
	v_and_b32_e32 v171, 0xffff0000, v172
	v_lshlrev_b32_e32 v172, 16, v173
	v_and_b32_e32 v173, 0xffff0000, v173
	v_pk_mul_f32 v[148:149], v[116:117], v[148:149]
	v_pk_mul_f32 v[238:239], v[118:119], v[238:239]
	v_pk_mul_f32 v[170:171], v[112:113], v[170:171]
	v_pk_mul_f32 v[172:173], v[114:115], v[172:173]
	v_add_u32_e32 v241, s19, v152
	v_lshl_add_u32 v241, v241, 11, v240
	v_cvt_pk_bf16_f32 v173, v172, v173
	v_cvt_pk_bf16_f32 v172, v170, v171
	v_cvt_pk_bf16_f32 v170, v148, v149
	v_cvt_pk_bf16_f32 v171, v238, v239
	global_store_dwordx4 v241, v[170:173], s[12:13] offset:0
	s_waitcnt vmcnt(15)
	v_lshlrev_b32_e32 v148, 16, v174
	v_and_b32_e32 v149, 0xffff0000, v174
	v_lshlrev_b32_e32 v238, 16, v175
	v_and_b32_e32 v239, 0xffff0000, v175
	v_lshlrev_b32_e32 v174, 16, v176
	v_and_b32_e32 v175, 0xffff0000, v176
	v_lshlrev_b32_e32 v176, 16, v177
	v_and_b32_e32 v177, 0xffff0000, v177
	v_pk_mul_f32 v[148:149], v[84:85], v[148:149]
	v_pk_mul_f32 v[238:239], v[86:87], v[238:239]
	v_pk_mul_f32 v[174:175], v[80:81], v[174:175]
	v_pk_mul_f32 v[176:177], v[82:83], v[176:177]
	v_cvt_pk_bf16_f32 v177, v176, v177
	v_cvt_pk_bf16_f32 v176, v174, v175
	v_cvt_pk_bf16_f32 v174, v148, v149
	v_cvt_pk_bf16_f32 v175, v238, v239
	global_store_dwordx4 v241, v[174:177], s[12:13] offset:256
	s_waitcnt vmcnt(15)
	v_lshlrev_b32_e32 v148, 16, v178
	v_and_b32_e32 v149, 0xffff0000, v178
	v_lshlrev_b32_e32 v238, 16, v179
	v_and_b32_e32 v239, 0xffff0000, v179
	v_lshlrev_b32_e32 v178, 16, v180
	v_and_b32_e32 v179, 0xffff0000, v180
	v_lshlrev_b32_e32 v180, 16, v181
	v_and_b32_e32 v181, 0xffff0000, v181
	v_pk_mul_f32 v[148:149], v[108:109], v[148:149]
	v_pk_mul_f32 v[238:239], v[110:111], v[238:239]
	v_pk_mul_f32 v[178:179], v[104:105], v[178:179]
	v_pk_mul_f32 v[180:181], v[106:107], v[180:181]
	v_add_u32_e32 v241, s19, v153
	v_lshl_add_u32 v241, v241, 11, v240
	v_cvt_pk_bf16_f32 v181, v180, v181
	v_cvt_pk_bf16_f32 v180, v178, v179
	v_cvt_pk_bf16_f32 v178, v148, v149
	v_cvt_pk_bf16_f32 v179, v238, v239
	global_store_dwordx4 v241, v[178:181], s[12:13] offset:0
	s_waitcnt vmcnt(15)
	v_lshlrev_b32_e32 v148, 16, v182
	v_and_b32_e32 v149, 0xffff0000, v182
	v_lshlrev_b32_e32 v238, 16, v183
	v_and_b32_e32 v239, 0xffff0000, v183
	v_lshlrev_b32_e32 v182, 16, v184
	v_and_b32_e32 v183, 0xffff0000, v184
	v_lshlrev_b32_e32 v184, 16, v185
	v_and_b32_e32 v185, 0xffff0000, v185
	v_pk_mul_f32 v[148:149], v[76:77], v[148:149]
	v_pk_mul_f32 v[238:239], v[78:79], v[238:239]
	v_pk_mul_f32 v[182:183], v[72:73], v[182:183]
	v_pk_mul_f32 v[184:185], v[74:75], v[184:185]
	v_cvt_pk_bf16_f32 v185, v184, v185
	v_cvt_pk_bf16_f32 v184, v182, v183
	v_cvt_pk_bf16_f32 v182, v148, v149
	v_cvt_pk_bf16_f32 v183, v238, v239
	global_store_dwordx4 v241, v[182:185], s[12:13] offset:256
	s_waitcnt vmcnt(15)
	v_lshlrev_b32_e32 v148, 16, v186
	v_and_b32_e32 v149, 0xffff0000, v186
	v_lshlrev_b32_e32 v238, 16, v187
	v_and_b32_e32 v239, 0xffff0000, v187
	v_lshlrev_b32_e32 v186, 16, v188
	v_and_b32_e32 v187, 0xffff0000, v188
	v_lshlrev_b32_e32 v188, 16, v189
	v_and_b32_e32 v189, 0xffff0000, v189
	v_pk_mul_f32 v[148:149], v[100:101], v[148:149]
	v_pk_mul_f32 v[238:239], v[102:103], v[238:239]
	v_pk_mul_f32 v[186:187], v[96:97], v[186:187]
	v_pk_mul_f32 v[188:189], v[98:99], v[188:189]
	v_add_u32_e32 v241, s19, v154
	v_lshl_add_u32 v241, v241, 11, v240
	v_cvt_pk_bf16_f32 v189, v188, v189
	v_cvt_pk_bf16_f32 v188, v186, v187
	v_cvt_pk_bf16_f32 v186, v148, v149
	v_cvt_pk_bf16_f32 v187, v238, v239
	global_store_dwordx4 v241, v[186:189], s[12:13] offset:0
	s_waitcnt vmcnt(15)
	v_lshlrev_b32_e32 v148, 16, v190
	v_and_b32_e32 v149, 0xffff0000, v190
	v_lshlrev_b32_e32 v238, 16, v191
	v_and_b32_e32 v239, 0xffff0000, v191
	v_lshlrev_b32_e32 v190, 16, v192
	v_and_b32_e32 v191, 0xffff0000, v192
	v_lshlrev_b32_e32 v192, 16, v193
	v_and_b32_e32 v193, 0xffff0000, v193
	v_pk_mul_f32 v[148:149], v[68:69], v[148:149]
	v_pk_mul_f32 v[238:239], v[70:71], v[238:239]
	v_pk_mul_f32 v[190:191], v[64:65], v[190:191]
	v_pk_mul_f32 v[192:193], v[66:67], v[192:193]
	v_cvt_pk_bf16_f32 v193, v192, v193
	v_cvt_pk_bf16_f32 v192, v190, v191
	v_cvt_pk_bf16_f32 v190, v148, v149
	v_cvt_pk_bf16_f32 v191, v238, v239
	global_store_dwordx4 v241, v[190:193], s[12:13] offset:256
	s_waitcnt vmcnt(15)
; __device__ __forceinline__ u32x4 pack8(const float (&v)[8]) { u32x4 w; w.x = cvtpk(v[0], v[1]); w.y = cvtpk(v[2], v[3]); w.z = cvtpk(v[4], v[5]); w.w = cvtpk(v[6], v[7]); return w; }
;     __device__ __forceinline__ void operator()(pg8::f32x4 (&acc)[2][2][4][2], const pg8::Unit& u, int wr, int wc, int fr, int fq) const {
;     ...
;                     } else { float ga[8], o[8]; unpack8(__builtin_nontemporal_load((const u32x4*)(GATES + (size_t)row * 2048 + c0)), ga);
; #pragma unroll
;                         for (int i = 0; i < 8; ++i) o[i] = ga[i] * acc[ai][bj][m][i >> 2][i & 3];
;                         *(u32x4*)(U + (size_t)row * DM + c0) = pack8(o); }
	v_lshlrev_b32_e32 v148, 16, v194
	v_and_b32_e32 v149, 0xffff0000, v194
	v_lshlrev_b32_e32 v238, 16, v195
	v_and_b32_e32 v239, 0xffff0000, v195
	v_lshlrev_b32_e32 v194, 16, v196
	v_and_b32_e32 v195, 0xffff0000, v196
	v_lshlrev_b32_e32 v196, 16, v197
	v_and_b32_e32 v197, 0xffff0000, v197
	v_pk_mul_f32 v[148:149], v[60:61], v[148:149]
	v_pk_mul_f32 v[238:239], v[62:63], v[238:239]
	v_pk_mul_f32 v[194:195], v[56:57], v[194:195]
	v_pk_mul_f32 v[196:197], v[58:59], v[196:197]
	v_add_u32_e32 v241, s19, v155
	v_lshl_add_u32 v241, v241, 11, v240
	v_cvt_pk_bf16_f32 v197, v196, v197
	v_cvt_pk_bf16_f32 v196, v194, v195
	v_cvt_pk_bf16_f32 v194, v148, v149
	v_cvt_pk_bf16_f32 v195, v238, v239
	global_store_dwordx4 v241, v[194:197], s[12:13] offset:0
	s_waitcnt vmcnt(15)
	v_lshlrev_b32_e32 v148, 16, v198
	v_and_b32_e32 v149, 0xffff0000, v198
	v_lshlrev_b32_e32 v238, 16, v199
	v_and_b32_e32 v239, 0xffff0000, v199
	v_lshlrev_b32_e32 v198, 16, v200
	v_and_b32_e32 v199, 0xffff0000, v200
	v_lshlrev_b32_e32 v200, 16, v201
	v_and_b32_e32 v201, 0xffff0000, v201
	v_pk_mul_f32 v[148:149], v[28:29], v[148:149]
	v_pk_mul_f32 v[238:239], v[30:31], v[238:239]
	v_pk_mul_f32 v[198:199], v[24:25], v[198:199]
	v_pk_mul_f32 v[200:201], v[26:27], v[200:201]
	v_cvt_pk_bf16_f32 v201, v200, v201
	v_cvt_pk_bf16_f32 v200, v198, v199
	v_cvt_pk_bf16_f32 v198, v148, v149
	v_cvt_pk_bf16_f32 v199, v238, v239
	global_store_dwordx4 v241, v[198:201], s[12:13] offset:256
	s_waitcnt vmcnt(15)
	v_lshlrev_b32_e32 v148, 16, v202
	v_and_b32_e32 v149, 0xffff0000, v202
	v_lshlrev_b32_e32 v238, 16, v203
	v_and_b32_e32 v239, 0xffff0000, v203
	v_lshlrev_b32_e32 v202, 16, v204
	v_and_b32_e32 v203, 0xffff0000, v204
	v_lshlrev_b32_e32 v204, 16, v205
	v_and_b32_e32 v205, 0xffff0000, v205
	v_pk_mul_f32 v[148:149], v[52:53], v[148:149]
	v_pk_mul_f32 v[238:239], v[54:55], v[238:239]
	v_pk_mul_f32 v[202:203], v[48:49], v[202:203]
	v_pk_mul_f32 v[204:205], v[50:51], v[204:205]
	v_add_u32_e32 v241, s19, v156
	v_lshl_add_u32 v241, v241, 11, v240
	v_cvt_pk_bf16_f32 v205, v204, v205
	v_cvt_pk_bf16_f32 v204, v202, v203
	v_cvt_pk_bf16_f32 v202, v148, v149
	v_cvt_pk_bf16_f32 v203, v238, v239
	global_store_dwordx4 v241, v[202:205], s[12:13] offset:0
	s_waitcnt vmcnt(15)
	v_lshlrev_b32_e32 v148, 16, v210
	v_and_b32_e32 v149, 0xffff0000, v210
	v_lshlrev_b32_e32 v238, 16, v211
	v_and_b32_e32 v239, 0xffff0000, v211
	v_lshlrev_b32_e32 v210, 16, v212
	v_and_b32_e32 v211, 0xffff0000, v212
	v_lshlrev_b32_e32 v212, 16, v213
	v_and_b32_e32 v213, 0xffff0000, v213
	v_pk_mul_f32 v[148:149], v[20:21], v[148:149]
	v_pk_mul_f32 v[238:239], v[22:23], v[238:239]
	v_pk_mul_f32 v[210:211], v[16:17], v[210:211]
	v_pk_mul_f32 v[212:213], v[18:19], v[212:213]
	v_cvt_pk_bf16_f32 v213, v212, v213
	v_cvt_pk_bf16_f32 v212, v210, v211
	v_cvt_pk_bf16_f32 v210, v148, v149
	v_cvt_pk_bf16_f32 v211, v238, v239
	global_store_dwordx4 v241, v[210:213], s[12:13] offset:256
	s_waitcnt vmcnt(15)
	v_lshlrev_b32_e32 v148, 16, v214
	v_and_b32_e32 v149, 0xffff0000, v214
	v_lshlrev_b32_e32 v238, 16, v215
	v_and_b32_e32 v239, 0xffff0000, v215
	v_lshlrev_b32_e32 v214, 16, v216
	v_and_b32_e32 v215, 0xffff0000, v216
	v_lshlrev_b32_e32 v216, 16, v217
	v_and_b32_e32 v217, 0xffff0000, v217
	v_pk_mul_f32 v[148:149], v[44:45], v[148:149]
	v_pk_mul_f32 v[238:239], v[46:47], v[238:239]
	v_pk_mul_f32 v[214:215], v[40:41], v[214:215]
	v_pk_mul_f32 v[216:217], v[42:43], v[216:217]
	v_add_u32_e32 v241, s19, v157
	v_lshl_add_u32 v241, v241, 11, v240
	v_cvt_pk_bf16_f32 v217, v216, v217
	v_cvt_pk_bf16_f32 v216, v214, v215
	v_cvt_pk_bf16_f32 v214, v148, v149
	v_cvt_pk_bf16_f32 v215, v238, v239
	global_store_dwordx4 v241, v[214:217], s[12:13] offset:0
	s_waitcnt vmcnt(15)
	v_lshlrev_b32_e32 v148, 16, v218
	v_and_b32_e32 v149, 0xffff0000, v218
	v_lshlrev_b32_e32 v238, 16, v219
	v_and_b32_e32 v239, 0xffff0000, v219
	v_lshlrev_b32_e32 v218, 16, v220
	v_and_b32_e32 v219, 0xffff0000, v220
	v_lshlrev_b32_e32 v220, 16, v221
	v_and_b32_e32 v221, 0xffff0000, v221
	v_pk_mul_f32 v[148:149], v[12:13], v[148:149]
	v_pk_mul_f32 v[238:239], v[14:15], v[238:239]
	v_pk_mul_f32 v[218:219], v[8:9], v[218:219]
	v_pk_mul_f32 v[220:221], v[10:11], v[220:221]
	v_cvt_pk_bf16_f32 v221, v220, v221
	v_cvt_pk_bf16_f32 v220, v218, v219
	v_cvt_pk_bf16_f32 v218, v148, v149
	v_cvt_pk_bf16_f32 v219, v238, v239
	global_store_dwordx4 v241, v[218:221], s[12:13] offset:256
	s_waitcnt vmcnt(15)
	v_lshlrev_b32_e32 v148, 16, v222
	v_and_b32_e32 v149, 0xffff0000, v222
	v_lshlrev_b32_e32 v238, 16, v223
	v_and_b32_e32 v239, 0xffff0000, v223
	v_lshlrev_b32_e32 v222, 16, v224
	v_and_b32_e32 v223, 0xffff0000, v224
	v_lshlrev_b32_e32 v224, 16, v225
	v_and_b32_e32 v225, 0xffff0000, v225
	v_pk_mul_f32 v[148:149], v[36:37], v[148:149]
	v_pk_mul_f32 v[238:239], v[38:39], v[238:239]
	v_pk_mul_f32 v[222:223], v[32:33], v[222:223]
	v_pk_mul_f32 v[224:225], v[34:35], v[224:225]
	v_add_u32_e32 v241, s19, v158
	v_lshl_add_u32 v241, v241, 11, v240
	v_cvt_pk_bf16_f32 v225, v224, v225
	v_cvt_pk_bf16_f32 v224, v222, v223
	v_cvt_pk_bf16_f32 v222, v148, v149
	v_cvt_pk_bf16_f32 v223, v238, v239
	global_store_dwordx4 v241, v[222:225], s[12:13] offset:0
	s_waitcnt vmcnt(15)
	v_lshlrev_b32_e32 v148, 16, v144
	v_and_b32_e32 v149, 0xffff0000, v144
	v_lshlrev_b32_e32 v238, 16, v145
	v_and_b32_e32 v239, 0xffff0000, v145
	v_lshlrev_b32_e32 v144, 16, v146
	v_and_b32_e32 v145, 0xffff0000, v146
	v_lshlrev_b32_e32 v146, 16, v147
	v_and_b32_e32 v147, 0xffff0000, v147
	v_pk_mul_f32 v[148:149], v[4:5], v[148:149]
	v_pk_mul_f32 v[238:239], v[6:7], v[238:239]
	v_pk_mul_f32 v[144:145], v[0:1], v[144:145]
	v_pk_mul_f32 v[146:147], v[2:3], v[146:147]
	v_cvt_pk_bf16_f32 v147, v146, v147
	v_cvt_pk_bf16_f32 v146, v144, v145
	v_cvt_pk_bf16_f32 v144, v148, v149
	v_cvt_pk_bf16_f32 v145, v238, v239
	global_store_dwordx4 v241, v[144:147], s[12:13] offset:256
; template <class Epi, class Sched, bool ALIGN_EPI = false, bool SP2 = false>
; __device__ __forceinline__ void gemm_phase(PG8_LAS unsigned char* lds, const Gemm g, const Sched& S, const Epi& E) {
;     ...
;         if (!has_next) break;
;         if (!(TwoSeg<Epi>::v && cur.seg == 0)) {
; #pragma unroll
;         for (int a = 0; a < 2; ++a)
; #pragma unroll
;             for (int b = 0; b < 2; ++b)
; #pragma unroll
;                 for (int m = 0; m < 4; ++m)
; #pragma unroll
;                     for (int n = 0; n < 2; ++n) acc[a][b][m][n] = (f32x4){0.f, 0.f, 0.f, 0.f};
;         }
.Lp4e_done:
	s_andn2_b64 vcc, exec, s[0:1]
	s_mov_b64 s[0:1], -1
	s_cbranch_vccnz .LBB9_510
.LBB9_586:
	s_and_b64 vcc, exec, s[4:5]
	s_cbranch_vccnz .LBB9_588
	v_mov_b32_e32 v0, 0
	v_mov_b32_e32 v1, v0
	v_mov_b32_e32 v2, v0
	v_mov_b32_e32 v3, v0
	v_mov_b32_e32 v4, v0
	v_mov_b32_e32 v5, v0
	v_mov_b32_e32 v6, v0
	v_mov_b32_e32 v7, v0
	v_mov_b32_e32 v8, v0
	v_mov_b32_e32 v9, v0
	v_mov_b32_e32 v10, v0
	v_mov_b32_e32 v11, v0
	v_mov_b32_e32 v12, v0
	v_mov_b32_e32 v13, v0
	v_mov_b32_e32 v14, v0
	v_mov_b32_e32 v15, v0
	v_mov_b32_e32 v16, v0
	v_mov_b32_e32 v17, v0
	v_mov_b32_e32 v18, v0
	v_mov_b32_e32 v19, v0
	v_mov_b32_e32 v20, v0
	v_mov_b32_e32 v21, v0
	v_mov_b32_e32 v22, v0
	v_mov_b32_e32 v23, v0
	v_mov_b32_e32 v24, v0
	v_mov_b32_e32 v25, v0
	v_mov_b32_e32 v26, v0
	v_mov_b32_e32 v27, v0
	v_mov_b32_e32 v28, v0
	v_mov_b32_e32 v29, v0
	v_mov_b32_e32 v30, v0
	v_mov_b32_e32 v31, v0
	v_mov_b32_e32 v32, v0
	v_mov_b32_e32 v33, v0
	v_mov_b32_e32 v34, v0
	v_mov_b32_e32 v35, v0
	v_mov_b32_e32 v36, v0
	v_mov_b32_e32 v37, v0
	v_mov_b32_e32 v38, v0
	v_mov_b32_e32 v39, v0
	v_mov_b32_e32 v40, v0
	v_mov_b32_e32 v41, v0
	v_mov_b32_e32 v42, v0
	v_mov_b32_e32 v43, v0
	v_mov_b32_e32 v44, v0
	v_mov_b32_e32 v45, v0
	v_mov_b32_e32 v46, v0
	v_mov_b32_e32 v47, v0
	v_mov_b32_e32 v48, v0
	v_mov_b32_e32 v49, v0
	v_mov_b32_e32 v50, v0
	v_mov_b32_e32 v51, v0
	v_mov_b32_e32 v52, v0
	v_mov_b32_e32 v53, v0
	v_mov_b32_e32 v54, v0
	v_mov_b32_e32 v55, v0
	v_mov_b32_e32 v56, v0
	v_mov_b32_e32 v57, v0
	v_mov_b32_e32 v58, v0
	v_mov_b32_e32 v59, v0
	v_mov_b32_e32 v60, v0
	v_mov_b32_e32 v61, v0
	v_mov_b32_e32 v62, v0
	v_mov_b32_e32 v63, v0
	v_mov_b32_e32 v64, v0
	v_mov_b32_e32 v65, v0
	v_mov_b32_e32 v66, v0
	v_mov_b32_e32 v67, v0
	v_mov_b32_e32 v68, v0
	v_mov_b32_e32 v69, v0
	v_mov_b32_e32 v70, v0
	v_mov_b32_e32 v71, v0
	v_mov_b32_e32 v72, v0
	v_mov_b32_e32 v73, v0
	v_mov_b32_e32 v74, v0
	v_mov_b32_e32 v75, v0
	v_mov_b32_e32 v76, v0
	v_mov_b32_e32 v77, v0
	v_mov_b32_e32 v78, v0
	v_mov_b32_e32 v79, v0
	v_mov_b32_e32 v80, v0
	v_mov_b32_e32 v81, v0
	v_mov_b32_e32 v82, v0
	v_mov_b32_e32 v83, v0
	v_mov_b32_e32 v84, v0
	v_mov_b32_e32 v85, v0
	v_mov_b32_e32 v86, v0
	v_mov_b32_e32 v87, v0
	v_mov_b32_e32 v88, v0
	v_mov_b32_e32 v89, v0
	v_mov_b32_e32 v90, v0
	v_mov_b32_e32 v91, v0
	v_mov_b32_e32 v92, v0
	v_mov_b32_e32 v93, v0
	v_mov_b32_e32 v94, v0
	v_mov_b32_e32 v95, v0
	v_mov_b32_e32 v96, v0
	v_mov_b32_e32 v97, v0
	v_mov_b32_e32 v98, v0
	v_mov_b32_e32 v99, v0
	v_mov_b32_e32 v100, v0
	v_mov_b32_e32 v101, v0
	v_mov_b32_e32 v102, v0
	v_mov_b32_e32 v103, v0
	v_mov_b32_e32 v104, v0
	v_mov_b32_e32 v105, v0
	v_mov_b32_e32 v106, v0
	v_mov_b32_e32 v107, v0
	v_mov_b32_e32 v108, v0
	v_mov_b32_e32 v109, v0
	v_mov_b32_e32 v110, v0
	v_mov_b32_e32 v111, v0
	v_mov_b32_e32 v112, v0
	v_mov_b32_e32 v113, v0
	v_mov_b32_e32 v114, v0
	v_mov_b32_e32 v115, v0
	v_mov_b32_e32 v116, v0
	v_mov_b32_e32 v117, v0
	v_mov_b32_e32 v118, v0
	v_mov_b32_e32 v119, v0
	v_mov_b32_e32 v120, v0
	v_mov_b32_e32 v121, v0
	v_mov_b32_e32 v122, v0
	v_mov_b32_e32 v123, v0
	v_mov_b32_e32 v124, v0
	v_mov_b32_e32 v125, v0
	v_mov_b32_e32 v126, v0
	v_mov_b32_e32 v127, v0

; __device__ __forceinline__ u32x4 pack8(const float (&v)[8]) { u32x4 w; w.x = cvtpk(v[0], v[1]); w.y = cvtpk(v[2], v[3]); w.z = cvtpk(v[4], v[5]); w.w = cvtpk(v[6], v[7]); return w; }
; __device__ __forceinline__ float siluf_(float v) { return v * __builtin_amdgcn_rcpf(1.0f + __builtin_amdgcn_exp2f(-LOG2E * v)); }
; __device__ __forceinline__ float row_rstd(const float* SSQ, int row) {
;     const f32x4 v = *(const f32x4*)(SSQ + (size_t)row * 4);
;     return __builtin_amdgcn_rsqf(((v[0] + v[1]) + (v[2] + v[3])) * (1.0f / DM) + EPS);
; }
;     __device__ __forceinline__ void operator()(const pg8::f32x4 (&acc)[2][2][4][2], const pg8::Unit& u, int wr, int wc, int fr, int fq) const {
;         const int b = u.pm >> 4, c0 = u.pn * 128 + wc * 32 + 8 * fq; const float* bb = e.bias2 + (size_t)b * NUP + u.pn * 256 + wc * 32 + 8 * fq; float ba[8], bg[8];
; #pragma unroll
;         for (int h = 0; h < 2; ++h) { const f32x4 a = *(const f32x4*)(bb + 4 * h), g = *(const f32x4*)(bb + 128 + 4 * h);
; #pragma unroll
;             for (int i = 0; i < 4; ++i) { ba[4 * h + i] = a[i]; bg[4 * h + i] = g[i]; } }
; #pragma unroll
;         for (int ai = 0; ai < 2; ++ai)
; #pragma unroll
;             for (int m = 0; m < 4; ++m) { ACC8(va, ai, 0, m); ACC8(vb, ai, 1, m); const int row = u.pm * 256 + ai * 128 + wr * 64 + m * 16 + fr; const float rstd = row_rstd(SSQ, row); float o[8];
; #pragma unroll
;                 for (int i = 0; i < 8; ++i) o[i] = siluf_(rstd * va[i] + ba[i]) * (rstd * vb[i] + bg[i]);
;                 *(u32x4*)(e.ACT + (size_t)row * FF + c0) = pack8(o); }
;     }
.LBB9_773:
	v_lshl_add_u32 v164, s24, 8, v166
	v_ashrrev_i32_e32 v165, 31, v164
	s_ashr_i32 s2, s24, 4
	v_lshl_add_u64 v[88:89], v[164:165], 4, s[8:9]
	s_mul_hi_i32 s3, s2, 0x5800
	s_mulk_i32 s2, 0x5800
	global_load_dwordx4 v[174:177], v[88:89], off
	global_load_dwordx4 v[192:195], v[88:89], off offset:256
	global_load_dwordx4 v[196:199], v[88:89], off offset:512
	global_load_dwordx4 v[200:203], v[88:89], off offset:768
	global_load_dwordx4 v[210:213], v[88:89], off offset:2048
	global_load_dwordx4 v[214:217], v[88:89], off offset:2304
	global_load_dwordx4 v[218:221], v[88:89], off offset:2560
	global_load_dwordx4 v[238:241], v[88:89], off offset:2816
	s_add_u32 s17, s44, s2
	s_addc_u32 s19, s45, s3
	s_lshl_b32 s2, s54, 8
	s_ashr_i32 s3, s2, 31
	s_lshl_b64 s[2:3], s[2:3], 2
	s_add_u32 s2, s17, s2
	s_addc_u32 s3, s19, s3
	s_add_u32 s2, s2, s52
	s_addc_u32 s3, s3, 0
	global_load_dwordx4 v[96:99], v172, s[2:3]
	global_load_dwordx4 v[100:103], v172, s[2:3] offset:512
	global_load_dwordx4 v[88:91], v172, s[2:3] offset:16
	global_load_dwordx4 v[92:95], v172, s[2:3] offset:528
	v_lshl_or_b32 v162, s54, 7, v168
	v_mov_b64_e32 v[160:161], s[10:11]
	v_ashrrev_i32_e32 v163, 31, v162
	v_or_b32_e32 v180, 16, v164
	v_mad_i64_i32 v[178:179], s[2:3], v164, s53, v[160:161]
	v_lshlrev_b64 v[162:163], 1, v[162:163]
	v_ashrrev_i32_e32 v181, 31, v180
	s_andn2_b64 vcc, exec, s[0:1]
	s_mov_b64 s[0:1], -1
	s_waitcnt vmcnt(0)
	v_mov_b32_e32 v182, v175
	v_mov_b32_e32 v183, v176
	v_mov_b32_e32 v175, v177
	v_pk_add_f32 v[174:175], v[182:183], v[174:175]
	v_lshl_add_u64 v[176:177], v[178:179], 0, v[162:163]
	v_add_f32_e32 v165, v174, v175
	v_fmamk_f32 v165, v165, 0x3a800000, v173
	v_rsq_f32_e32 v174, v165
	v_lshl_add_u64 v[178:179], v[180:181], 4, s[8:9]
	v_pk_fma_f32 v[140:141], v[140:141], v[174:175], v[96:97] op_sel_hi:[1,0,1]
	v_pk_fma_f32 v[142:143], v[142:143], v[174:175], v[98:99] op_sel_hi:[1,0,1]
	v_pk_fma_f32 v[136:137], v[136:137], v[174:175], v[88:89] op_sel_hi:[1,0,1]
	v_pk_fma_f32 v[138:139], v[138:139], v[174:175], v[90:91] op_sel_hi:[1,0,1]
	v_pk_fma_f32 v[132:133], v[132:133], v[174:175], v[100:101] op_sel_hi:[1,0,1]
	v_pk_fma_f32 v[134:135], v[134:135], v[174:175], v[102:103] op_sel_hi:[1,0,1]
	v_pk_fma_f32 v[128:129], v[128:129], v[174:175], v[92:93] op_sel_hi:[1,0,1]
	v_pk_fma_f32 v[130:131], v[130:131], v[174:175], v[94:95] op_sel_hi:[1,0,1]
	v_mul_f32_e32 v165, 0xbfb8aa3b, v140
	v_mul_f32_e32 v174, 0xbfb8aa3b, v141
	v_mul_f32_e32 v175, 0xbfb8aa3b, v142
	v_mul_f32_e32 v181, 0xbfb8aa3b, v143
	v_mul_f32_e32 v182, 0xbfb8aa3b, v136
	v_mul_f32_e32 v183, 0xbfb8aa3b, v137
	v_mul_f32_e32 v184, 0xbfb8aa3b, v138
	v_mul_f32_e32 v185, 0xbfb8aa3b, v139
	v_exp_f32_e32 v165, v165
	v_exp_f32_e32 v174, v174
	v_exp_f32_e32 v175, v175
	v_exp_f32_e32 v181, v181
	v_exp_f32_e32 v182, v182
	v_exp_f32_e32 v183, v183
	v_exp_f32_e32 v184, v184
	v_exp_f32_e32 v185, v185
	v_add_f32_e32 v165, 1.0, v165
	v_add_f32_e32 v186, 1.0, v174
	v_add_f32_e32 v187, 1.0, v175
	v_add_f32_e32 v181, 1.0, v181
	v_add_f32_e32 v188, 1.0, v182
	v_add_f32_e32 v189, 1.0, v183
	v_add_f32_e32 v190, 1.0, v184
	v_add_f32_e32 v191, 1.0, v185
	v_rcp_f32_e32 v174, v165
	v_rcp_f32_e32 v175, v186
	v_rcp_f32_e32 v182, v187
	v_rcp_f32_e32 v183, v181
	v_rcp_f32_e32 v184, v188
	v_rcp_f32_e32 v185, v189
	v_rcp_f32_e32 v186, v190
	v_rcp_f32_e32 v187, v191
	v_pk_mul_f32 v[140:141], v[140:141], v[174:175]
	v_pk_mul_f32 v[142:143], v[142:143], v[182:183]
	v_pk_mul_f32 v[136:137], v[136:137], v[184:185]
	v_pk_mul_f32 v[138:139], v[138:139], v[186:187]
	v_pk_mul_f32 v[132:133], v[132:133], v[140:141]
	v_pk_mul_f32 v[134:135], v[134:135], v[142:143]
	v_pk_mul_f32 v[136:137], v[128:129], v[136:137]
	v_pk_mul_f32 v[138:139], v[130:131], v[138:139]
	v_cvt_pk_bf16_f32 v128, v132, v133
	v_cvt_pk_bf16_f32 v129, v134, v135
	v_cvt_pk_bf16_f32 v130, v136, v137
	v_cvt_pk_bf16_f32 v131, v138, v139
	global_store_dwordx4 v[176:177], v[128:131], off
	v_or_b32_e32 v132, 32, v164
	v_mad_i64_i32 v[134:135], s[2:3], v180, s53, v[160:161]
	v_ashrrev_i32_e32 v133, 31, v132
	s_nop 1
	v_mov_b32_e32 v128, v192
	v_mov_b32_e32 v129, v193
	v_mov_b32_e32 v130, v194
	v_mov_b32_e32 v131, v195
	v_mov_b32_e32 v136, v129
	v_mov_b32_e32 v137, v130
	v_mov_b32_e32 v129, v131
	v_pk_add_f32 v[128:129], v[136:137], v[128:129]
	v_lshl_add_u64 v[130:131], v[134:135], 0, v[162:163]
	v_add_f32_e32 v128, v128, v129
	v_fmamk_f32 v128, v128, 0x3a800000, v173
	v_rsq_f32_e32 v128, v128
	v_lshl_add_u64 v[134:135], v[132:133], 4, s[8:9]
	v_pk_fma_f32 v[124:125], v[124:125], v[128:129], v[96:97] op_sel_hi:[1,0,1]
	v_pk_fma_f32 v[126:127], v[126:127], v[128:129], v[98:99] op_sel_hi:[1,0,1]
	v_pk_fma_f32 v[120:121], v[120:121], v[128:129], v[88:89] op_sel_hi:[1,0,1]
	v_pk_fma_f32 v[122:123], v[122:123], v[128:129], v[90:91] op_sel_hi:[1,0,1]
	v_pk_fma_f32 v[116:117], v[116:117], v[128:129], v[100:101] op_sel_hi:[1,0,1]
	v_pk_fma_f32 v[118:119], v[118:119], v[128:129], v[102:103] op_sel_hi:[1,0,1]
	v_pk_fma_f32 v[112:113], v[112:113], v[128:129], v[92:93] op_sel_hi:[1,0,1]
	v_pk_fma_f32 v[114:115], v[114:115], v[128:129], v[94:95] op_sel_hi:[1,0,1]
	v_mul_f32_e32 v128, 0xbfb8aa3b, v124
	v_mul_f32_e32 v129, 0xbfb8aa3b, v125
	v_mul_f32_e32 v133, 0xbfb8aa3b, v126
	v_mul_f32_e32 v136, 0xbfb8aa3b, v127
	v_mul_f32_e32 v137, 0xbfb8aa3b, v120
	v_mul_f32_e32 v138, 0xbfb8aa3b, v121
	v_mul_f32_e32 v139, 0xbfb8aa3b, v122
	v_mul_f32_e32 v140, 0xbfb8aa3b, v123
	v_exp_f32_e32 v128, v128
	v_exp_f32_e32 v129, v129
	v_exp_f32_e32 v133, v133
	v_exp_f32_e32 v136, v136
	v_exp_f32_e32 v137, v137
	v_exp_f32_e32 v138, v138
	v_exp_f32_e32 v139, v139
	v_exp_f32_e32 v140, v140
; __device__ __forceinline__ u32x4 pack8(const float (&v)[8]) { u32x4 w; w.x = cvtpk(v[0], v[1]); w.y = cvtpk(v[2], v[3]); w.z = cvtpk(v[4], v[5]); w.w = cvtpk(v[6], v[7]); return w; }
; __device__ __forceinline__ float siluf_(float v) { return v * __builtin_amdgcn_rcpf(1.0f + __builtin_amdgcn_exp2f(-LOG2E * v)); }
;     __device__ __forceinline__ void operator()(const pg8::f32x4 (&acc)[2][2][4][2], const pg8::Unit& u, int wr, int wc, int fr, int fq) const {
;     ...
;             for (int m = 0; m < 4; ++m) { ACC8(va, ai, 0, m); ACC8(vb, ai, 1, m); const int row = u.pm * 256 + ai * 128 + wr * 64 + m * 16 + fr; const float rstd = row_rstd(SSQ, row); float o[8];
; #pragma unroll
;                 for (int i = 0; i < 8; ++i) o[i] = siluf_(rstd * va[i] + ba[i]) * (rstd * vb[i] + bg[i]);
;                 *(u32x4*)(e.ACT + (size_t)row * FF + c0) = pack8(o); }
	v_add_f32_e32 v128, 1.0, v128
	v_add_f32_e32 v129, 1.0, v129
	v_add_f32_e32 v133, 1.0, v133
	v_add_f32_e32 v141, 1.0, v136
	v_add_f32_e32 v142, 1.0, v137
	v_add_f32_e32 v143, 1.0, v138
	v_add_f32_e32 v165, 1.0, v139
	v_add_f32_e32 v174, 1.0, v140
	v_rcp_f32_e32 v128, v128
	v_rcp_f32_e32 v129, v129
	v_rcp_f32_e32 v136, v133
	v_rcp_f32_e32 v137, v141
	v_rcp_f32_e32 v138, v142
	v_rcp_f32_e32 v139, v143
	v_rcp_f32_e32 v140, v165
	v_rcp_f32_e32 v141, v174
	v_pk_mul_f32 v[124:125], v[124:125], v[128:129]
	v_pk_mul_f32 v[126:127], v[126:127], v[136:137]
	v_pk_mul_f32 v[120:121], v[120:121], v[138:139]
	v_pk_mul_f32 v[122:123], v[122:123], v[140:141]
	v_pk_mul_f32 v[116:117], v[116:117], v[124:125]
	v_pk_mul_f32 v[118:119], v[118:119], v[126:127]
	v_pk_mul_f32 v[120:121], v[112:113], v[120:121]
	v_pk_mul_f32 v[122:123], v[114:115], v[122:123]
	v_cvt_pk_bf16_f32 v112, v116, v117
	v_cvt_pk_bf16_f32 v113, v118, v119
	v_cvt_pk_bf16_f32 v114, v120, v121
	v_cvt_pk_bf16_f32 v115, v122, v123
	global_store_dwordx4 v[130:131], v[112:115], off
	v_or_b32_e32 v116, 48, v164
	v_mad_i64_i32 v[118:119], s[2:3], v132, s53, v[160:161]
	v_ashrrev_i32_e32 v117, 31, v116
	s_nop 1
	v_mov_b32_e32 v112, v196
	v_mov_b32_e32 v113, v197
	v_mov_b32_e32 v114, v198
	v_mov_b32_e32 v115, v199
	v_mov_b32_e32 v120, v113
	v_mov_b32_e32 v121, v114
	v_mov_b32_e32 v113, v115
	v_pk_add_f32 v[112:113], v[120:121], v[112:113]
	v_lshl_add_u64 v[114:115], v[118:119], 0, v[162:163]
	v_add_f32_e32 v112, v112, v113
	v_fmamk_f32 v112, v112, 0x3a800000, v173
	v_rsq_f32_e32 v112, v112
	v_lshl_add_u64 v[118:119], v[116:117], 4, s[8:9]
	v_pk_fma_f32 v[108:109], v[108:109], v[112:113], v[96:97] op_sel_hi:[1,0,1]
	v_pk_fma_f32 v[110:111], v[110:111], v[112:113], v[98:99] op_sel_hi:[1,0,1]
	v_pk_fma_f32 v[104:105], v[104:105], v[112:113], v[88:89] op_sel_hi:[1,0,1]
	v_pk_fma_f32 v[106:107], v[106:107], v[112:113], v[90:91] op_sel_hi:[1,0,1]
	v_pk_fma_f32 v[84:85], v[84:85], v[112:113], v[100:101] op_sel_hi:[1,0,1]
	v_pk_fma_f32 v[86:87], v[86:87], v[112:113], v[102:103] op_sel_hi:[1,0,1]
	v_pk_fma_f32 v[80:81], v[80:81], v[112:113], v[92:93] op_sel_hi:[1,0,1]
	v_pk_fma_f32 v[82:83], v[82:83], v[112:113], v[94:95] op_sel_hi:[1,0,1]
	v_mul_f32_e32 v112, 0xbfb8aa3b, v108
	v_mul_f32_e32 v113, 0xbfb8aa3b, v109
	v_mul_f32_e32 v117, 0xbfb8aa3b, v110
	v_mul_f32_e32 v120, 0xbfb8aa3b, v111
	v_mul_f32_e32 v121, 0xbfb8aa3b, v104
	v_mul_f32_e32 v122, 0xbfb8aa3b, v105
	v_mul_f32_e32 v123, 0xbfb8aa3b, v106
	v_mul_f32_e32 v124, 0xbfb8aa3b, v107
	v_exp_f32_e32 v112, v112
	v_exp_f32_e32 v113, v113
	v_exp_f32_e32 v117, v117
	v_exp_f32_e32 v120, v120
	v_exp_f32_e32 v121, v121
	v_exp_f32_e32 v122, v122
	v_exp_f32_e32 v123, v123
	v_exp_f32_e32 v124, v124
	v_add_f32_e32 v112, 1.0, v112
	v_add_f32_e32 v113, 1.0, v113
	v_add_f32_e32 v117, 1.0, v117
	v_add_f32_e32 v125, 1.0, v120
	v_add_f32_e32 v126, 1.0, v121
	v_add_f32_e32 v127, 1.0, v122
	v_add_f32_e32 v128, 1.0, v123
	v_add_f32_e32 v129, 1.0, v124
	v_rcp_f32_e32 v112, v112
	v_rcp_f32_e32 v113, v113
	v_rcp_f32_e32 v120, v117
	v_rcp_f32_e32 v121, v125
	v_rcp_f32_e32 v122, v126
	v_rcp_f32_e32 v123, v127
	v_rcp_f32_e32 v124, v128
	v_rcp_f32_e32 v125, v129
	v_pk_mul_f32 v[108:109], v[108:109], v[112:113]
	v_pk_mul_f32 v[110:111], v[110:111], v[120:121]
	v_pk_mul_f32 v[104:105], v[104:105], v[122:123]
	v_pk_mul_f32 v[106:107], v[106:107], v[124:125]
	v_pk_mul_f32 v[84:85], v[84:85], v[108:109]
	v_pk_mul_f32 v[86:87], v[86:87], v[110:111]
	v_pk_mul_f32 v[104:105], v[80:81], v[104:105]
	v_pk_mul_f32 v[106:107], v[82:83], v[106:107]
	v_cvt_pk_bf16_f32 v80, v84, v85
	v_cvt_pk_bf16_f32 v81, v86, v87
	v_cvt_pk_bf16_f32 v82, v104, v105
	v_cvt_pk_bf16_f32 v83, v106, v107
	global_store_dwordx4 v[114:115], v[80:83], off
	v_add_u32_e32 v84, 0x80, v164
	v_mad_i64_i32 v[86:87], s[2:3], v116, s53, v[160:161]
	v_ashrrev_i32_e32 v85, 31, v84
	s_nop 1
	v_mov_b32_e32 v80, v200
	v_mov_b32_e32 v81, v201
	v_mov_b32_e32 v82, v202
	v_mov_b32_e32 v83, v203
	v_mov_b32_e32 v104, v81
	v_mov_b32_e32 v105, v82
	v_mov_b32_e32 v81, v83
	v_pk_add_f32 v[80:81], v[104:105], v[80:81]
	v_lshl_add_u64 v[82:83], v[86:87], 0, v[162:163]
	v_add_f32_e32 v80, v80, v81
	v_fmamk_f32 v80, v80, 0x3a800000, v173
	v_rsq_f32_e32 v80, v80
	v_lshl_add_u64 v[86:87], v[84:85], 4, s[8:9]
	v_pk_fma_f32 v[76:77], v[76:77], v[80:81], v[96:97] op_sel_hi:[1,0,1]
	v_pk_fma_f32 v[78:79], v[78:79], v[80:81], v[98:99] op_sel_hi:[1,0,1]
	v_pk_fma_f32 v[72:73], v[72:73], v[80:81], v[88:89] op_sel_hi:[1,0,1]
	v_pk_fma_f32 v[74:75], v[74:75], v[80:81], v[90:91] op_sel_hi:[1,0,1]
	v_pk_fma_f32 v[68:69], v[68:69], v[80:81], v[100:101] op_sel_hi:[1,0,1]
	v_pk_fma_f32 v[70:71], v[70:71], v[80:81], v[102:103] op_sel_hi:[1,0,1]
	v_pk_fma_f32 v[64:65], v[64:65], v[80:81], v[92:93] op_sel_hi:[1,0,1]
	v_pk_fma_f32 v[66:67], v[66:67], v[80:81], v[94:95] op_sel_hi:[1,0,1]
	v_mul_f32_e32 v80, 0xbfb8aa3b, v76
	v_mul_f32_e32 v81, 0xbfb8aa3b, v77
	v_mul_f32_e32 v85, 0xbfb8aa3b, v78
	v_mul_f32_e32 v104, 0xbfb8aa3b, v79
	v_mul_f32_e32 v105, 0xbfb8aa3b, v72
	v_mul_f32_e32 v106, 0xbfb8aa3b, v73
	v_mul_f32_e32 v107, 0xbfb8aa3b, v74
	v_mul_f32_e32 v108, 0xbfb8aa3b, v75
	v_exp_f32_e32 v80, v80
	v_exp_f32_e32 v81, v81
	v_exp_f32_e32 v85, v85
	v_exp_f32_e32 v104, v104
	v_exp_f32_e32 v105, v105
	v_exp_f32_e32 v106, v106
	v_exp_f32_e32 v107, v107
	v_exp_f32_e32 v108, v108
	v_add_f32_e32 v80, 1.0, v80
	v_add_f32_e32 v81, 1.0, v81
	v_add_f32_e32 v85, 1.0, v85
	v_add_f32_e32 v109, 1.0, v104
	v_add_f32_e32 v110, 1.0, v105
	v_add_f32_e32 v111, 1.0, v106
	v_add_f32_e32 v112, 1.0, v107
	v_add_f32_e32 v113, 1.0, v108
	v_rcp_f32_e32 v80, v80
	v_rcp_f32_e32 v81, v81
; __device__ __forceinline__ u32x4 pack8(const float (&v)[8]) { u32x4 w; w.x = cvtpk(v[0], v[1]); w.y = cvtpk(v[2], v[3]); w.z = cvtpk(v[4], v[5]); w.w = cvtpk(v[6], v[7]); return w; }
; __device__ __forceinline__ float siluf_(float v) { return v * __builtin_amdgcn_rcpf(1.0f + __builtin_amdgcn_exp2f(-LOG2E * v)); }
;     __device__ __forceinline__ void operator()(const pg8::f32x4 (&acc)[2][2][4][2], const pg8::Unit& u, int wr, int wc, int fr, int fq) const {
;     ...
;             for (int m = 0; m < 4; ++m) { ACC8(va, ai, 0, m); ACC8(vb, ai, 1, m); const int row = u.pm * 256 + ai * 128 + wr * 64 + m * 16 + fr; const float rstd = row_rstd(SSQ, row); float o[8];
; #pragma unroll
;                 for (int i = 0; i < 8; ++i) o[i] = siluf_(rstd * va[i] + ba[i]) * (rstd * vb[i] + bg[i]);
;                 *(u32x4*)(e.ACT + (size_t)row * FF + c0) = pack8(o); }
	v_rcp_f32_e32 v104, v85
	v_rcp_f32_e32 v105, v109
	v_rcp_f32_e32 v106, v110
	v_rcp_f32_e32 v107, v111
	v_rcp_f32_e32 v108, v112
	v_rcp_f32_e32 v109, v113
	v_pk_mul_f32 v[76:77], v[76:77], v[80:81]
	v_pk_mul_f32 v[78:79], v[78:79], v[104:105]
	v_pk_mul_f32 v[72:73], v[72:73], v[106:107]
	v_pk_mul_f32 v[74:75], v[74:75], v[108:109]
	v_pk_mul_f32 v[68:69], v[68:69], v[76:77]
	v_pk_mul_f32 v[70:71], v[70:71], v[78:79]
	v_pk_mul_f32 v[72:73], v[64:65], v[72:73]
	v_pk_mul_f32 v[74:75], v[66:67], v[74:75]
	v_cvt_pk_bf16_f32 v64, v68, v69
	v_cvt_pk_bf16_f32 v65, v70, v71
	v_cvt_pk_bf16_f32 v66, v72, v73
	v_cvt_pk_bf16_f32 v67, v74, v75
	global_store_dwordx4 v[82:83], v[64:67], off
	v_add_u32_e32 v68, 0x90, v164
	v_mad_i64_i32 v[70:71], s[2:3], v84, s53, v[160:161]
	v_ashrrev_i32_e32 v69, 31, v68
	s_nop 1
	v_mov_b32_e32 v64, v210
	v_mov_b32_e32 v65, v211
	v_mov_b32_e32 v66, v212
	v_mov_b32_e32 v67, v213
	v_mov_b32_e32 v72, v65
	v_mov_b32_e32 v73, v66
	v_mov_b32_e32 v65, v67
	v_pk_add_f32 v[64:65], v[72:73], v[64:65]
	v_lshl_add_u64 v[66:67], v[70:71], 0, v[162:163]
	v_add_f32_e32 v64, v64, v65
	v_fmamk_f32 v64, v64, 0x3a800000, v173
	v_rsq_f32_e32 v64, v64
	v_lshl_add_u64 v[70:71], v[68:69], 4, s[8:9]
	v_pk_fma_f32 v[60:61], v[60:61], v[64:65], v[96:97] op_sel_hi:[1,0,1]
	v_pk_fma_f32 v[62:63], v[62:63], v[64:65], v[98:99] op_sel_hi:[1,0,1]
	v_pk_fma_f32 v[56:57], v[56:57], v[64:65], v[88:89] op_sel_hi:[1,0,1]
	v_pk_fma_f32 v[58:59], v[58:59], v[64:65], v[90:91] op_sel_hi:[1,0,1]
	v_pk_fma_f32 v[52:53], v[52:53], v[64:65], v[100:101] op_sel_hi:[1,0,1]
	v_pk_fma_f32 v[54:55], v[54:55], v[64:65], v[102:103] op_sel_hi:[1,0,1]
	v_pk_fma_f32 v[48:49], v[48:49], v[64:65], v[92:93] op_sel_hi:[1,0,1]
	v_pk_fma_f32 v[50:51], v[50:51], v[64:65], v[94:95] op_sel_hi:[1,0,1]
	v_mul_f32_e32 v64, 0xbfb8aa3b, v60
	v_mul_f32_e32 v65, 0xbfb8aa3b, v61
	v_mul_f32_e32 v69, 0xbfb8aa3b, v62
	v_mul_f32_e32 v72, 0xbfb8aa3b, v63
	v_mul_f32_e32 v73, 0xbfb8aa3b, v56
	v_mul_f32_e32 v74, 0xbfb8aa3b, v57
	v_mul_f32_e32 v75, 0xbfb8aa3b, v58
	v_mul_f32_e32 v76, 0xbfb8aa3b, v59
	v_exp_f32_e32 v64, v64
	v_exp_f32_e32 v65, v65
	v_exp_f32_e32 v69, v69
	v_exp_f32_e32 v72, v72
	v_exp_f32_e32 v73, v73
	v_exp_f32_e32 v74, v74
	v_exp_f32_e32 v75, v75
	v_exp_f32_e32 v76, v76
	v_add_f32_e32 v64, 1.0, v64
	v_add_f32_e32 v65, 1.0, v65
	v_add_f32_e32 v69, 1.0, v69
	v_add_f32_e32 v77, 1.0, v72
	v_add_f32_e32 v78, 1.0, v73
	v_add_f32_e32 v79, 1.0, v74
	v_add_f32_e32 v80, 1.0, v75
	v_add_f32_e32 v81, 1.0, v76
	v_rcp_f32_e32 v64, v64
	v_rcp_f32_e32 v65, v65
	v_rcp_f32_e32 v72, v69
	v_rcp_f32_e32 v73, v77
	v_rcp_f32_e32 v74, v78
	v_rcp_f32_e32 v75, v79
	v_rcp_f32_e32 v76, v80
	v_rcp_f32_e32 v77, v81
	v_pk_mul_f32 v[60:61], v[60:61], v[64:65]
	v_pk_mul_f32 v[62:63], v[62:63], v[72:73]
	v_pk_mul_f32 v[56:57], v[56:57], v[74:75]
	v_pk_mul_f32 v[58:59], v[58:59], v[76:77]
	v_pk_mul_f32 v[52:53], v[52:53], v[60:61]
	v_pk_mul_f32 v[54:55], v[54:55], v[62:63]
	v_pk_mul_f32 v[56:57], v[48:49], v[56:57]
	v_pk_mul_f32 v[58:59], v[50:51], v[58:59]
	v_cvt_pk_bf16_f32 v48, v52, v53
	v_cvt_pk_bf16_f32 v49, v54, v55
	v_cvt_pk_bf16_f32 v50, v56, v57
	v_cvt_pk_bf16_f32 v51, v58, v59
	global_store_dwordx4 v[66:67], v[48:51], off
	v_add_u32_e32 v52, 0xa0, v164
	v_mad_i64_i32 v[54:55], s[2:3], v68, s53, v[160:161]
	v_ashrrev_i32_e32 v53, 31, v52
	s_nop 1
	v_mov_b32_e32 v48, v214
	v_mov_b32_e32 v49, v215
	v_mov_b32_e32 v50, v216
	v_mov_b32_e32 v51, v217
	v_mov_b32_e32 v56, v49
	v_mov_b32_e32 v57, v50
	v_mov_b32_e32 v49, v51
	v_pk_add_f32 v[48:49], v[56:57], v[48:49]
	v_lshl_add_u64 v[50:51], v[54:55], 0, v[162:163]
	v_add_f32_e32 v48, v48, v49
	v_fmamk_f32 v48, v48, 0x3a800000, v173
	v_rsq_f32_e32 v48, v48
	v_lshl_add_u64 v[54:55], v[52:53], 4, s[8:9]
	v_pk_fma_f32 v[44:45], v[44:45], v[48:49], v[96:97] op_sel_hi:[1,0,1]
	v_pk_fma_f32 v[46:47], v[46:47], v[48:49], v[98:99] op_sel_hi:[1,0,1]
	v_pk_fma_f32 v[40:41], v[40:41], v[48:49], v[88:89] op_sel_hi:[1,0,1]
	v_pk_fma_f32 v[42:43], v[42:43], v[48:49], v[90:91] op_sel_hi:[1,0,1]
	v_pk_fma_f32 v[36:37], v[36:37], v[48:49], v[100:101] op_sel_hi:[1,0,1]
	v_pk_fma_f32 v[38:39], v[38:39], v[48:49], v[102:103] op_sel_hi:[1,0,1]
	v_pk_fma_f32 v[32:33], v[32:33], v[48:49], v[92:93] op_sel_hi:[1,0,1]
	v_pk_fma_f32 v[34:35], v[34:35], v[48:49], v[94:95] op_sel_hi:[1,0,1]
	v_mul_f32_e32 v48, 0xbfb8aa3b, v44
	v_mul_f32_e32 v49, 0xbfb8aa3b, v45
	v_mul_f32_e32 v53, 0xbfb8aa3b, v46
	v_mul_f32_e32 v56, 0xbfb8aa3b, v47
	v_mul_f32_e32 v57, 0xbfb8aa3b, v40
	v_mul_f32_e32 v58, 0xbfb8aa3b, v41
	v_mul_f32_e32 v59, 0xbfb8aa3b, v42
	v_mul_f32_e32 v60, 0xbfb8aa3b, v43
	v_exp_f32_e32 v48, v48
	v_exp_f32_e32 v49, v49
	v_exp_f32_e32 v53, v53
	v_exp_f32_e32 v56, v56
	v_exp_f32_e32 v57, v57
	v_exp_f32_e32 v58, v58
	v_exp_f32_e32 v59, v59
	v_exp_f32_e32 v60, v60
	v_add_f32_e32 v48, 1.0, v48
	v_add_f32_e32 v49, 1.0, v49
	v_add_f32_e32 v53, 1.0, v53
	v_add_f32_e32 v61, 1.0, v56
	v_add_f32_e32 v62, 1.0, v57
	v_add_f32_e32 v63, 1.0, v58
	v_add_f32_e32 v64, 1.0, v59
	v_add_f32_e32 v65, 1.0, v60
	v_rcp_f32_e32 v48, v48
	v_rcp_f32_e32 v49, v49
	v_rcp_f32_e32 v56, v53
	v_rcp_f32_e32 v57, v61
	v_rcp_f32_e32 v58, v62
	v_rcp_f32_e32 v59, v63
	v_rcp_f32_e32 v60, v64
	v_rcp_f32_e32 v61, v65
	v_pk_mul_f32 v[44:45], v[44:45], v[48:49]
	v_pk_mul_f32 v[46:47], v[46:47], v[56:57]
	v_pk_mul_f32 v[40:41], v[40:41], v[58:59]
	v_pk_mul_f32 v[42:43], v[42:43], v[60:61]
; __device__ __forceinline__ u32x4 pack8(const float (&v)[8]) { u32x4 w; w.x = cvtpk(v[0], v[1]); w.y = cvtpk(v[2], v[3]); w.z = cvtpk(v[4], v[5]); w.w = cvtpk(v[6], v[7]); return w; }
; __device__ __forceinline__ float siluf_(float v) { return v * __builtin_amdgcn_rcpf(1.0f + __builtin_amdgcn_exp2f(-LOG2E * v)); }
;     __device__ __forceinline__ void operator()(const pg8::f32x4 (&acc)[2][2][4][2], const pg8::Unit& u, int wr, int wc, int fr, int fq) const {
;     ...
;             for (int m = 0; m < 4; ++m) { ACC8(va, ai, 0, m); ACC8(vb, ai, 1, m); const int row = u.pm * 256 + ai * 128 + wr * 64 + m * 16 + fr; const float rstd = row_rstd(SSQ, row); float o[8];
; #pragma unroll
;                 for (int i = 0; i < 8; ++i) o[i] = siluf_(rstd * va[i] + ba[i]) * (rstd * vb[i] + bg[i]);
;                 *(u32x4*)(e.ACT + (size_t)row * FF + c0) = pack8(o); }
	v_pk_mul_f32 v[36:37], v[36:37], v[44:45]
	v_pk_mul_f32 v[38:39], v[38:39], v[46:47]
	v_pk_mul_f32 v[40:41], v[32:33], v[40:41]
	v_pk_mul_f32 v[42:43], v[34:35], v[42:43]
	v_cvt_pk_bf16_f32 v32, v36, v37
	v_cvt_pk_bf16_f32 v33, v38, v39
	v_cvt_pk_bf16_f32 v34, v40, v41
	v_cvt_pk_bf16_f32 v35, v42, v43
	global_store_dwordx4 v[50:51], v[32:35], off
	v_add_u32_e32 v36, 0xb0, v164
	v_mad_i64_i32 v[38:39], s[2:3], v52, s53, v[160:161]
	v_ashrrev_i32_e32 v37, 31, v36
	s_nop 1
	v_mov_b32_e32 v32, v218
	v_mov_b32_e32 v33, v219
	v_mov_b32_e32 v34, v220
	v_mov_b32_e32 v35, v221
	v_mov_b32_e32 v40, v33
	v_mov_b32_e32 v41, v34
	v_mov_b32_e32 v33, v35
	v_pk_add_f32 v[32:33], v[40:41], v[32:33]
	v_lshl_add_u64 v[34:35], v[38:39], 0, v[162:163]
	v_add_f32_e32 v32, v32, v33
	v_fmamk_f32 v32, v32, 0x3a800000, v173
	v_rsq_f32_e32 v32, v32
	v_lshl_add_u64 v[38:39], v[36:37], 4, s[8:9]
	v_pk_fma_f32 v[28:29], v[28:29], v[32:33], v[96:97] op_sel_hi:[1,0,1]
	v_pk_fma_f32 v[30:31], v[30:31], v[32:33], v[98:99] op_sel_hi:[1,0,1]
	v_pk_fma_f32 v[24:25], v[24:25], v[32:33], v[88:89] op_sel_hi:[1,0,1]
	v_pk_fma_f32 v[26:27], v[26:27], v[32:33], v[90:91] op_sel_hi:[1,0,1]
	v_pk_fma_f32 v[20:21], v[20:21], v[32:33], v[100:101] op_sel_hi:[1,0,1]
	v_pk_fma_f32 v[22:23], v[22:23], v[32:33], v[102:103] op_sel_hi:[1,0,1]
	v_pk_fma_f32 v[16:17], v[16:17], v[32:33], v[92:93] op_sel_hi:[1,0,1]
	v_pk_fma_f32 v[18:19], v[18:19], v[32:33], v[94:95] op_sel_hi:[1,0,1]
	v_mul_f32_e32 v32, 0xbfb8aa3b, v28
	v_mul_f32_e32 v33, 0xbfb8aa3b, v29
	v_mul_f32_e32 v37, 0xbfb8aa3b, v30
	v_mul_f32_e32 v40, 0xbfb8aa3b, v31
	v_mul_f32_e32 v41, 0xbfb8aa3b, v24
	v_mul_f32_e32 v42, 0xbfb8aa3b, v25
	v_mul_f32_e32 v43, 0xbfb8aa3b, v26
	v_mul_f32_e32 v44, 0xbfb8aa3b, v27
	v_exp_f32_e32 v32, v32
	v_exp_f32_e32 v33, v33
	v_exp_f32_e32 v37, v37
	v_exp_f32_e32 v40, v40
	v_exp_f32_e32 v41, v41
	v_exp_f32_e32 v42, v42
	v_exp_f32_e32 v43, v43
	v_exp_f32_e32 v44, v44
	v_add_f32_e32 v32, 1.0, v32
	v_add_f32_e32 v33, 1.0, v33
	v_add_f32_e32 v37, 1.0, v37
	v_add_f32_e32 v45, 1.0, v40
	v_add_f32_e32 v46, 1.0, v41
	v_add_f32_e32 v47, 1.0, v42
	v_add_f32_e32 v48, 1.0, v43
	v_add_f32_e32 v49, 1.0, v44
	v_rcp_f32_e32 v32, v32
	v_rcp_f32_e32 v33, v33
	v_rcp_f32_e32 v40, v37
	v_rcp_f32_e32 v41, v45
	v_rcp_f32_e32 v42, v46
	v_rcp_f32_e32 v43, v47
	v_rcp_f32_e32 v44, v48
	v_rcp_f32_e32 v45, v49
	v_pk_mul_f32 v[28:29], v[28:29], v[32:33]
	v_pk_mul_f32 v[30:31], v[30:31], v[40:41]
	v_pk_mul_f32 v[24:25], v[24:25], v[42:43]
	v_pk_mul_f32 v[26:27], v[26:27], v[44:45]
	v_pk_mul_f32 v[20:21], v[20:21], v[28:29]
	v_pk_mul_f32 v[22:23], v[22:23], v[30:31]
	v_pk_mul_f32 v[24:25], v[16:17], v[24:25]
	v_pk_mul_f32 v[26:27], v[18:19], v[26:27]
	v_cvt_pk_bf16_f32 v16, v20, v21
	v_cvt_pk_bf16_f32 v17, v22, v23
	v_cvt_pk_bf16_f32 v18, v24, v25
	v_cvt_pk_bf16_f32 v19, v26, v27
	global_store_dwordx4 v[34:35], v[16:19], off
	s_nop 1
	v_mov_b32_e32 v16, v238
	v_mov_b32_e32 v17, v239
	v_mov_b32_e32 v18, v240
	v_mov_b32_e32 v19, v241
	v_mov_b32_e32 v20, v17
	v_mov_b32_e32 v21, v18
	v_mov_b32_e32 v17, v19
	v_pk_add_f32 v[16:17], v[20:21], v[16:17]
	v_mad_i64_i32 v[18:19], s[2:3], v36, s53, v[160:161]
	v_add_f32_e32 v16, v16, v17
	v_fmamk_f32 v16, v16, 0x3a800000, v173
	v_rsq_f32_e32 v16, v16
	v_lshl_add_u64 v[18:19], v[18:19], 0, v[162:163]
	v_pk_fma_f32 v[12:13], v[12:13], v[16:17], v[96:97] op_sel_hi:[1,0,1]
	v_pk_fma_f32 v[14:15], v[14:15], v[16:17], v[98:99] op_sel_hi:[1,0,1]
	v_pk_fma_f32 v[8:9], v[8:9], v[16:17], v[88:89] op_sel_hi:[1,0,1]
	v_pk_fma_f32 v[10:11], v[10:11], v[16:17], v[90:91] op_sel_hi:[1,0,1]
	v_pk_fma_f32 v[4:5], v[4:5], v[16:17], v[100:101] op_sel_hi:[1,0,1]
	v_pk_fma_f32 v[6:7], v[6:7], v[16:17], v[102:103] op_sel_hi:[1,0,1]
	v_pk_fma_f32 v[0:1], v[0:1], v[16:17], v[92:93] op_sel_hi:[1,0,1]
	v_pk_fma_f32 v[2:3], v[2:3], v[16:17], v[94:95] op_sel_hi:[1,0,1]
	v_mul_f32_e32 v16, 0xbfb8aa3b, v12
	v_mul_f32_e32 v17, 0xbfb8aa3b, v13
	v_mul_f32_e32 v20, 0xbfb8aa3b, v14
	v_mul_f32_e32 v21, 0xbfb8aa3b, v15
	v_mul_f32_e32 v22, 0xbfb8aa3b, v8
	v_mul_f32_e32 v23, 0xbfb8aa3b, v9
	v_mul_f32_e32 v24, 0xbfb8aa3b, v10
	v_mul_f32_e32 v25, 0xbfb8aa3b, v11
	v_exp_f32_e32 v16, v16
	v_exp_f32_e32 v17, v17
	v_exp_f32_e32 v20, v20
	v_exp_f32_e32 v21, v21
	v_exp_f32_e32 v22, v22
	v_exp_f32_e32 v23, v23
	v_exp_f32_e32 v24, v24
	v_exp_f32_e32 v25, v25
	v_add_f32_e32 v16, 1.0, v16
	v_add_f32_e32 v17, 1.0, v17
	v_add_f32_e32 v20, 1.0, v20
	v_add_f32_e32 v21, 1.0, v21
	v_add_f32_e32 v22, 1.0, v22
	v_add_f32_e32 v23, 1.0, v23
	v_add_f32_e32 v24, 1.0, v24
	v_add_f32_e32 v25, 1.0, v25
	v_rcp_f32_e32 v16, v16
	v_rcp_f32_e32 v17, v17
	v_rcp_f32_e32 v20, v20
	v_rcp_f32_e32 v21, v21
	v_rcp_f32_e32 v22, v22
	v_rcp_f32_e32 v23, v23
	v_rcp_f32_e32 v24, v24
	v_rcp_f32_e32 v25, v25
	v_pk_mul_f32 v[12:13], v[12:13], v[16:17]
	v_pk_mul_f32 v[14:15], v[14:15], v[20:21]
	v_pk_mul_f32 v[8:9], v[8:9], v[22:23]
	v_pk_mul_f32 v[10:11], v[10:11], v[24:25]
	v_pk_mul_f32 v[4:5], v[4:5], v[12:13]
	v_pk_mul_f32 v[6:7], v[6:7], v[14:15]
	v_pk_mul_f32 v[8:9], v[0:1], v[8:9]
	v_pk_mul_f32 v[10:11], v[2:3], v[10:11]
	v_cvt_pk_bf16_f32 v0, v4, v5
	v_cvt_pk_bf16_f32 v1, v6, v7
	v_cvt_pk_bf16_f32 v2, v8, v9
	v_cvt_pk_bf16_f32 v3, v10, v11
	global_store_dwordx4 v[18:19], v[0:3], off
	s_cbranch_vccnz .LBB9_766
	s_andn2_b64 vcc, exec, s[6:7]
	s_cbranch_vccnz .LBB9_765
	s_barrier
	s_branch .LBB9_765

; #define LAS __attribute__((address_space(3)))
; __global__ void __launch_bounds__(NTHR, 2) mk_fwd(MkArgs a) {
;     extern __shared__ __attribute__((aligned(16))) unsigned char lds_raw[];
;     LAS unsigned char* lds = (LAS unsigned char*)lds_raw;
;     cg::grid_group grid = cg::this_grid();
;     const Ptrs& P = a.P;
;     const int tid = threadIdx.x, lane = tid & 63, wave = __builtin_amdgcn_readfirstlane(tid >> 6), bx = blockIdx.x, G = gridDim.x;
	.amdhsa_kernel _Z6mk_fwd6MkArgs
		.amdhsa_group_segment_fixed_size 0
		.amdhsa_private_segment_fixed_size 0
		.amdhsa_kernarg_size 440
		.amdhsa_user_sgpr_count 2
		.amdhsa_user_sgpr_dispatch_ptr 0
		.amdhsa_user_sgpr_queue_ptr 0
		.amdhsa_user_sgpr_kernarg_segment_ptr 1
		.amdhsa_user_sgpr_dispatch_id 0
		.amdhsa_user_sgpr_kernarg_preload_length 0
		.amdhsa_user_sgpr_kernarg_preload_offset 0
		.amdhsa_user_sgpr_private_segment_size 0
		.amdhsa_uses_dynamic_stack 0
		.amdhsa_enable_private_segment 0
		.amdhsa_system_sgpr_workgroup_id_x 1
		.amdhsa_system_sgpr_workgroup_id_y 0
		.amdhsa_system_sgpr_workgroup_id_z 0
		.amdhsa_system_sgpr_workgroup_info 0
		.amdhsa_system_vgpr_workitem_id 2
		.amdhsa_next_free_vgpr 256
		.amdhsa_next_free_sgpr 98
		.amdhsa_accum_offset 256
		.amdhsa_reserve_vcc 1
		.amdhsa_float_round_mode_32 0
		.amdhsa_float_round_mode_16_64 0
		.amdhsa_float_denorm_mode_32 3
		.amdhsa_float_denorm_mode_16_64 3
		.amdhsa_dx10_clamp 1
		.amdhsa_ieee_mode 1
		.amdhsa_fp16_overflow 0
		.amdhsa_tg_split 0
		.amdhsa_exception_fp_ieee_invalid_op 0
		.amdhsa_exception_fp_denorm_src 0
		.amdhsa_exception_fp_ieee_div_zero 0
		.amdhsa_exception_fp_ieee_overflow 0
		.amdhsa_exception_fp_ieee_underflow 0
		.amdhsa_exception_fp_ieee_inexact 0
		.amdhsa_exception_int_div_zero 0
	.end_amdhsa_kernel

; __device__ __forceinline__ unsigned f2bf(float f) { unsigned u = __float_as_uint(f); return (u + 0x7fffu + ((u >> 16) & 1u)) >> 16; }
; __device__ __forceinline__ float siluf_(float v) { return v * __builtin_amdgcn_rcpf(1.0f + __builtin_amdgcn_exp2f(-LOG2E * v)); }
; __global__ void k_transpose(const float* W, int K, int N, bf16_t* WT, int upmode) {
;     const size_t total = (size_t)K * N;
;     for (size_t idx = (size_t)blockIdx.x * blockDim.x + threadIdx.x; idx < total; idx += (size_t)gridDim.x * blockDim.x) {
;         const int np = (int)(idx / K), k = (int)(idx % K); const int n = upmode ? up_src_col(np) : np;
;         WT[idx] = (bf16_t)f2bf(W[(size_t)k * N + n]);
;     }
; }
; __global__ void k_mod(Ptrs P) {
;     const int idx = blockIdx.x * blockDim.x + threadIdx.x; if (idx >= 5 * NMOD) return;
;     const int r = idx / NMOD, n = idx % NMOD; const float* cv = r < 4 ? P.c + (size_t)r * DM : P.c_ctx; float s = 0.f;
;     for (int k = 0; k < DM; ++k) s += siluf_(cv[k]) * P.mod_w[(size_t)k * NMOD + n];
;     ((float*)(P.ws + WS_MOD))[idx] = s + P.mod_b[n];
; }
; __global__ void k_rows(Ptrs P) {
;     const int gw = (blockIdx.x * blockDim.x + threadIdx.x) >> 6, nw = (gridDim.x * blockDim.x) >> 6, lane = threadIdx.x & 63;
;     const float* mod = (const float*)(P.ws + WS_MOD); bf16_t* H = (bf16_t*)(P.ws + WS_H);
;     for (int m = gw; m < MTOK + MCTX; m += nw) {
;         const float* xr = m < MTOK ? P.x + (size_t)m * DM : P.ctx + (size_t)(m - MTOK) * DM; const float* mb = mod + (size_t)(m < MTOK ? (m >> 12) : 4) * NMOD;
;         h_row(xr, P.n1g, mb, mb + DM, H + (size_t)m * DM, lane);
;     }
;     for (int np = gw; np < NUP; np += nw) bias2_row((const bf16_t*)(P.ws + WS_WUP) + (size_t)np * DM, mod, (float*)(P.ws + WS_B2), np, lane);
; }
amdhsa.kernels:
  - .agpr_count:     0
    .args:
      - .address_space:  global
        .offset:         0
        .size:           8
        .value_kind:     global_buffer
      - .offset:         8
        .size:           4
        .value_kind:     by_value
      - .offset:         12
        .size:           4
        .value_kind:     by_value
      - .address_space:  global
        .offset:         16
        .size:           8
        .value_kind:     global_buffer
      - .offset:         24
        .size:           4
        .value_kind:     by_value
      - .offset:         32
        .size:           4
        .value_kind:     hidden_block_count_x
      - .offset:         36
        .size:           4
        .value_kind:     hidden_block_count_y
      - .offset:         40
        .size:           4
        .value_kind:     hidden_block_count_z
      - .offset:         44
        .size:           2
        .value_kind:     hidden_group_size_x
      - .offset:         46
        .size:           2
        .value_kind:     hidden_group_size_y
      - .offset:         48
        .size:           2
        .value_kind:     hidden_group_size_z
      - .offset:         50
        .size:           2
        .value_kind:     hidden_remainder_x
      - .offset:         52
        .size:           2
        .value_kind:     hidden_remainder_y
      - .offset:         54
        .size:           2
        .value_kind:     hidden_remainder_z
      - .offset:         72
        .size:           8
        .value_kind:     hidden_global_offset_x
      - .offset:         80
        .size:           8
        .value_kind:     hidden_global_offset_y
      - .offset:         88
        .size:           8
        .value_kind:     hidden_global_offset_z
      - .offset:         96
        .size:           2
        .value_kind:     hidden_grid_dims
    .group_segment_fixed_size: 0
    .kernarg_segment_align: 8
    .kernarg_segment_size: 288
    .language:       OpenCL C
    .language_version:
      - 2
      - 0
    .max_flat_workgroup_size: 1024
    .name:           _Z11k_transposePKfiiPti
    .private_segment_fixed_size: 0
    .sgpr_count:     36
    .sgpr_spill_count: 0
    .symbol:         _Z11k_transposePKfiiPti.kd
    .uniform_work_group_size: 1
    .uses_dynamic_stack: false
    .vgpr_count:     17
    .vgpr_spill_count: 0
    .wavefront_size: 64
  - .agpr_count:     0
    .args:
      - .offset:         0
        .size:           176
        .value_kind:     by_value
      - .offset:         176
        .size:           4
        .value_kind:     hidden_block_count_x
      - .offset:         180
        .size:           4
        .value_kind:     hidden_block_count_y
      - .offset:         184
        .size:           4
        .value_kind:     hidden_block_count_z
      - .offset:         188
        .size:           2
        .value_kind:     hidden_group_size_x
      - .offset:         190
        .size:           2
        .value_kind:     hidden_group_size_y
      - .offset:         192
        .size:           2
        .value_kind:     hidden_group_size_z
      - .offset:         194
        .size:           2
        .value_kind:     hidden_remainder_x
      - .offset:         196
        .size:           2
        .value_kind:     hidden_remainder_y
      - .offset:         198
        .size:           2
        .value_kind:     hidden_remainder_z
      - .offset:         216
        .size:           8
        .value_kind:     hidden_global_offset_x
      - .offset:         224
        .size:           8
        .value_kind:     hidden_global_offset_y
      - .offset:         232
        .size:           8
        .value_kind:     hidden_global_offset_z
      - .offset:         240
        .size:           2
        .value_kind:     hidden_grid_dims
    .group_segment_fixed_size: 0
    .kernarg_segment_align: 8
    .kernarg_segment_size: 432
    .language:       OpenCL C
    .language_version:
      - 2
      - 0
    .max_flat_workgroup_size: 1024
    .name:           _Z5k_mod4Ptrs
    .private_segment_fixed_size: 0
    .sgpr_count:     18
    .sgpr_spill_count: 0
    .symbol:         _Z5k_mod4Ptrs.kd
    .uniform_work_group_size: 1
    .uses_dynamic_stack: false
    .vgpr_count:     20
    .vgpr_spill_count: 0
    .wavefront_size: 64
  - .agpr_count:     0
    .args:
      - .offset:         0
        .size:           176
        .value_kind:     by_value
      - .offset:         176
        .size:           4
        .value_kind:     hidden_block_count_x
      - .offset:         180
        .size:           4
        .value_kind:     hidden_block_count_y
      - .offset:         184
        .size:           4
        .value_kind:     hidden_block_count_z
      - .offset:         188
        .size:           2
        .value_kind:     hidden_group_size_x
      - .offset:         190
        .size:           2
        .value_kind:     hidden_group_size_y
      - .offset:         192
        .size:           2
        .value_kind:     hidden_group_size_z
      - .offset:         194
        .size:           2
        .value_kind:     hidden_remainder_x
      - .offset:         196
        .size:           2
        .value_kind:     hidden_remainder_y
      - .offset:         198
        .size:           2
        .value_kind:     hidden_remainder_z
      - .offset:         216
        .size:           8
        .value_kind:     hidden_global_offset_x
      - .offset:         224
        .size:           8
        .value_kind:     hidden_global_offset_y
      - .offset:         232
        .size:           8
        .value_kind:     hidden_global_offset_z
      - .offset:         240
        .size:           2
        .value_kind:     hidden_grid_dims
    .group_segment_fixed_size: 0
    .kernarg_segment_align: 8
    .kernarg_segment_size: 432
    .language:       OpenCL C
    .language_version:
      - 2
      - 0
    .max_flat_workgroup_size: 1024
    .name:           _Z6k_rows4Ptrs
    .private_segment_fixed_size: 0
    .sgpr_count:     30
    .sgpr_spill_count: 0
    .symbol:         _Z6k_rows4Ptrs.kd
    .uniform_work_group_size: 1
    .uses_dynamic_stack: false
    .vgpr_count:     70
    .vgpr_spill_count: 0
    .wavefront_size: 64
; __global__ void k_gemm_out(const bf16_t* A, const bf16_t* Bt, EpiOut E) {
;     const int gw = (blockIdx.x * blockDim.x + threadIdx.x) >> 6, lane = threadIdx.x & 63, nrb = MTOK / 64;
;     if (gw >= nrb * (DM / 8)) return;
;     const int row = (gw % nrb) * 64 + lane, c0 = (gw / nrb) * 8;
;     float acc[8];
; #pragma unroll
;     for (int j = 0; j < 8; ++j) acc[j] = 0.f;
;     for (int k0 = 0; k0 < DM; k0 += 8) {
;         float a[8]; unpack8(*(const u32x4*)(A + (size_t)row * DM + k0), a);
; #pragma unroll
;         for (int j = 0; j < 8; ++j) { float b[8]; unpack8(*(const u32x4*)(Bt + (size_t)(c0 + j) * DM + k0), b);
; #pragma unroll
;             for (int i = 0; i < 8; ++i) acc[j] += a[i] * b[i]; }
;     }
;     (void)E(row, c0, acc);
; }
; __global__ void k_ssq(const float* out, float* SSQ) {
;     const int idx = blockIdx.x * blockDim.x + threadIdx.x; if (idx >= MTOK * 4) return;
;     const float* p = out + (size_t)(idx >> 2) * DM + (idx & 3) * 256; float s = 0.f;
;     for (int i = 0; i < 256; ++i) s += p[i] * p[i];
;     SSQ[idx] = s;
; }
; __global__ void k_gemm_up(const bf16_t* A, const bf16_t* Bt, const float* SSQ, EpiUp E) {
;     const int gw = (blockIdx.x * blockDim.x + threadIdx.x) >> 6, lane = threadIdx.x & 63, nrb = MTOK / 64;
;     if (gw >= nrb * (FF / 8)) return;
;     const int row = (gw % nrb) * 64 + lane, c0 = (gw / nrb) * 8, np = ((c0 >> 7) << 8) + (c0 & 127);
;     float aa[8], ab[8];
; #pragma unroll
;     for (int j = 0; j < 8; ++j) { aa[j] = 0.f; ab[j] = 0.f; }
;     for (int k0 = 0; k0 < DM; k0 += 8) {
;         float a[8]; unpack8(*(const u32x4*)(A + (size_t)row * DM + k0), a);
; #pragma unroll
;         for (int j = 0; j < 8; ++j) { float b[8]; unpack8(*(const u32x4*)(Bt + (size_t)(np + j) * DM + k0), b);
; #pragma unroll
;             for (int i = 0; i < 8; ++i) aa[j] += a[i] * b[i];
;             unpack8(*(const u32x4*)(Bt + (size_t)(np + 128 + j) * DM + k0), b);
; #pragma unroll
;             for (int i = 0; i < 8; ++i) ab[j] += a[i] * b[i]; }
;     }
;     E(row, c0, row_rstd(SSQ, row), aa, ab);
; }
  - .agpr_count:     0
    .args:
      - .address_space:  global
        .offset:         0
        .size:           8
        .value_kind:     global_buffer
      - .address_space:  global
        .offset:         8
        .size:           8
        .value_kind:     global_buffer
      - .offset:         16
        .size:           40
        .value_kind:     by_value
      - .offset:         56
        .size:           4
        .value_kind:     hidden_block_count_x
      - .offset:         60
        .size:           4
        .value_kind:     hidden_block_count_y
      - .offset:         64
        .size:           4
        .value_kind:     hidden_block_count_z
      - .offset:         68
        .size:           2
        .value_kind:     hidden_group_size_x
      - .offset:         70
        .size:           2
        .value_kind:     hidden_group_size_y
      - .offset:         72
        .size:           2
        .value_kind:     hidden_group_size_z
      - .offset:         74
        .size:           2
        .value_kind:     hidden_remainder_x
      - .offset:         76
        .size:           2
        .value_kind:     hidden_remainder_y
      - .offset:         78
        .size:           2
        .value_kind:     hidden_remainder_z
      - .offset:         96
        .size:           8
        .value_kind:     hidden_global_offset_x
      - .offset:         104
        .size:           8
        .value_kind:     hidden_global_offset_y
      - .offset:         112
        .size:           8
        .value_kind:     hidden_global_offset_z
      - .offset:         120
        .size:           2
        .value_kind:     hidden_grid_dims
    .group_segment_fixed_size: 0
    .kernarg_segment_align: 8
    .kernarg_segment_size: 312
    .language:       OpenCL C
    .language_version:
      - 2
      - 0
    .max_flat_workgroup_size: 1024
    .name:           _Z10k_gemm_outPKtS0_6EpiOut
    .private_segment_fixed_size: 0
    .sgpr_count:     26
    .sgpr_spill_count: 0
    .symbol:         _Z10k_gemm_outPKtS0_6EpiOut.kd
    .uniform_work_group_size: 1
    .uses_dynamic_stack: false
    .vgpr_count:     100
    .vgpr_spill_count: 0
    .wavefront_size: 64
  - .agpr_count:     0
    .args:
      - .address_space:  global
        .offset:         0
        .size:           8
        .value_kind:     global_buffer
      - .address_space:  global
        .offset:         8
        .size:           8
        .value_kind:     global_buffer
      - .offset:         16
        .size:           4
        .value_kind:     hidden_block_count_x
      - .offset:         20
        .size:           4
        .value_kind:     hidden_block_count_y
      - .offset:         24
        .size:           4
        .value_kind:     hidden_block_count_z
      - .offset:         28
        .size:           2
        .value_kind:     hidden_group_size_x
      - .offset:         30
        .size:           2
        .value_kind:     hidden_group_size_y
      - .offset:         32
        .size:           2
        .value_kind:     hidden_group_size_z
      - .offset:         34
        .size:           2
        .value_kind:     hidden_remainder_x
      - .offset:         36
        .size:           2
        .value_kind:     hidden_remainder_y
      - .offset:         38
        .size:           2
        .value_kind:     hidden_remainder_z
      - .offset:         56
        .size:           8
        .value_kind:     hidden_global_offset_x
      - .offset:         64
        .size:           8
        .value_kind:     hidden_global_offset_y
      - .offset:         72
        .size:           8
        .value_kind:     hidden_global_offset_z
      - .offset:         80
        .size:           2
        .value_kind:     hidden_grid_dims
    .group_segment_fixed_size: 0
    .kernarg_segment_align: 8
    .kernarg_segment_size: 272
    .language:       OpenCL C
    .language_version:
      - 2
      - 0
    .max_flat_workgroup_size: 1024
    .name:           _Z5k_ssqPKfPf
    .private_segment_fixed_size: 0
    .sgpr_count:     10
    .sgpr_spill_count: 0
    .symbol:         _Z5k_ssqPKfPf.kd
    .uniform_work_group_size: 1
    .uses_dynamic_stack: false
    .vgpr_count:     24
    .vgpr_spill_count: 0
    .wavefront_size: 64
  - .agpr_count:     0
    .args:
      - .address_space:  global
        .offset:         0
        .size:           8
        .value_kind:     global_buffer
      - .address_space:  global
        .offset:         8
        .size:           8
        .value_kind:     global_buffer
      - .address_space:  global
        .offset:         16
        .size:           8
        .value_kind:     global_buffer
      - .offset:         24
        .size:           16
        .value_kind:     by_value
      - .offset:         40
        .size:           4
        .value_kind:     hidden_block_count_x
      - .offset:         44
        .size:           4
        .value_kind:     hidden_block_count_y
      - .offset:         48
        .size:           4
        .value_kind:     hidden_block_count_z
      - .offset:         52
        .size:           2
        .value_kind:     hidden_group_size_x
      - .offset:         54
        .size:           2
        .value_kind:     hidden_group_size_y
      - .offset:         56
        .size:           2
        .value_kind:     hidden_group_size_z
      - .offset:         58
        .size:           2
        .value_kind:     hidden_remainder_x
      - .offset:         60
        .size:           2
        .value_kind:     hidden_remainder_y
      - .offset:         62
        .size:           2
        .value_kind:     hidden_remainder_z
      - .offset:         80
        .size:           8
        .value_kind:     hidden_global_offset_x
      - .offset:         88
        .size:           8
        .value_kind:     hidden_global_offset_y
      - .offset:         96
        .size:           8
        .value_kind:     hidden_global_offset_z
      - .offset:         104
        .size:           2
        .value_kind:     hidden_grid_dims
    .group_segment_fixed_size: 0
    .kernarg_segment_align: 8
    .kernarg_segment_size: 296
    .language:       OpenCL C
    .language_version:
      - 2
      - 0
    .max_flat_workgroup_size: 1024
    .name:           _Z9k_gemm_upPKtS0_PKf5EpiUp
    .private_segment_fixed_size: 0
    .sgpr_count:     22
    .sgpr_spill_count: 0
    .symbol:         _Z9k_gemm_upPKtS0_PKf5EpiUp.kd
    .uniform_work_group_size: 1
    .uses_dynamic_stack: false
    .vgpr_count:     68
    .vgpr_spill_count: 0
    .wavefront_size: 64
; __global__ void __launch_bounds__(256) k_qk(Ptrs P, int ctxmode) {
;     const int gw = (blockIdx.x * blockDim.x + threadIdx.x) >> 6, lane = threadIdx.x & 63;
;     const int nrows = ctxmode ? MCTX : MTOK, nrb = nrows / 64, nheads = ctxmode ? 4 : 20;
;     if (gw >= nrb * nheads) return;
;     const int row = (gw % nrb) * 64 + lane, hh = gw / nrb;
;     const bool isq = !ctxmode && hh < 16; const int wtile = (ctxmode || hh >= 16) ? 4 : hh >> 2, whd = hh & 3;
;     const bf16_t* A = (const bf16_t*)(P.ws + WS_H) + (size_t)(ctxmode ? MTOK + row : row) * DM; const bf16_t* Bt = (const bf16_t*)(P.ws + WS_WIN);
;     float acc[64];
; __global__ void __launch_bounds__(256) k_attn(Ptrs P) {
;     const int gw = (blockIdx.x * blockDim.x + threadIdx.x) >> 6, lane = threadIdx.x & 63, nrb = MTOK / 64;
;     if (gw >= nrb * 16) return;
;     const int row = (gw % nrb) * 64 + lane, h = gw / nrb, kh = h >> 2, b = row >> 12, t = row & 4095;
;     bf16_t* Qp = (bf16_t*)(P.ws + WS_Q) + (size_t)row * DM + h * 64;
;     const bf16_t* Kb = (const bf16_t*)(P.ws + WS_K) + (size_t)b * SEQ * KVW + kh * 64; const bf16_t* Vb = (const bf16_t*)(P.ws + WS_VT) + (size_t)(b * 4 + kh) * 64 * SEQ;
;     const bf16_t* Kc = (const bf16_t*)(P.ws + WS_KC) + (size_t)b * CTX * KVW + kh * 64; const bf16_t* Vc = (const bf16_t*)(P.ws + WS_VCT) + (size_t)(b * 4 + kh) * 64 * CTX;
;     float q[64], o[64];
; #pragma unroll
;     for (int j = 0; j < 64; j += 8) { float tq[8]; unpack8(*(const u32x4*)(Qp + j), tq);
; #pragma unroll
;         for (int i = 0; i < 8; ++i) { q[j + i] = tq[i]; o[j + i] = 0.f; } }
;     const float sink2 = P.sink[h] * LOG2E; float m = sink2;
;     const int jlo = t - 128 < 0 ? 0 : t - 128, jhi = t + 128 > SEQ - 1 ? SEQ - 1 : t + 128;
;     for (int pass = 0; pass < 2; ++pass) {
;         float den = 0.f;
;         for (int kk = jlo; kk <= jhi + CTX; ++kk) {
;             const bool isc = kk > jhi; const int j = isc ? kk - jhi - 1 : kk; const bf16_t* kp = isc ? Kc + (size_t)j * KVW : Kb + (size_t)j * KVW;
;             float s = 0.f;
; #pragma unroll
;             for (int d8 = 0; d8 < 64; d8 += 8) { float kv[8]; unpack8(*(const u32x4*)(kp + d8), kv);
; #pragma unroll
;                 for (int i = 0; i < 8; ++i) s += q[d8 + i] * kv[i]; }
;             if (pass == 0) m = fmaxf(m, s);
  - .agpr_count:     0
    .args:
      - .offset:         0
        .size:           176
        .value_kind:     by_value
      - .offset:         176
        .size:           4
        .value_kind:     by_value
      - .offset:         184
        .size:           4
        .value_kind:     hidden_block_count_x
      - .offset:         188
        .size:           4
        .value_kind:     hidden_block_count_y
      - .offset:         192
        .size:           4
        .value_kind:     hidden_block_count_z
      - .offset:         196
        .size:           2
        .value_kind:     hidden_group_size_x
      - .offset:         198
        .size:           2
        .value_kind:     hidden_group_size_y
      - .offset:         200
        .size:           2
        .value_kind:     hidden_group_size_z
      - .offset:         202
        .size:           2
        .value_kind:     hidden_remainder_x
      - .offset:         204
        .size:           2
        .value_kind:     hidden_remainder_y
      - .offset:         206
        .size:           2
        .value_kind:     hidden_remainder_z
      - .offset:         224
        .size:           8
        .value_kind:     hidden_global_offset_x
      - .offset:         232
        .size:           8
        .value_kind:     hidden_global_offset_y
      - .offset:         240
        .size:           8
        .value_kind:     hidden_global_offset_z
      - .offset:         248
        .size:           2
        .value_kind:     hidden_grid_dims
    .group_segment_fixed_size: 0
    .kernarg_segment_align: 8
    .kernarg_segment_size: 440
    .language:       OpenCL C
    .language_version:
      - 2
      - 0
    .max_flat_workgroup_size: 256
    .name:           _Z4k_qk4Ptrsi
    .private_segment_fixed_size: 0
    .sgpr_count:     37
    .sgpr_spill_count: 0
    .symbol:         _Z4k_qk4Ptrsi.kd
    .uniform_work_group_size: 1
    .uses_dynamic_stack: false
    .vgpr_count:     214
    .vgpr_spill_count: 0
    .wavefront_size: 64
  - .agpr_count:     0
    .args:
      - .offset:         0
        .size:           176
        .value_kind:     by_value
      - .offset:         176
        .size:           4
        .value_kind:     hidden_block_count_x
      - .offset:         180
        .size:           4
        .value_kind:     hidden_block_count_y
      - .offset:         184
        .size:           4
        .value_kind:     hidden_block_count_z
      - .offset:         188
        .size:           2
        .value_kind:     hidden_group_size_x
      - .offset:         190
        .size:           2
        .value_kind:     hidden_group_size_y
      - .offset:         192
        .size:           2
        .value_kind:     hidden_group_size_z
      - .offset:         194
        .size:           2
        .value_kind:     hidden_remainder_x
      - .offset:         196
        .size:           2
        .value_kind:     hidden_remainder_y
      - .offset:         198
        .size:           2
        .value_kind:     hidden_remainder_z
      - .offset:         216
        .size:           8
        .value_kind:     hidden_global_offset_x
      - .offset:         224
        .size:           8
        .value_kind:     hidden_global_offset_y
      - .offset:         232
        .size:           8
        .value_kind:     hidden_global_offset_z
      - .offset:         240
        .size:           2
        .value_kind:     hidden_grid_dims
    .group_segment_fixed_size: 0
    .kernarg_segment_align: 8
    .kernarg_segment_size: 432
    .language:       OpenCL C
    .language_version:
      - 2
      - 0
    .max_flat_workgroup_size: 256
    .name:           _Z6k_attn4Ptrs
    .private_segment_fixed_size: 0
    .sgpr_count:     23
    .sgpr_spill_count: 0
    .symbol:         _Z6k_attn4Ptrs.kd
    .uniform_work_group_size: 1
    .uses_dynamic_stack: false
    .vgpr_count:     254
    .vgpr_spill_count: 0
    .wavefront_size: 64
  - .agpr_count:     0
    .args:
      - .address_space:  global
        .offset:         0
        .size:           8
        .value_kind:     global_buffer
      - .address_space:  global
        .offset:         8
        .size:           8
        .value_kind:     global_buffer
      - .offset:         16
        .size:           4
        .value_kind:     hidden_block_count_x
      - .offset:         20
        .size:           4
        .value_kind:     hidden_block_count_y
      - .offset:         24
        .size:           4
        .value_kind:     hidden_block_count_z
      - .offset:         28
        .size:           2
        .value_kind:     hidden_group_size_x
      - .offset:         30
        .size:           2
        .value_kind:     hidden_group_size_y
      - .offset:         32
        .size:           2
        .value_kind:     hidden_group_size_z
      - .offset:         34
        .size:           2
        .value_kind:     hidden_remainder_x
      - .offset:         36
        .size:           2
        .value_kind:     hidden_remainder_y
      - .offset:         38
        .size:           2
        .value_kind:     hidden_remainder_z
      - .offset:         56
        .size:           8
        .value_kind:     hidden_global_offset_x
      - .offset:         64
        .size:           8
        .value_kind:     hidden_global_offset_y
      - .offset:         72
        .size:           8
        .value_kind:     hidden_global_offset_z
      - .offset:         80
        .size:           2
        .value_kind:     hidden_grid_dims
    .group_segment_fixed_size: 0
    .kernarg_segment_align: 8
    .kernarg_segment_size: 272
    .language:       OpenCL C
    .language_version:
      - 2
      - 0
    .max_flat_workgroup_size: 1024
    .name:           _Z6k_diffPKtPt
    .private_segment_fixed_size: 0
    .sgpr_count:     16
    .sgpr_spill_count: 0
    .symbol:         _Z6k_diffPKtPt.kd
    .uniform_work_group_size: 1
    .uses_dynamic_stack: false
    .vgpr_count:     10
    .vgpr_spill_count: 0
    .wavefront_size: 64
; #define LAS __attribute__((address_space(3)))
; template <class Epi> __global__ void k_gemm(const bf16_t* A, int lda, const bf16_t* Bt, int ldb, int Mrows, int N, int K, int col_off, Epi E) {
;     const int gw = (blockIdx.x * blockDim.x + threadIdx.x) >> 6, lane = threadIdx.x & 63, nrb = Mrows / 64;
;     if (gw >= nrb * (N / 8)) return;
;     const int row = (gw % nrb) * 64 + lane, c0 = (gw / nrb) * 8;
;     float acc[8];
; #pragma unroll
;     for (int j = 0; j < 8; ++j) acc[j] = 0.f;
;     for (int k0 = 0; k0 < K; k0 += 8) {
;         float a[8]; unpack8(*(const u32x4*)(A + (size_t)row * lda + k0), a);
; #pragma unroll
;         for (int j = 0; j < 8; ++j) { float b[8]; unpack8(*(const u32x4*)(Bt + (size_t)(c0 + j) * ldb + k0), b);
; #pragma unroll
;             for (int i = 0; i < 8; ++i) acc[j] += a[i] * b[i]; }
;     }
;     E(row, c0 + col_off, acc);
; }
; __global__ void __launch_bounds__(NTHR, 2) mk_fwd(MkArgs a) {
;     extern __shared__ __attribute__((aligned(16))) unsigned char lds_raw[];
;     LAS unsigned char* lds = (LAS unsigned char*)lds_raw;
;     cg::grid_group grid = cg::this_grid();
;     const Ptrs& P = a.P;
;     const int tid = threadIdx.x, lane = tid & 63, wave = __builtin_amdgcn_readfirstlane(tid >> 6), bx = blockIdx.x, G = gridDim.x;
  - .agpr_count:     0
    .args:
      - .offset:         0
        .size:           184
        .value_kind:     by_value
      - .offset:         184
        .size:           4
        .value_kind:     hidden_block_count_x
      - .offset:         188
        .size:           4
        .value_kind:     hidden_block_count_y
      - .offset:         192
        .size:           4
        .value_kind:     hidden_block_count_z
      - .offset:         196
        .size:           2
        .value_kind:     hidden_group_size_x
      - .offset:         198
        .size:           2
        .value_kind:     hidden_group_size_y
      - .offset:         200
        .size:           2
        .value_kind:     hidden_group_size_z
      - .offset:         202
        .size:           2
        .value_kind:     hidden_remainder_x
      - .offset:         204
        .size:           2
        .value_kind:     hidden_remainder_y
      - .offset:         206
        .size:           2
        .value_kind:     hidden_remainder_z
      - .offset:         224
        .size:           8
        .value_kind:     hidden_global_offset_x
      - .offset:         232
        .size:           8
        .value_kind:     hidden_global_offset_y
      - .offset:         240
        .size:           8
        .value_kind:     hidden_global_offset_z
      - .offset:         248
        .size:           2
        .value_kind:     hidden_grid_dims
      - .offset:         272
        .size:           8
        .value_kind:     hidden_multigrid_sync_arg
      - .offset:         304
        .size:           4
        .value_kind:     hidden_dynamic_lds_size
    .group_segment_fixed_size: 0
    .kernarg_segment_align: 8
    .kernarg_segment_size: 440
    .language:       OpenCL C
    .language_version:
      - 2
      - 0
    .max_flat_workgroup_size: 512
    .name:           _Z6mk_fwd6MkArgs
    .private_segment_fixed_size: 0
    .sgpr_count:     104
    .sgpr_spill_count: 83
    .symbol:         _Z6mk_fwd6MkArgs.kd
    .uniform_work_group_size: 1
    .uses_dynamic_stack: false
    .vgpr_count:     256
    .vgpr_spill_count: 0
    .wavefront_size: 64
  - .agpr_count:     0
    .args:
      - .address_space:  global
        .offset:         0
        .size:           8
        .value_kind:     global_buffer
      - .offset:         8
        .size:           4
        .value_kind:     by_value
      - .address_space:  global
        .offset:         16
        .size:           8
        .value_kind:     global_buffer
      - .offset:         24
        .size:           4
        .value_kind:     by_value
      - .offset:         28
        .size:           4
        .value_kind:     by_value
      - .offset:         32
        .size:           4
        .value_kind:     by_value
      - .offset:         36
        .size:           4
        .value_kind:     by_value
      - .offset:         40
        .size:           4
        .value_kind:     by_value
      - .offset:         48
        .size:           32
        .value_kind:     by_value
      - .offset:         80
        .size:           4
        .value_kind:     hidden_block_count_x
      - .offset:         84
        .size:           4
        .value_kind:     hidden_block_count_y
      - .offset:         88
        .size:           4
        .value_kind:     hidden_block_count_z
      - .offset:         92
        .size:           2
        .value_kind:     hidden_group_size_x
      - .offset:         94
        .size:           2
        .value_kind:     hidden_group_size_y
      - .offset:         96
        .size:           2
        .value_kind:     hidden_group_size_z
      - .offset:         98
        .size:           2
        .value_kind:     hidden_remainder_x
      - .offset:         100
        .size:           2
        .value_kind:     hidden_remainder_y
      - .offset:         102
        .size:           2
        .value_kind:     hidden_remainder_z
      - .offset:         120
        .size:           8
        .value_kind:     hidden_global_offset_x
      - .offset:         128
        .size:           8
        .value_kind:     hidden_global_offset_y
      - .offset:         136
        .size:           8
        .value_kind:     hidden_global_offset_z
      - .offset:         144
        .size:           2
        .value_kind:     hidden_grid_dims
    .group_segment_fixed_size: 0
    .kernarg_segment_align: 8
    .kernarg_segment_size: 336
    .language:       OpenCL C
    .language_version:
      - 2
      - 0
    .max_flat_workgroup_size: 1024
    .name:           _Z6k_gemmI9EpiInRestEvPKtiS2_iiiiiT_
    .private_segment_fixed_size: 0
    .sgpr_count:     21
    .sgpr_spill_count: 0
    .symbol:         _Z6k_gemmI9EpiInRestEvPKtiS2_iiiiiT_.kd
    .uniform_work_group_size: 1
    .uses_dynamic_stack: false
    .vgpr_count:     98
    .vgpr_spill_count: 0
    .wavefront_size: 64
; __device__ __forceinline__ unsigned f2bf(float f) { unsigned u = __float_as_uint(f); return (u + 0x7fffu + ((u >> 16) & 1u)) >> 16; }
; __device__ __forceinline__ u32x4 pack8(const float (&v)[8]) { u32x4 w; w.x = cvtpk(v[0], v[1]); w.y = cvtpk(v[2], v[3]); w.z = cvtpk(v[4], v[5]); w.w = cvtpk(v[6], v[7]); return w; }
; __device__ __forceinline__ int perm16(int t) { return (t & ~12) | ((t & 4) << 1) | ((t & 8) >> 1); }
;     __device__ __forceinline__ void operator()(int row, int c0, const float (&v)[8]) const {
;         const int b = row >> 8, t = row & 255, kh = c0 >> 6, d0 = c0 & 63;
;         bf16_t* p = Vct + ((size_t)((b * 4 + kh) * 64 + d0)) * CTX + perm16(t);
; #pragma unroll
;         for (int i = 0; i < 8; ++i) p[(size_t)i * CTX] = (bf16_t)f2bf(v[i]);
;     }
;     __device__ __forceinline__ void operator()(int row, int c0, const float (&v)[8]) const {
;         float o[8];
; #pragma unroll
;         for (int i = 0; i < 8; ++i) o[i] = v[i] * pool_scale[g * 128 + c0 + i];
;         *(u32x4*)(PM + (size_t)row * PMP + g * 128 + c0) = pack8(o);
;     }
; template <class Epi> __global__ void k_gemm(const bf16_t* A, int lda, const bf16_t* Bt, int ldb, int Mrows, int N, int K, int col_off, Epi E) {
;     const int gw = (blockIdx.x * blockDim.x + threadIdx.x) >> 6, lane = threadIdx.x & 63, nrb = Mrows / 64;
;     if (gw >= nrb * (N / 8)) return;
;     const int row = (gw % nrb) * 64 + lane, c0 = (gw / nrb) * 8;
;     float acc[8];
; #pragma unroll
;     for (int j = 0; j < 8; ++j) acc[j] = 0.f;
;     for (int k0 = 0; k0 < K; k0 += 8) {
;         float a[8]; unpack8(*(const u32x4*)(A + (size_t)row * lda + k0), a);
; #pragma unroll
;         for (int j = 0; j < 8; ++j) { float b[8]; unpack8(*(const u32x4*)(Bt + (size_t)(c0 + j) * ldb + k0), b);
; #pragma unroll
;             for (int i = 0; i < 8; ++i) acc[j] += a[i] * b[i]; }
;     }
;     E(row, c0 + col_off, acc);
; }
  - .agpr_count:     0
    .args:
      - .address_space:  global
        .offset:         0
        .size:           8
        .value_kind:     global_buffer
      - .offset:         8
        .size:           4
        .value_kind:     by_value
      - .address_space:  global
        .offset:         16
        .size:           8
        .value_kind:     global_buffer
      - .offset:         24
        .size:           4
        .value_kind:     by_value
      - .offset:         28
        .size:           4
        .value_kind:     by_value
      - .offset:         32
        .size:           4
        .value_kind:     by_value
      - .offset:         36
        .size:           4
        .value_kind:     by_value
      - .offset:         40
        .size:           4
        .value_kind:     by_value
      - .address_space:  global
        .offset:         48
        .size:           8
        .value_kind:     global_buffer
      - .offset:         56
        .size:           4
        .value_kind:     hidden_block_count_x
      - .offset:         60
        .size:           4
        .value_kind:     hidden_block_count_y
      - .offset:         64
        .size:           4
        .value_kind:     hidden_block_count_z
      - .offset:         68
        .size:           2
        .value_kind:     hidden_group_size_x
      - .offset:         70
        .size:           2
        .value_kind:     hidden_group_size_y
      - .offset:         72
        .size:           2
        .value_kind:     hidden_group_size_z
      - .offset:         74
        .size:           2
        .value_kind:     hidden_remainder_x
      - .offset:         76
        .size:           2
        .value_kind:     hidden_remainder_y
      - .offset:         78
        .size:           2
        .value_kind:     hidden_remainder_z
      - .offset:         96
        .size:           8
        .value_kind:     hidden_global_offset_x
      - .offset:         104
        .size:           8
        .value_kind:     hidden_global_offset_y
      - .offset:         112
        .size:           8
        .value_kind:     hidden_global_offset_z
      - .offset:         120
        .size:           2
        .value_kind:     hidden_grid_dims
    .group_segment_fixed_size: 0
    .kernarg_segment_align: 8
    .kernarg_segment_size: 312
    .language:       OpenCL C
    .language_version:
      - 2
      - 0
    .max_flat_workgroup_size: 1024
    .name:           _Z6k_gemmI7EpiCtxVEvPKtiS2_iiiiiT_
    .private_segment_fixed_size: 0
    .sgpr_count:     21
    .sgpr_spill_count: 0
    .symbol:         _Z6k_gemmI7EpiCtxVEvPKtiS2_iiiiiT_.kd
    .uniform_work_group_size: 1
    .uses_dynamic_stack: false
    .vgpr_count:     98
    .vgpr_spill_count: 0
    .wavefront_size: 64
  - .agpr_count:     0
    .args:
      - .address_space:  global
        .offset:         0
        .size:           8
        .value_kind:     global_buffer
      - .offset:         8
        .size:           4
        .value_kind:     by_value
      - .address_space:  global
        .offset:         16
        .size:           8
        .value_kind:     global_buffer
      - .offset:         24
        .size:           4
        .value_kind:     by_value
      - .offset:         28
        .size:           4
        .value_kind:     by_value
      - .offset:         32
        .size:           4
        .value_kind:     by_value
      - .offset:         36
        .size:           4
        .value_kind:     by_value
      - .offset:         40
        .size:           4
        .value_kind:     by_value
      - .offset:         48
        .size:           24
        .value_kind:     by_value
      - .offset:         72
        .size:           4
        .value_kind:     hidden_block_count_x
      - .offset:         76
        .size:           4
        .value_kind:     hidden_block_count_y
      - .offset:         80
        .size:           4
        .value_kind:     hidden_block_count_z
      - .offset:         84
        .size:           2
        .value_kind:     hidden_group_size_x
      - .offset:         86
        .size:           2
        .value_kind:     hidden_group_size_y
      - .offset:         88
        .size:           2
        .value_kind:     hidden_group_size_z
      - .offset:         90
        .size:           2
        .value_kind:     hidden_remainder_x
      - .offset:         92
        .size:           2
        .value_kind:     hidden_remainder_y
      - .offset:         94
        .size:           2
        .value_kind:     hidden_remainder_z
      - .offset:         112
        .size:           8
        .value_kind:     hidden_global_offset_x
      - .offset:         120
        .size:           8
        .value_kind:     hidden_global_offset_y
      - .offset:         128
        .size:           8
        .value_kind:     hidden_global_offset_z
      - .offset:         136
        .size:           2
        .value_kind:     hidden_grid_dims
    .group_segment_fixed_size: 0
    .kernarg_segment_align: 8
    .kernarg_segment_size: 328
    .language:       OpenCL C
    .language_version:
      - 2
      - 0
    .max_flat_workgroup_size: 1024
    .name:           _Z6k_gemmI10EpiPoolMixEvPKtiS2_iiiiiT_
    .private_segment_fixed_size: 0
    .sgpr_count:     21
    .sgpr_spill_count: 0
    .symbol:         _Z6k_gemmI10EpiPoolMixEvPKtiS2_iiiiiT_.kd
    .uniform_work_group_size: 1
    .uses_dynamic_stack: false
    .vgpr_count:     96
    .vgpr_spill_count: 0
    .wavefront_size: 64
; __device__ __forceinline__ u32x4 pack8(const float (&v)[8]) { u32x4 w; w.x = cvtpk(v[0], v[1]); w.y = cvtpk(v[2], v[3]); w.z = cvtpk(v[4], v[5]); w.w = cvtpk(v[6], v[7]); return w; }
;     __device__ __forceinline__ void operator()(int row, int c0, const float (&v)[8]) const {
;         float g[8], o[8]; unpack8(*(const u32x4*)(GATES + (size_t)row * 2048 + 1024 + c0), g);
; #pragma unroll
;         for (int i = 0; i < 8; ++i) o[i] = g[i] * v[i];
;         *(u32x4*)(PG + (size_t)row * DM + c0) = pack8(o);
;     }
; template <class Epi> __global__ void k_gemm(const bf16_t* A, int lda, const bf16_t* Bt, int ldb, int Mrows, int N, int K, int col_off, Epi E) {
;     const int gw = (blockIdx.x * blockDim.x + threadIdx.x) >> 6, lane = threadIdx.x & 63, nrb = Mrows / 64;
;     if (gw >= nrb * (N / 8)) return;
;     const int row = (gw % nrb) * 64 + lane, c0 = (gw / nrb) * 8;
;     float acc[8];
; #pragma unroll
;     for (int j = 0; j < 8; ++j) acc[j] = 0.f;
;     for (int k0 = 0; k0 < K; k0 += 8) {
;         float a[8]; unpack8(*(const u32x4*)(A + (size_t)row * lda + k0), a);
; #pragma unroll
;         for (int j = 0; j < 8; ++j) { float b[8]; unpack8(*(const u32x4*)(Bt + (size_t)(c0 + j) * ldb + k0), b);
; #pragma unroll
;             for (int i = 0; i < 8; ++i) acc[j] += a[i] * b[i]; }
;     }
;     E(row, c0 + col_off, acc);
; }
  - .agpr_count:     0
    .args:
      - .address_space:  global
        .offset:         0
        .size:           8
        .value_kind:     global_buffer
      - .offset:         8
        .size:           4
        .value_kind:     by_value
      - .address_space:  global
        .offset:         16
        .size:           8
        .value_kind:     global_buffer
      - .offset:         24
        .size:           4
        .value_kind:     by_value
      - .offset:         28
        .size:           4
        .value_kind:     by_value
      - .offset:         32
        .size:           4
        .value_kind:     by_value
      - .offset:         36
        .size:           4
        .value_kind:     by_value
      - .offset:         40
        .size:           4
        .value_kind:     by_value
      - .offset:         48
        .size:           16
        .value_kind:     by_value
      - .offset:         64
        .size:           4
        .value_kind:     hidden_block_count_x
      - .offset:         68
        .size:           4
        .value_kind:     hidden_block_count_y
      - .offset:         72
        .size:           4
        .value_kind:     hidden_block_count_z
      - .offset:         76
        .size:           2
        .value_kind:     hidden_group_size_x
      - .offset:         78
        .size:           2
        .value_kind:     hidden_group_size_y
      - .offset:         80
        .size:           2
        .value_kind:     hidden_group_size_z
      - .offset:         82
        .size:           2
        .value_kind:     hidden_remainder_x
      - .offset:         84
        .size:           2
        .value_kind:     hidden_remainder_y
      - .offset:         86
        .size:           2
        .value_kind:     hidden_remainder_z
      - .offset:         104
        .size:           8
        .value_kind:     hidden_global_offset_x
      - .offset:         112
        .size:           8
        .value_kind:     hidden_global_offset_y
      - .offset:         120
        .size:           8
        .value_kind:     hidden_global_offset_z
      - .offset:         128
        .size:           2
        .value_kind:     hidden_grid_dims
    .group_segment_fixed_size: 0
    .kernarg_segment_align: 8
    .kernarg_segment_size: 320
    .language:       OpenCL C
    .language_version:
      - 2
      - 0
    .max_flat_workgroup_size: 1024
    .name:           _Z6k_gemmI11EpiPoolProjEvPKtiS2_iiiiiT_
    .private_segment_fixed_size: 0
    .sgpr_count:     21
    .sgpr_spill_count: 0
    .symbol:         _Z6k_gemmI11EpiPoolProjEvPKtiS2_iiiiiT_.kd
    .uniform_work_group_size: 1
    .uses_dynamic_stack: false
    .vgpr_count:     96
    .vgpr_spill_count: 0
    .wavefront_size: 64
;     __device__ __forceinline__ void operator()(int row, int c0, const float (&v)[8]) const {
;         float g[8], p[8], o[8]; unpack8(*(const u32x4*)(GATES + (size_t)row * 2048 + c0), g); unpack8(*(const u32x4*)(PG + (size_t)row * DM + c0), p);
; #pragma unroll
;         for (int i = 0; i < 8; ++i) o[i] = g[i] * v[i] + p[i];
;         *(u32x4*)(PG + (size_t)row * DM + c0) = pack8(o);
;     }
;     __device__ __forceinline__ float operator()(int row, int c0, const float (&v)[8]) const {
;         const int b = row >> 12; const float* mb = mod + (size_t)b * NMOD; float o[8], y[8], ss = 0.f;
; #pragma unroll
;         for (int h = 0; h < 2; ++h) {
;             const f32x4 xv = *(const f32x4*)(x + (size_t)row * DM + c0 + 4 * h), g1 = *(const f32x4*)(mb + 2 * DM + c0 + 4 * h), sc2 = *(const f32x4*)(mb + 4 * DM + c0 + 4 * h), ng = *(const f32x4*)(n2g + c0 + 4 * h);
; #pragma unroll
;             for (int i = 0; i < 4; ++i) { const float x1 = xv[i] + g1[i] * v[4 * h + i]; o[4 * h + i] = x1; ss += x1 * x1; y[4 * h + i] = x1 * (ng[i] * (1.0f + sc2[i])); }
;             *(f32x4*)(out + (size_t)row * DM + c0 + 4 * h) = (f32x4){o[4 * h], o[4 * h + 1], o[4 * h + 2], o[4 * h + 3]};
;         }
;         *(u32x4*)(Y2 + (size_t)row * DM + c0) = pack8(y);
;         return ss;
;     }
;     __device__ __forceinline__ void operator()(int row, int c0, float rstd, const float (&va)[8], const float (&vb)[8]) const {
;         const int b = row >> 12, np = ((c0 >> 7) << 8) + (c0 & 127); const float* bb = bias2 + (size_t)b * NUP + np; float o[8];
; #pragma unroll
; template <class Epi> __global__ void k_gemm(const bf16_t* A, int lda, const bf16_t* Bt, int ldb, int Mrows, int N, int K, int col_off, Epi E) {
;     const int gw = (blockIdx.x * blockDim.x + threadIdx.x) >> 6, lane = threadIdx.x & 63, nrb = Mrows / 64;
;     if (gw >= nrb * (N / 8)) return;
;     const int row = (gw % nrb) * 64 + lane, c0 = (gw / nrb) * 8;
;     float acc[8];
; #pragma unroll
;     for (int j = 0; j < 8; ++j) acc[j] = 0.f;
;     for (int k0 = 0; k0 < K; k0 += 8) {
;         float a[8]; unpack8(*(const u32x4*)(A + (size_t)row * lda + k0), a);
; #pragma unroll
;         for (int j = 0; j < 8; ++j) { float b[8]; unpack8(*(const u32x4*)(Bt + (size_t)(c0 + j) * ldb + k0), b);
; #pragma unroll
;             for (int i = 0; i < 8; ++i) acc[j] += a[i] * b[i]; }
;     }
;     E(row, c0 + col_off, acc);
; }
  - .agpr_count:     0
    .args:
      - .address_space:  global
        .offset:         0
        .size:           8
        .value_kind:     global_buffer
      - .offset:         8
        .size:           4
        .value_kind:     by_value
      - .address_space:  global
        .offset:         16
        .size:           8
        .value_kind:     global_buffer
      - .offset:         24
        .size:           4
        .value_kind:     by_value
      - .offset:         28
        .size:           4
        .value_kind:     by_value
      - .offset:         32
        .size:           4
        .value_kind:     by_value
      - .offset:         36
        .size:           4
        .value_kind:     by_value
      - .offset:         40
        .size:           4
        .value_kind:     by_value
      - .offset:         48
        .size:           16
        .value_kind:     by_value
      - .offset:         64
        .size:           4
        .value_kind:     hidden_block_count_x
      - .offset:         68
        .size:           4
        .value_kind:     hidden_block_count_y
      - .offset:         72
        .size:           4
        .value_kind:     hidden_block_count_z
      - .offset:         76
        .size:           2
        .value_kind:     hidden_group_size_x
      - .offset:         78
        .size:           2
        .value_kind:     hidden_group_size_y
      - .offset:         80
        .size:           2
        .value_kind:     hidden_group_size_z
      - .offset:         82
        .size:           2
        .value_kind:     hidden_remainder_x
      - .offset:         84
        .size:           2
        .value_kind:     hidden_remainder_y
      - .offset:         86
        .size:           2
        .value_kind:     hidden_remainder_z
      - .offset:         104
        .size:           8
        .value_kind:     hidden_global_offset_x
      - .offset:         112
        .size:           8
        .value_kind:     hidden_global_offset_y
      - .offset:         120
        .size:           8
        .value_kind:     hidden_global_offset_z
      - .offset:         128
        .size:           2
        .value_kind:     hidden_grid_dims
    .group_segment_fixed_size: 0
    .kernarg_segment_align: 8
    .kernarg_segment_size: 320
    .language:       OpenCL C
    .language_version:
      - 2
      - 0
    .max_flat_workgroup_size: 1024
    .name:           _Z6k_gemmI11EpiAttnProjEvPKtiS2_iiiiiT_
    .private_segment_fixed_size: 0
    .sgpr_count:     21
    .sgpr_spill_count: 0
    .symbol:         _Z6k_gemmI11EpiAttnProjEvPKtiS2_iiiiiT_.kd
    .uniform_work_group_size: 1
    .uses_dynamic_stack: false
    .vgpr_count:     96
    .vgpr_spill_count: 0
    .wavefront_size: 64
  - .agpr_count:     0
    .args:
      - .address_space:  global
        .offset:         0
        .size:           8
        .value_kind:     global_buffer
      - .offset:         8
        .size:           4
        .value_kind:     by_value
      - .address_space:  global
        .offset:         16
        .size:           8
        .value_kind:     global_buffer
      - .offset:         24
        .size:           4
        .value_kind:     by_value
      - .offset:         28
        .size:           4
        .value_kind:     by_value
      - .offset:         32
        .size:           4
        .value_kind:     by_value
      - .offset:         36
        .size:           4
        .value_kind:     by_value
      - .offset:         40
        .size:           4
        .value_kind:     by_value
      - .offset:         48
        .size:           24
        .value_kind:     by_value
      - .offset:         72
        .size:           4
        .value_kind:     hidden_block_count_x
      - .offset:         76
        .size:           4
        .value_kind:     hidden_block_count_y
      - .offset:         80
        .size:           4
        .value_kind:     hidden_block_count_z
      - .offset:         84
        .size:           2
        .value_kind:     hidden_group_size_x
      - .offset:         86
        .size:           2
        .value_kind:     hidden_group_size_y
      - .offset:         88
        .size:           2
        .value_kind:     hidden_group_size_z
      - .offset:         90
        .size:           2
        .value_kind:     hidden_remainder_x
      - .offset:         92
        .size:           2
        .value_kind:     hidden_remainder_y
      - .offset:         94
        .size:           2
        .value_kind:     hidden_remainder_z
      - .offset:         112
        .size:           8
        .value_kind:     hidden_global_offset_x
      - .offset:         120
        .size:           8
        .value_kind:     hidden_global_offset_y
      - .offset:         128
        .size:           8
        .value_kind:     hidden_global_offset_z
      - .offset:         136
        .size:           2
        .value_kind:     hidden_grid_dims
    .group_segment_fixed_size: 0
    .kernarg_segment_align: 8
    .kernarg_segment_size: 328
    .language:       OpenCL C
    .language_version:
      - 2
      - 0
    .max_flat_workgroup_size: 1024
    .name:           _Z6k_gemmI7EpiDownEvPKtiS2_iiiiiT_
    .private_segment_fixed_size: 0
    .sgpr_count:     25
    .sgpr_spill_count: 0
    .symbol:         _Z6k_gemmI7EpiDownEvPKtiS2_iiiiiT_.kd
    .uniform_work_group_size: 1
    .uses_dynamic_stack: false
    .vgpr_count:     96
    .vgpr_spill_count: 0
    .wavefront_size: 64
